# ring-buffer base constants folded into the m0 computations: no scalar re-materialisation at the head of the load segments
# speedup vs baseline: 1.0022x; 1.0022x over previous
.LBB0_445:
	s_add_u32 s56, s62, 0xb0080
	s_addc_u32 s57, s63, 0
	s_add_u32 s62, s60, 0x100
	v_mov_b32_e32 v2, 0
	s_addc_u32 s63, s61, 0
	s_mov_b32 s84, -2
	s_waitcnt lgkmcnt(0)
	v_add_u32_e32 v243, 0x10000, v191
	ds_read_b128 v[114:117], v243
	ds_read_b128 v[126:129], v243 offset:1024
	ds_read_b128 v[130:133], v243 offset:2048
	ds_read_b128 v[134:137], v243 offset:3072
	ds_read_b128 v[146:149], v243 offset:16384
	ds_read_b128 v[150:153], v243 offset:17408
	ds_read_b128 v[158:161], v243 offset:18432
	ds_read_b128 v[182:185], v243 offset:19456
	ds_read_b128 v[186:189], v193
	ds_read_b128 v[194:197], v193 offset:1024
	ds_read_b128 v[198:201], v193 offset:2048
	ds_read_b128 v[214:217], v193 offset:3072
	ds_read_b128 v[218:221], v193 offset:4096
	ds_read_b128 v[222:225], v193 offset:5120
	ds_read_b128 v[226:229], v193 offset:6144
	ds_read_b128 v[230:233], v193 offset:7168
	s_mov_b64 s[12:13], 0xb0000
	s_mov_b64 s[86:87], 0x108000
	s_mov_b64 s[96:97], 0x58080
	s_mov_b64 vcc, 0xb0080
	s_mov_b64 s[0:1], 0x108080
	s_cmp_eq_u64 s[40:41], 0
	s_cbranch_scc0 .Lpr_446
	s_setprio 1

.Lmid1_446:
	s_add_u32 s20, s56, 0xfff50080
	s_addc_u32 s21, s57, -1
	s_cmp_eq_u32 s84, 40
	s_cselect_b32 s61, s49, s21
	s_cselect_b32 s60, s48, s20
	s_cselect_b32 s21, s51, s63
	s_cselect_b32 s20, s50, s62
	s_add_i32 m0, s47, 0xc000
	v_lshl_add_u64 v[162:163], s[56:57], 0, v[156:157]
	global_load_lds_dwordx4 v[162:163], off
	v_lshl_add_u64 v[162:163], v[162:163], 0, s[2:3]
	s_add_i32 m0, s47, 0xe000
	s_nop 0
	global_load_lds_dwordx4 v[162:163], off
	s_waitcnt vmcnt(8) lgkmcnt(0)
	s_barrier
	v_mfma_f32_16x16x32_bf16 v[142:145], v[114:117], v[186:189], 0
	v_mfma_f32_16x16x32_bf16 v[142:145], v[126:129], v[194:197], v[142:145]
	v_mfma_f32_16x16x32_bf16 v[138:141], v[130:133], v[186:189], 0
	v_mfma_f32_16x16x32_bf16 v[138:141], v[134:137], v[194:197], v[138:141]
	v_mfma_f32_16x16x32_bf16 v[110:113], v[114:117], v[198:201], 0
	v_mfma_f32_16x16x32_bf16 v[110:113], v[126:129], v[214:217], v[110:113]
	v_mfma_f32_16x16x32_bf16 v[106:109], v[130:133], v[198:201], 0
	v_mfma_f32_16x16x32_bf16 v[106:109], v[134:137], v[214:217], v[106:109]
	v_mfma_f32_16x16x32_bf16 v[94:97], v[114:117], v[218:221], 0
	v_mfma_f32_16x16x32_bf16 v[94:97], v[126:129], v[222:225], v[94:97]
	v_mfma_f32_16x16x32_bf16 v[90:93], v[130:133], v[218:221], 0
	v_mfma_f32_16x16x32_bf16 v[90:93], v[134:137], v[222:225], v[90:93]
	v_mfma_f32_16x16x32_bf16 v[78:81], v[114:117], v[226:229], 0
	v_mfma_f32_16x16x32_bf16 v[78:81], v[126:129], v[230:233], v[78:81]
	v_mfma_f32_16x16x32_bf16 v[74:77], v[130:133], v[226:229], 0
	v_mfma_f32_16x16x32_bf16 v[74:77], v[134:137], v[230:233], v[74:77]
	v_mfma_f32_16x16x32_bf16 v[122:125], v[146:149], v[186:189], 0
	v_mfma_f32_16x16x32_bf16 v[122:125], v[150:153], v[194:197], v[122:125]
	v_mfma_f32_16x16x32_bf16 v[118:121], v[158:161], v[186:189], 0
	v_mfma_f32_16x16x32_bf16 v[118:121], v[182:185], v[194:197], v[118:121]
	v_mfma_f32_16x16x32_bf16 v[102:105], v[146:149], v[198:201], 0
	v_mfma_f32_16x16x32_bf16 v[102:105], v[150:153], v[214:217], v[102:105]
	v_mfma_f32_16x16x32_bf16 v[98:101], v[158:161], v[198:201], 0
	v_mfma_f32_16x16x32_bf16 v[98:101], v[182:185], v[214:217], v[98:101]
	v_mfma_f32_16x16x32_bf16 v[86:89], v[146:149], v[218:221], 0
	v_mfma_f32_16x16x32_bf16 v[86:89], v[150:153], v[222:225], v[86:89]
	v_mfma_f32_16x16x32_bf16 v[82:85], v[158:161], v[218:221], 0
	v_mfma_f32_16x16x32_bf16 v[82:85], v[182:185], v[222:225], v[82:85]
	v_mfma_f32_16x16x32_bf16 v[70:73], v[146:149], v[226:229], 0
	v_mfma_f32_16x16x32_bf16 v[70:73], v[150:153], v[230:233], v[70:73]
	v_mfma_f32_16x16x32_bf16 v[66:69], v[158:161], v[226:229], 0
	v_mfma_f32_16x16x32_bf16 v[66:69], v[182:185], v[230:233], v[66:69]
	s_barrier
	ds_read_b128 v[186:189], v193 offset:16384
	ds_read_b128 v[194:197], v193 offset:17408
	ds_read_b128 v[198:201], v193 offset:18432
	ds_read_b128 v[214:217], v193 offset:19456
	ds_read_b128 v[218:221], v193 offset:20480
	ds_read_b128 v[222:225], v193 offset:21504
	ds_read_b128 v[226:229], v193 offset:22528
	ds_read_b128 v[230:233], v193 offset:23552
	v_lshl_add_u64 v[162:163], s[20:21], 0, v[0:1]
	s_add_i32 s20, s46, 0x10000
	s_mov_b32 m0, s20
	s_nop 0
	s_nop 0
	global_load_lds_dwordx4 v[162:163], off
	v_lshl_add_u64 v[202:203], v[162:163], 0, s[2:3]
	s_add_i32 m0, s20, 0x2000
	s_add_i32 s20, s46, 0x14000
	global_load_lds_dwordx4 v[202:203], off
	v_lshl_add_u64 v[202:203], v[162:163], 0, s[12:13]
	s_mov_b32 m0, s20
	s_nop 0
	global_load_lds_dwordx4 v[202:203], off
	v_lshl_add_u64 v[202:203], v[162:163], 0, s[86:87]
	s_add_i32 m0, s20, 0x2000
	s_nop 0
	global_load_lds_dwordx4 v[202:203], off
	v_lshl_add_u64 v[202:203], s[60:61], 0, v[154:155]
	s_mov_b32 m0, s47
	v_lshl_add_u64 v[234:235], v[202:203], 0, s[2:3]
	global_load_lds_dwordx4 v[202:203], off
	s_mov_b32 m0, s68
	s_nop 0
	global_load_lds_dwordx4 v[234:235], off
	s_waitcnt vmcnt(8) lgkmcnt(0)
	s_barrier
	v_mfma_f32_16x16x32_bf16 v[62:65], v[114:117], v[186:189], 0
	v_mfma_f32_16x16x32_bf16 v[62:65], v[126:129], v[194:197], v[62:65]
	v_mfma_f32_16x16x32_bf16 v[58:61], v[130:133], v[186:189], 0
	v_mfma_f32_16x16x32_bf16 v[58:61], v[134:137], v[194:197], v[58:61]
	v_mfma_f32_16x16x32_bf16 v[46:49], v[114:117], v[198:201], 0
	v_mfma_f32_16x16x32_bf16 v[46:49], v[126:129], v[214:217], v[46:49]
	v_mfma_f32_16x16x32_bf16 v[42:45], v[130:133], v[198:201], 0
	v_mfma_f32_16x16x32_bf16 v[42:45], v[134:137], v[214:217], v[42:45]
	v_mfma_f32_16x16x32_bf16 v[30:33], v[114:117], v[218:221], 0
	v_mfma_f32_16x16x32_bf16 v[30:33], v[126:129], v[222:225], v[30:33]
	v_mfma_f32_16x16x32_bf16 v[26:29], v[130:133], v[218:221], 0
	v_mfma_f32_16x16x32_bf16 v[26:29], v[134:137], v[222:225], v[26:29]
	v_mfma_f32_16x16x32_bf16 v[14:17], v[114:117], v[226:229], 0
	v_mfma_f32_16x16x32_bf16 v[14:17], v[126:129], v[230:233], v[14:17]
	v_mfma_f32_16x16x32_bf16 v[10:13], v[130:133], v[226:229], 0
	v_mfma_f32_16x16x32_bf16 v[10:13], v[134:137], v[230:233], v[10:13]
	v_mfma_f32_16x16x32_bf16 v[54:57], v[146:149], v[186:189], 0
	v_mfma_f32_16x16x32_bf16 v[54:57], v[150:153], v[194:197], v[54:57]
	v_mfma_f32_16x16x32_bf16 v[50:53], v[158:161], v[186:189], 0
	v_mfma_f32_16x16x32_bf16 v[50:53], v[182:185], v[194:197], v[50:53]
	v_mfma_f32_16x16x32_bf16 v[38:41], v[146:149], v[198:201], 0
	v_mfma_f32_16x16x32_bf16 v[38:41], v[150:153], v[214:217], v[38:41]
	v_mfma_f32_16x16x32_bf16 v[34:37], v[158:161], v[198:201], 0
	v_mfma_f32_16x16x32_bf16 v[34:37], v[182:185], v[214:217], v[34:37]
	v_mfma_f32_16x16x32_bf16 v[22:25], v[146:149], v[218:221], 0
	v_mfma_f32_16x16x32_bf16 v[22:25], v[150:153], v[222:225], v[22:25]
	v_mfma_f32_16x16x32_bf16 v[18:21], v[158:161], v[218:221], 0
	v_mfma_f32_16x16x32_bf16 v[18:21], v[182:185], v[222:225], v[18:21]
	v_mfma_f32_16x16x32_bf16 v[6:9], v[146:149], v[226:229], 0
	v_mfma_f32_16x16x32_bf16 v[6:9], v[150:153], v[230:233], v[6:9]
	v_mfma_f32_16x16x32_bf16 v[2:5], v[158:161], v[226:229], 0
	v_mfma_f32_16x16x32_bf16 v[2:5], v[182:185], v[230:233], v[2:5]
	s_barrier
	ds_read_b128 v[114:117], v243 offset:32768
	ds_read_b128 v[126:129], v243 offset:33792
	ds_read_b128 v[130:133], v243 offset:34816
	ds_read_b128 v[134:137], v243 offset:35840
	ds_read_b128 v[146:149], v243 offset:49152
	ds_read_b128 v[150:153], v243 offset:50176
	ds_read_b128 v[158:161], v243 offset:51200
	ds_read_b128 v[182:185], v243 offset:52224
	ds_read_b128 v[186:189], v193 offset:32768
	ds_read_b128 v[194:197], v193 offset:33792
	ds_read_b128 v[198:201], v193 offset:34816
	ds_read_b128 v[214:217], v193 offset:35840
	ds_read_b128 v[218:221], v193 offset:36864
	ds_read_b128 v[222:225], v193 offset:37888
	ds_read_b128 v[226:229], v193 offset:38912
	ds_read_b128 v[230:233], v193 offset:39936
	s_mov_b32 m0, s69
	v_lshl_add_u64 v[234:235], v[202:203], 0, s[12:13]
	global_load_lds_dwordx4 v[234:235], off
	v_lshl_add_u64 v[234:235], v[202:203], 0, s[86:87]
	s_mov_b32 m0, s76
	s_nop 0
	global_load_lds_dwordx4 v[234:235], off
	s_waitcnt vmcnt(8) lgkmcnt(0)
	s_barrier
	v_mfma_f32_16x16x32_bf16 v[142:145], v[114:117], v[186:189], v[142:145]
	v_mfma_f32_16x16x32_bf16 v[142:145], v[126:129], v[194:197], v[142:145]
	v_mfma_f32_16x16x32_bf16 v[138:141], v[130:133], v[186:189], v[138:141]
	v_mfma_f32_16x16x32_bf16 v[138:141], v[134:137], v[194:197], v[138:141]
	v_mfma_f32_16x16x32_bf16 v[110:113], v[114:117], v[198:201], v[110:113]
	v_mfma_f32_16x16x32_bf16 v[110:113], v[126:129], v[214:217], v[110:113]
	v_mfma_f32_16x16x32_bf16 v[106:109], v[130:133], v[198:201], v[106:109]
	v_mfma_f32_16x16x32_bf16 v[106:109], v[134:137], v[214:217], v[106:109]
	v_mfma_f32_16x16x32_bf16 v[94:97], v[114:117], v[218:221], v[94:97]
	v_mfma_f32_16x16x32_bf16 v[94:97], v[126:129], v[222:225], v[94:97]
	v_mfma_f32_16x16x32_bf16 v[90:93], v[130:133], v[218:221], v[90:93]
	v_mfma_f32_16x16x32_bf16 v[90:93], v[134:137], v[222:225], v[90:93]
	v_mfma_f32_16x16x32_bf16 v[78:81], v[114:117], v[226:229], v[78:81]
	v_mfma_f32_16x16x32_bf16 v[78:81], v[126:129], v[230:233], v[78:81]
	v_mfma_f32_16x16x32_bf16 v[74:77], v[130:133], v[226:229], v[74:77]
	v_mfma_f32_16x16x32_bf16 v[74:77], v[134:137], v[230:233], v[74:77]
	v_mfma_f32_16x16x32_bf16 v[122:125], v[146:149], v[186:189], v[122:125]
	v_mfma_f32_16x16x32_bf16 v[122:125], v[150:153], v[194:197], v[122:125]
	v_mfma_f32_16x16x32_bf16 v[118:121], v[158:161], v[186:189], v[118:121]
	v_mfma_f32_16x16x32_bf16 v[118:121], v[182:185], v[194:197], v[118:121]
	v_mfma_f32_16x16x32_bf16 v[102:105], v[146:149], v[198:201], v[102:105]
	v_mfma_f32_16x16x32_bf16 v[102:105], v[150:153], v[214:217], v[102:105]
	v_mfma_f32_16x16x32_bf16 v[98:101], v[158:161], v[198:201], v[98:101]
	v_mfma_f32_16x16x32_bf16 v[98:101], v[182:185], v[214:217], v[98:101]
	v_mfma_f32_16x16x32_bf16 v[86:89], v[146:149], v[218:221], v[86:89]
	v_mfma_f32_16x16x32_bf16 v[86:89], v[150:153], v[222:225], v[86:89]
	v_mfma_f32_16x16x32_bf16 v[82:85], v[158:161], v[218:221], v[82:85]
	v_mfma_f32_16x16x32_bf16 v[82:85], v[182:185], v[222:225], v[82:85]
	v_mfma_f32_16x16x32_bf16 v[70:73], v[146:149], v[226:229], v[70:73]
	v_mfma_f32_16x16x32_bf16 v[70:73], v[150:153], v[230:233], v[70:73]
	v_mfma_f32_16x16x32_bf16 v[66:69], v[158:161], v[226:229], v[66:69]
	v_mfma_f32_16x16x32_bf16 v[66:69], v[182:185], v[230:233], v[66:69]
	s_barrier
	ds_read_b128 v[186:189], v193 offset:49152
	ds_read_b128 v[194:197], v193 offset:50176
	ds_read_b128 v[198:201], v193 offset:51200
	ds_read_b128 v[214:217], v193 offset:52224
	ds_read_b128 v[218:221], v193 offset:53248
	ds_read_b128 v[222:225], v193 offset:54272
	ds_read_b128 v[226:229], v193 offset:55296
	ds_read_b128 v[230:233], v193 offset:56320
	s_add_i32 s20, s46, 0x18000
	s_mov_b32 m0, s20
	v_lshl_add_u64 v[234:235], v[162:163], 0, s[34:35]
	global_load_lds_dwordx4 v[234:235], off
	v_lshl_add_u64 v[234:235], v[162:163], 0, s[96:97]
	s_add_i32 m0, s20, 0x2000
	s_add_i32 s20, s46, 0x1c000
	global_load_lds_dwordx4 v[234:235], off
	v_lshl_add_u64 v[234:235], v[162:163], 0, vcc
	s_mov_b32 m0, s20
	v_lshl_add_u64 v[162:163], v[162:163], 0, s[0:1]
	global_load_lds_dwordx4 v[234:235], off
	s_add_i32 m0, s20, 0x2000
	s_nop 0
	global_load_lds_dwordx4 v[162:163], off
	v_lshl_add_u64 v[162:163], v[202:203], 0, s[34:35]
	s_mov_b32 m0, s77
	s_nop 0
	global_load_lds_dwordx4 v[162:163], off
	v_lshl_add_u64 v[162:163], v[202:203], 0, s[96:97]
	s_mov_b32 m0, s78
	s_nop 0
	global_load_lds_dwordx4 v[162:163], off
	s_waitcnt vmcnt(8) lgkmcnt(0)
	s_barrier
	v_mfma_f32_16x16x32_bf16 v[62:65], v[114:117], v[186:189], v[62:65]
	v_mfma_f32_16x16x32_bf16 v[62:65], v[126:129], v[194:197], v[62:65]
	v_mfma_f32_16x16x32_bf16 v[58:61], v[130:133], v[186:189], v[58:61]
	v_mfma_f32_16x16x32_bf16 v[58:61], v[134:137], v[194:197], v[58:61]
	v_mfma_f32_16x16x32_bf16 v[46:49], v[114:117], v[198:201], v[46:49]
	v_mfma_f32_16x16x32_bf16 v[46:49], v[126:129], v[214:217], v[46:49]
	v_mfma_f32_16x16x32_bf16 v[42:45], v[130:133], v[198:201], v[42:45]
	v_mfma_f32_16x16x32_bf16 v[42:45], v[134:137], v[214:217], v[42:45]
	v_mfma_f32_16x16x32_bf16 v[30:33], v[114:117], v[218:221], v[30:33]
	v_mfma_f32_16x16x32_bf16 v[30:33], v[126:129], v[222:225], v[30:33]
	v_mfma_f32_16x16x32_bf16 v[26:29], v[130:133], v[218:221], v[26:29]
	v_mfma_f32_16x16x32_bf16 v[26:29], v[134:137], v[222:225], v[26:29]
	v_mfma_f32_16x16x32_bf16 v[14:17], v[114:117], v[226:229], v[14:17]
	v_mfma_f32_16x16x32_bf16 v[14:17], v[126:129], v[230:233], v[14:17]
	v_mfma_f32_16x16x32_bf16 v[10:13], v[130:133], v[226:229], v[10:13]
	v_mfma_f32_16x16x32_bf16 v[10:13], v[134:137], v[230:233], v[10:13]
	s_add_i32 s84, s84, 2
	s_add_u32 s56, s56, 0x100
	s_addc_u32 s57, s57, 0
	s_add_u32 s62, s62, 0x100
	s_addc_u32 s63, s63, 0
	v_mfma_f32_16x16x32_bf16 v[54:57], v[146:149], v[186:189], v[54:57]
	v_mfma_f32_16x16x32_bf16 v[54:57], v[150:153], v[194:197], v[54:57]
	v_mfma_f32_16x16x32_bf16 v[50:53], v[158:161], v[186:189], v[50:53]
	v_mfma_f32_16x16x32_bf16 v[50:53], v[182:185], v[194:197], v[50:53]
	v_mfma_f32_16x16x32_bf16 v[38:41], v[146:149], v[198:201], v[38:41]
	v_mfma_f32_16x16x32_bf16 v[38:41], v[150:153], v[214:217], v[38:41]
	v_mfma_f32_16x16x32_bf16 v[34:37], v[158:161], v[198:201], v[34:37]
	v_mfma_f32_16x16x32_bf16 v[34:37], v[182:185], v[214:217], v[34:37]
	v_mfma_f32_16x16x32_bf16 v[22:25], v[146:149], v[218:221], v[22:25]
	v_mfma_f32_16x16x32_bf16 v[22:25], v[150:153], v[222:225], v[22:25]
	v_mfma_f32_16x16x32_bf16 v[18:21], v[158:161], v[218:221], v[18:21]
	v_mfma_f32_16x16x32_bf16 v[18:21], v[182:185], v[222:225], v[18:21]
	v_mfma_f32_16x16x32_bf16 v[6:9], v[146:149], v[226:229], v[6:9]
	v_mfma_f32_16x16x32_bf16 v[6:9], v[150:153], v[230:233], v[6:9]
	v_mfma_f32_16x16x32_bf16 v[2:5], v[158:161], v[226:229], v[2:5]
	v_mfma_f32_16x16x32_bf16 v[2:5], v[182:185], v[230:233], v[2:5]
	s_barrier
	s_branch .LBB0_446
	.p2alignl 6, 3212836864
.LBB0_446:
	ds_read_b128 v[114:117], v243
	ds_read_b128 v[126:129], v243 offset:1024
	ds_read_b128 v[130:133], v243 offset:2048
	ds_read_b128 v[134:137], v243 offset:3072
	ds_read_b128 v[146:149], v243 offset:16384
	ds_read_b128 v[150:153], v243 offset:17408
	ds_read_b128 v[158:161], v243 offset:18432
	ds_read_b128 v[182:185], v243 offset:19456
	ds_read_b128 v[186:189], v193
	ds_read_b128 v[194:197], v193 offset:1024
	ds_read_b128 v[198:201], v193 offset:2048
	ds_read_b128 v[214:217], v193 offset:3072
	ds_read_b128 v[218:221], v193 offset:4096
	ds_read_b128 v[222:225], v193 offset:5120
	ds_read_b128 v[226:229], v193 offset:6144
	ds_read_b128 v[230:233], v193 offset:7168
	s_add_u32 s20, s56, 0xfff50080
	s_addc_u32 s21, s57, -1
	s_cmp_eq_u32 s84, 40
	s_cselect_b32 s61, s49, s21
	s_cselect_b32 s60, s48, s20
	s_cselect_b32 s21, s51, s63
	s_cselect_b32 s20, s50, s62
	s_add_i32 m0, s47, 0xc000
	v_lshl_add_u64 v[162:163], s[56:57], 0, v[156:157]
	global_load_lds_dwordx4 v[162:163], off
	v_lshl_add_u64 v[162:163], v[162:163], 0, s[2:3]
	s_add_i32 m0, s47, 0xe000
	s_nop 0
	global_load_lds_dwordx4 v[162:163], off
	s_waitcnt vmcnt(8) lgkmcnt(0)
	s_barrier
	v_mfma_f32_16x16x32_bf16 v[142:145], v[114:117], v[186:189], v[142:145]
	v_mfma_f32_16x16x32_bf16 v[142:145], v[126:129], v[194:197], v[142:145]
	v_mfma_f32_16x16x32_bf16 v[138:141], v[130:133], v[186:189], v[138:141]
	v_mfma_f32_16x16x32_bf16 v[138:141], v[134:137], v[194:197], v[138:141]
	v_mfma_f32_16x16x32_bf16 v[110:113], v[114:117], v[198:201], v[110:113]
	v_mfma_f32_16x16x32_bf16 v[110:113], v[126:129], v[214:217], v[110:113]
	v_mfma_f32_16x16x32_bf16 v[106:109], v[130:133], v[198:201], v[106:109]
	v_mfma_f32_16x16x32_bf16 v[106:109], v[134:137], v[214:217], v[106:109]
	v_mfma_f32_16x16x32_bf16 v[94:97], v[114:117], v[218:221], v[94:97]
	v_mfma_f32_16x16x32_bf16 v[94:97], v[126:129], v[222:225], v[94:97]
	v_mfma_f32_16x16x32_bf16 v[90:93], v[130:133], v[218:221], v[90:93]
	v_mfma_f32_16x16x32_bf16 v[90:93], v[134:137], v[222:225], v[90:93]
	v_mfma_f32_16x16x32_bf16 v[78:81], v[114:117], v[226:229], v[78:81]
	v_mfma_f32_16x16x32_bf16 v[78:81], v[126:129], v[230:233], v[78:81]
	v_mfma_f32_16x16x32_bf16 v[74:77], v[130:133], v[226:229], v[74:77]
	v_mfma_f32_16x16x32_bf16 v[74:77], v[134:137], v[230:233], v[74:77]
	v_mfma_f32_16x16x32_bf16 v[122:125], v[146:149], v[186:189], v[122:125]
	v_mfma_f32_16x16x32_bf16 v[122:125], v[150:153], v[194:197], v[122:125]
	v_mfma_f32_16x16x32_bf16 v[118:121], v[158:161], v[186:189], v[118:121]
	v_mfma_f32_16x16x32_bf16 v[118:121], v[182:185], v[194:197], v[118:121]
	v_mfma_f32_16x16x32_bf16 v[102:105], v[146:149], v[198:201], v[102:105]
	v_mfma_f32_16x16x32_bf16 v[102:105], v[150:153], v[214:217], v[102:105]
	v_mfma_f32_16x16x32_bf16 v[98:101], v[158:161], v[198:201], v[98:101]
	v_mfma_f32_16x16x32_bf16 v[98:101], v[182:185], v[214:217], v[98:101]
	v_mfma_f32_16x16x32_bf16 v[86:89], v[146:149], v[218:221], v[86:89]
	v_mfma_f32_16x16x32_bf16 v[86:89], v[150:153], v[222:225], v[86:89]
	v_mfma_f32_16x16x32_bf16 v[82:85], v[158:161], v[218:221], v[82:85]
	v_mfma_f32_16x16x32_bf16 v[82:85], v[182:185], v[222:225], v[82:85]
	v_mfma_f32_16x16x32_bf16 v[70:73], v[146:149], v[226:229], v[70:73]
	v_mfma_f32_16x16x32_bf16 v[70:73], v[150:153], v[230:233], v[70:73]
	v_mfma_f32_16x16x32_bf16 v[66:69], v[158:161], v[226:229], v[66:69]
	v_mfma_f32_16x16x32_bf16 v[66:69], v[182:185], v[230:233], v[66:69]
	s_barrier
	ds_read_b128 v[186:189], v193 offset:16384
	ds_read_b128 v[194:197], v193 offset:17408
	ds_read_b128 v[198:201], v193 offset:18432
	ds_read_b128 v[214:217], v193 offset:19456
	ds_read_b128 v[218:221], v193 offset:20480
	ds_read_b128 v[222:225], v193 offset:21504
	ds_read_b128 v[226:229], v193 offset:22528
	ds_read_b128 v[230:233], v193 offset:23552
	v_lshl_add_u64 v[162:163], s[20:21], 0, v[0:1]
	s_add_i32 s20, s46, 0x10000
	s_mov_b32 m0, s20
	s_nop 0
	s_nop 0
	global_load_lds_dwordx4 v[162:163], off
	v_lshl_add_u64 v[202:203], v[162:163], 0, s[2:3]
	s_add_i32 m0, s20, 0x2000
	s_add_i32 s20, s46, 0x14000
	global_load_lds_dwordx4 v[202:203], off
	v_lshl_add_u64 v[202:203], v[162:163], 0, s[12:13]
	s_mov_b32 m0, s20
	s_nop 0
	global_load_lds_dwordx4 v[202:203], off
	v_lshl_add_u64 v[202:203], v[162:163], 0, s[86:87]
	s_add_i32 m0, s20, 0x2000
	s_nop 0
	global_load_lds_dwordx4 v[202:203], off
	v_lshl_add_u64 v[202:203], s[60:61], 0, v[154:155]
	s_mov_b32 m0, s47
	v_lshl_add_u64 v[234:235], v[202:203], 0, s[2:3]
	global_load_lds_dwordx4 v[202:203], off
	s_mov_b32 m0, s68
	s_nop 0
	global_load_lds_dwordx4 v[234:235], off
	s_waitcnt vmcnt(8) lgkmcnt(0)
	s_barrier
	v_mfma_f32_16x16x32_bf16 v[62:65], v[114:117], v[186:189], v[62:65]
	v_mfma_f32_16x16x32_bf16 v[62:65], v[126:129], v[194:197], v[62:65]
	v_mfma_f32_16x16x32_bf16 v[58:61], v[130:133], v[186:189], v[58:61]
	v_mfma_f32_16x16x32_bf16 v[58:61], v[134:137], v[194:197], v[58:61]
	v_mfma_f32_16x16x32_bf16 v[46:49], v[114:117], v[198:201], v[46:49]
	v_mfma_f32_16x16x32_bf16 v[46:49], v[126:129], v[214:217], v[46:49]
	v_mfma_f32_16x16x32_bf16 v[42:45], v[130:133], v[198:201], v[42:45]
	v_mfma_f32_16x16x32_bf16 v[42:45], v[134:137], v[214:217], v[42:45]
	v_mfma_f32_16x16x32_bf16 v[30:33], v[114:117], v[218:221], v[30:33]
	v_mfma_f32_16x16x32_bf16 v[30:33], v[126:129], v[222:225], v[30:33]
	v_mfma_f32_16x16x32_bf16 v[26:29], v[130:133], v[218:221], v[26:29]
	v_mfma_f32_16x16x32_bf16 v[26:29], v[134:137], v[222:225], v[26:29]
	v_mfma_f32_16x16x32_bf16 v[14:17], v[114:117], v[226:229], v[14:17]
	v_mfma_f32_16x16x32_bf16 v[14:17], v[126:129], v[230:233], v[14:17]
	v_mfma_f32_16x16x32_bf16 v[10:13], v[130:133], v[226:229], v[10:13]
	v_mfma_f32_16x16x32_bf16 v[10:13], v[134:137], v[230:233], v[10:13]
	v_mfma_f32_16x16x32_bf16 v[54:57], v[146:149], v[186:189], v[54:57]
	v_mfma_f32_16x16x32_bf16 v[54:57], v[150:153], v[194:197], v[54:57]
	v_mfma_f32_16x16x32_bf16 v[50:53], v[158:161], v[186:189], v[50:53]
	v_mfma_f32_16x16x32_bf16 v[50:53], v[182:185], v[194:197], v[50:53]
	v_mfma_f32_16x16x32_bf16 v[38:41], v[146:149], v[198:201], v[38:41]
	v_mfma_f32_16x16x32_bf16 v[38:41], v[150:153], v[214:217], v[38:41]
	v_mfma_f32_16x16x32_bf16 v[34:37], v[158:161], v[198:201], v[34:37]
	v_mfma_f32_16x16x32_bf16 v[34:37], v[182:185], v[214:217], v[34:37]
	v_mfma_f32_16x16x32_bf16 v[22:25], v[146:149], v[218:221], v[22:25]
	v_mfma_f32_16x16x32_bf16 v[22:25], v[150:153], v[222:225], v[22:25]
	v_mfma_f32_16x16x32_bf16 v[18:21], v[158:161], v[218:221], v[18:21]
	v_mfma_f32_16x16x32_bf16 v[18:21], v[182:185], v[222:225], v[18:21]
	v_mfma_f32_16x16x32_bf16 v[6:9], v[146:149], v[226:229], v[6:9]
	v_mfma_f32_16x16x32_bf16 v[6:9], v[150:153], v[230:233], v[6:9]
	v_mfma_f32_16x16x32_bf16 v[2:5], v[158:161], v[226:229], v[2:5]
	v_mfma_f32_16x16x32_bf16 v[2:5], v[182:185], v[230:233], v[2:5]
	s_barrier
	ds_read_b128 v[114:117], v243 offset:32768
	ds_read_b128 v[126:129], v243 offset:33792
	ds_read_b128 v[130:133], v243 offset:34816
	ds_read_b128 v[134:137], v243 offset:35840
	ds_read_b128 v[146:149], v243 offset:49152
	ds_read_b128 v[150:153], v243 offset:50176
	ds_read_b128 v[158:161], v243 offset:51200
	ds_read_b128 v[182:185], v243 offset:52224
	ds_read_b128 v[186:189], v193 offset:32768
	ds_read_b128 v[194:197], v193 offset:33792
	ds_read_b128 v[198:201], v193 offset:34816
	ds_read_b128 v[214:217], v193 offset:35840
	ds_read_b128 v[218:221], v193 offset:36864
	ds_read_b128 v[222:225], v193 offset:37888
	ds_read_b128 v[226:229], v193 offset:38912
	ds_read_b128 v[230:233], v193 offset:39936
	s_mov_b32 m0, s69
	v_lshl_add_u64 v[234:235], v[202:203], 0, s[12:13]
	global_load_lds_dwordx4 v[234:235], off
	v_lshl_add_u64 v[234:235], v[202:203], 0, s[86:87]
	s_mov_b32 m0, s76
	s_nop 0
	global_load_lds_dwordx4 v[234:235], off
	s_waitcnt vmcnt(8) lgkmcnt(0)
	s_barrier
	v_mfma_f32_16x16x32_bf16 v[142:145], v[114:117], v[186:189], v[142:145]
	v_mfma_f32_16x16x32_bf16 v[142:145], v[126:129], v[194:197], v[142:145]
	v_mfma_f32_16x16x32_bf16 v[138:141], v[130:133], v[186:189], v[138:141]
	v_mfma_f32_16x16x32_bf16 v[138:141], v[134:137], v[194:197], v[138:141]
	v_mfma_f32_16x16x32_bf16 v[110:113], v[114:117], v[198:201], v[110:113]
	v_mfma_f32_16x16x32_bf16 v[110:113], v[126:129], v[214:217], v[110:113]
	v_mfma_f32_16x16x32_bf16 v[106:109], v[130:133], v[198:201], v[106:109]
	v_mfma_f32_16x16x32_bf16 v[106:109], v[134:137], v[214:217], v[106:109]
	v_mfma_f32_16x16x32_bf16 v[94:97], v[114:117], v[218:221], v[94:97]
	v_mfma_f32_16x16x32_bf16 v[94:97], v[126:129], v[222:225], v[94:97]
	v_mfma_f32_16x16x32_bf16 v[90:93], v[130:133], v[218:221], v[90:93]
	v_mfma_f32_16x16x32_bf16 v[90:93], v[134:137], v[222:225], v[90:93]
	v_mfma_f32_16x16x32_bf16 v[78:81], v[114:117], v[226:229], v[78:81]
	v_mfma_f32_16x16x32_bf16 v[78:81], v[126:129], v[230:233], v[78:81]
	v_mfma_f32_16x16x32_bf16 v[74:77], v[130:133], v[226:229], v[74:77]
	v_mfma_f32_16x16x32_bf16 v[74:77], v[134:137], v[230:233], v[74:77]
	v_mfma_f32_16x16x32_bf16 v[122:125], v[146:149], v[186:189], v[122:125]
	v_mfma_f32_16x16x32_bf16 v[122:125], v[150:153], v[194:197], v[122:125]
	v_mfma_f32_16x16x32_bf16 v[118:121], v[158:161], v[186:189], v[118:121]
	v_mfma_f32_16x16x32_bf16 v[118:121], v[182:185], v[194:197], v[118:121]
	v_mfma_f32_16x16x32_bf16 v[102:105], v[146:149], v[198:201], v[102:105]
	v_mfma_f32_16x16x32_bf16 v[102:105], v[150:153], v[214:217], v[102:105]
	v_mfma_f32_16x16x32_bf16 v[98:101], v[158:161], v[198:201], v[98:101]
	v_mfma_f32_16x16x32_bf16 v[98:101], v[182:185], v[214:217], v[98:101]
	v_mfma_f32_16x16x32_bf16 v[86:89], v[146:149], v[218:221], v[86:89]
	v_mfma_f32_16x16x32_bf16 v[86:89], v[150:153], v[222:225], v[86:89]
	v_mfma_f32_16x16x32_bf16 v[82:85], v[158:161], v[218:221], v[82:85]
	v_mfma_f32_16x16x32_bf16 v[82:85], v[182:185], v[222:225], v[82:85]
	v_mfma_f32_16x16x32_bf16 v[70:73], v[146:149], v[226:229], v[70:73]
	v_mfma_f32_16x16x32_bf16 v[70:73], v[150:153], v[230:233], v[70:73]
	v_mfma_f32_16x16x32_bf16 v[66:69], v[158:161], v[226:229], v[66:69]
	v_mfma_f32_16x16x32_bf16 v[66:69], v[182:185], v[230:233], v[66:69]
	s_barrier
	ds_read_b128 v[186:189], v193 offset:49152
	ds_read_b128 v[194:197], v193 offset:50176
	ds_read_b128 v[198:201], v193 offset:51200
	ds_read_b128 v[214:217], v193 offset:52224
	ds_read_b128 v[218:221], v193 offset:53248
	ds_read_b128 v[222:225], v193 offset:54272
	ds_read_b128 v[226:229], v193 offset:55296
	ds_read_b128 v[230:233], v193 offset:56320
	s_add_i32 s20, s46, 0x18000
	s_mov_b32 m0, s20
	v_lshl_add_u64 v[234:235], v[162:163], 0, s[34:35]
	global_load_lds_dwordx4 v[234:235], off
	v_lshl_add_u64 v[234:235], v[162:163], 0, s[96:97]
	s_add_i32 m0, s20, 0x2000
	s_add_i32 s20, s46, 0x1c000
	global_load_lds_dwordx4 v[234:235], off
	v_lshl_add_u64 v[234:235], v[162:163], 0, vcc
	s_mov_b32 m0, s20
	v_lshl_add_u64 v[162:163], v[162:163], 0, s[0:1]
	global_load_lds_dwordx4 v[234:235], off
	s_add_i32 m0, s20, 0x2000
	s_nop 0
	global_load_lds_dwordx4 v[162:163], off
	v_lshl_add_u64 v[162:163], v[202:203], 0, s[34:35]
	s_mov_b32 m0, s77
	s_nop 0
	global_load_lds_dwordx4 v[162:163], off
	v_lshl_add_u64 v[162:163], v[202:203], 0, s[96:97]
	s_mov_b32 m0, s78
	s_nop 0
	global_load_lds_dwordx4 v[162:163], off
	s_waitcnt vmcnt(8) lgkmcnt(0)
	s_barrier
	v_mfma_f32_16x16x32_bf16 v[62:65], v[114:117], v[186:189], v[62:65]
	v_mfma_f32_16x16x32_bf16 v[62:65], v[126:129], v[194:197], v[62:65]
	v_mfma_f32_16x16x32_bf16 v[58:61], v[130:133], v[186:189], v[58:61]
	v_mfma_f32_16x16x32_bf16 v[58:61], v[134:137], v[194:197], v[58:61]
	v_mfma_f32_16x16x32_bf16 v[46:49], v[114:117], v[198:201], v[46:49]
	v_mfma_f32_16x16x32_bf16 v[46:49], v[126:129], v[214:217], v[46:49]
	v_mfma_f32_16x16x32_bf16 v[42:45], v[130:133], v[198:201], v[42:45]
	v_mfma_f32_16x16x32_bf16 v[42:45], v[134:137], v[214:217], v[42:45]
	v_mfma_f32_16x16x32_bf16 v[30:33], v[114:117], v[218:221], v[30:33]
	v_mfma_f32_16x16x32_bf16 v[30:33], v[126:129], v[222:225], v[30:33]
	v_mfma_f32_16x16x32_bf16 v[26:29], v[130:133], v[218:221], v[26:29]
	v_mfma_f32_16x16x32_bf16 v[26:29], v[134:137], v[222:225], v[26:29]
	v_mfma_f32_16x16x32_bf16 v[14:17], v[114:117], v[226:229], v[14:17]
	v_mfma_f32_16x16x32_bf16 v[14:17], v[126:129], v[230:233], v[14:17]
	v_mfma_f32_16x16x32_bf16 v[10:13], v[130:133], v[226:229], v[10:13]
	v_mfma_f32_16x16x32_bf16 v[10:13], v[134:137], v[230:233], v[10:13]
	s_add_i32 s84, s84, 2
	s_add_u32 s56, s56, 0x100
	s_addc_u32 s57, s57, 0
	s_add_u32 s62, s62, 0x100
	s_addc_u32 s63, s63, 0
	v_mfma_f32_16x16x32_bf16 v[54:57], v[146:149], v[186:189], v[54:57]
	v_mfma_f32_16x16x32_bf16 v[54:57], v[150:153], v[194:197], v[54:57]
	v_mfma_f32_16x16x32_bf16 v[50:53], v[158:161], v[186:189], v[50:53]
	v_mfma_f32_16x16x32_bf16 v[50:53], v[182:185], v[194:197], v[50:53]
	v_mfma_f32_16x16x32_bf16 v[38:41], v[146:149], v[198:201], v[38:41]
	v_mfma_f32_16x16x32_bf16 v[38:41], v[150:153], v[214:217], v[38:41]
	v_mfma_f32_16x16x32_bf16 v[34:37], v[158:161], v[198:201], v[34:37]
	v_mfma_f32_16x16x32_bf16 v[34:37], v[182:185], v[214:217], v[34:37]
	v_mfma_f32_16x16x32_bf16 v[22:25], v[146:149], v[218:221], v[22:25]
	v_mfma_f32_16x16x32_bf16 v[22:25], v[150:153], v[222:225], v[22:25]
	v_mfma_f32_16x16x32_bf16 v[18:21], v[158:161], v[218:221], v[18:21]
	v_mfma_f32_16x16x32_bf16 v[18:21], v[182:185], v[222:225], v[18:21]
	v_mfma_f32_16x16x32_bf16 v[6:9], v[146:149], v[226:229], v[6:9]
	v_mfma_f32_16x16x32_bf16 v[6:9], v[150:153], v[230:233], v[6:9]
	v_mfma_f32_16x16x32_bf16 v[2:5], v[158:161], v[226:229], v[2:5]
	v_mfma_f32_16x16x32_bf16 v[2:5], v[182:185], v[230:233], v[2:5]
	s_barrier
	s_cmp_gt_u32 s84, 41
	s_cbranch_scc0 .LBB0_446
	s_setprio 0
	s_and_b64 vcc, exec, s[40:41]
	s_cbranch_vccz .LBB0_449
	s_barrier

.LBB0_487:
	s_ashr_i32 s57, s56, 31
	s_lshl_b64 s[20:21], s[56:57], 19
	s_add_u32 s60, s94, s20
	s_addc_u32 s61, s95, s21
	s_and_b64 s[20:21], s[54:55], exec
	s_cselect_b32 s57, s61, s69
	s_cselect_b32 s86, s60, s68
	s_ashr_i32 s51, s50, 31
	s_lshl_b64 s[20:21], s[50:51], 19
	s_add_u32 s62, s15, s20
	s_addc_u32 s63, s42, s21
	s_and_b64 s[20:21], s[54:55], exec
	s_cselect_b32 s51, s63, s77
	s_cselect_b32 s87, s62, s76
	s_add_u32 s68, s68, 0x40080
	s_addc_u32 s69, s69, 0
	s_add_u32 s91, s76, 0x100
	v_mov_b32_e32 v2, 0
	s_addc_u32 s96, s77, 0
	s_mov_b32 s97, -2
	v_add_u32_e32 v243, 0x10000, v139
	ds_read_b128 v[134:137], v243
	ds_read_b128 v[144:147], v243 offset:1024
	ds_read_b128 v[148:151], v243 offset:2048
	ds_read_b128 v[152:155], v243 offset:3072
	ds_read_b128 v[156:159], v243 offset:16384
	ds_read_b128 v[160:163], v243 offset:17408
	ds_read_b128 v[182:185], v243 offset:18432
	ds_read_b128 v[186:189], v243 offset:19456
	ds_read_b128 v[190:193], v142
	ds_read_b128 v[194:197], v142 offset:1024
	ds_read_b128 v[198:201], v142 offset:2048
	ds_read_b128 v[214:217], v142 offset:3072
	ds_read_b128 v[218:221], v142 offset:4096
	ds_read_b128 v[222:225], v142 offset:5120
	ds_read_b128 v[226:229], v142 offset:6144
	ds_read_b128 v[230:233], v142 offset:7168
	s_cmp_eq_u64 s[48:49], 0
	s_cbranch_scc0 .Lpr_488
	s_setprio 1

.Lmid1_488:
	s_add_u32 s20, s68, 0xfffc0080
	s_addc_u32 s21, s69, -1
	s_cmp_eq_u32 s97, 12
	s_cselect_b32 s77, s57, s21
	s_cselect_b32 s76, s86, s20
	s_cselect_b32 s21, s51, s96
	s_cselect_b32 s20, s87, s91
	s_add_i32 m0, s43, 0xc000
	v_lshl_add_u64 v[202:203], s[68:69], 0, v[132:133]
	global_load_lds_dwordx4 v[202:203], off
	v_lshl_add_u64 v[202:203], v[202:203], 0, s[72:73]
	s_add_i32 m0, s43, 0xe000
	s_nop 0
	global_load_lds_dwordx4 v[202:203], off
	s_waitcnt vmcnt(8) lgkmcnt(0)
	s_barrier
	v_mfma_f32_16x16x32_bf16 v[126:129], v[134:137], v[190:193], 0
	v_mfma_f32_16x16x32_bf16 v[126:129], v[144:147], v[194:197], v[126:129]
	v_mfma_f32_16x16x32_bf16 v[114:117], v[148:151], v[190:193], 0
	v_mfma_f32_16x16x32_bf16 v[114:117], v[152:155], v[194:197], v[114:117]
	v_mfma_f32_16x16x32_bf16 v[110:113], v[134:137], v[198:201], 0
	v_mfma_f32_16x16x32_bf16 v[110:113], v[144:147], v[214:217], v[110:113]
	v_mfma_f32_16x16x32_bf16 v[98:101], v[148:151], v[198:201], 0
	v_mfma_f32_16x16x32_bf16 v[98:101], v[152:155], v[214:217], v[98:101]
	v_mfma_f32_16x16x32_bf16 v[94:97], v[134:137], v[218:221], 0
	v_mfma_f32_16x16x32_bf16 v[94:97], v[144:147], v[222:225], v[94:97]
	v_mfma_f32_16x16x32_bf16 v[82:85], v[148:151], v[218:221], 0
	v_mfma_f32_16x16x32_bf16 v[82:85], v[152:155], v[222:225], v[82:85]
	v_mfma_f32_16x16x32_bf16 v[78:81], v[134:137], v[226:229], 0
	v_mfma_f32_16x16x32_bf16 v[78:81], v[144:147], v[230:233], v[78:81]
	v_mfma_f32_16x16x32_bf16 v[66:69], v[148:151], v[226:229], 0
	v_mfma_f32_16x16x32_bf16 v[66:69], v[152:155], v[230:233], v[66:69]
	v_mfma_f32_16x16x32_bf16 v[122:125], v[156:159], v[190:193], 0
	v_mfma_f32_16x16x32_bf16 v[122:125], v[160:163], v[194:197], v[122:125]
	v_mfma_f32_16x16x32_bf16 v[118:121], v[182:185], v[190:193], 0
	v_mfma_f32_16x16x32_bf16 v[118:121], v[186:189], v[194:197], v[118:121]
	v_mfma_f32_16x16x32_bf16 v[106:109], v[156:159], v[198:201], 0
	v_mfma_f32_16x16x32_bf16 v[106:109], v[160:163], v[214:217], v[106:109]
	v_mfma_f32_16x16x32_bf16 v[102:105], v[182:185], v[198:201], 0
	v_mfma_f32_16x16x32_bf16 v[102:105], v[186:189], v[214:217], v[102:105]
	v_mfma_f32_16x16x32_bf16 v[90:93], v[156:159], v[218:221], 0
	v_mfma_f32_16x16x32_bf16 v[90:93], v[160:163], v[222:225], v[90:93]
	v_mfma_f32_16x16x32_bf16 v[86:89], v[182:185], v[218:221], 0
	v_mfma_f32_16x16x32_bf16 v[86:89], v[186:189], v[222:225], v[86:89]
	v_mfma_f32_16x16x32_bf16 v[74:77], v[156:159], v[226:229], 0
	v_mfma_f32_16x16x32_bf16 v[74:77], v[160:163], v[230:233], v[74:77]
	v_mfma_f32_16x16x32_bf16 v[70:73], v[182:185], v[226:229], 0
	v_mfma_f32_16x16x32_bf16 v[70:73], v[186:189], v[230:233], v[70:73]
	s_barrier
	ds_read_b128 v[190:193], v142 offset:16384
	ds_read_b128 v[194:197], v142 offset:17408
	ds_read_b128 v[198:201], v142 offset:18432
	ds_read_b128 v[214:217], v142 offset:19456
	ds_read_b128 v[218:221], v142 offset:20480
	ds_read_b128 v[222:225], v142 offset:21504
	ds_read_b128 v[226:229], v142 offset:22528
	ds_read_b128 v[230:233], v142 offset:23552
	v_lshl_add_u64 v[202:203], s[20:21], 0, v[0:1]
	s_add_i32 s20, s14, 0x10000
	s_mov_b32 m0, s20
	s_nop 0
	s_nop 0
	global_load_lds_dwordx4 v[202:203], off
	v_lshl_add_u64 v[234:235], v[202:203], 0, s[72:73]
	s_add_i32 m0, s20, 0x2000
	s_add_i32 s20, s14, 0x14000
	global_load_lds_dwordx4 v[234:235], off
	v_lshl_add_u64 v[234:235], v[202:203], 0, s[28:29]
	s_mov_b32 m0, s20
	s_nop 0
	global_load_lds_dwordx4 v[234:235], off
	v_lshl_add_u64 v[234:235], v[202:203], 0, s[82:83]
	s_add_i32 m0, s20, 0x2000
	s_nop 0
	global_load_lds_dwordx4 v[234:235], off
	v_lshl_add_u64 v[234:235], s[76:77], 0, v[130:131]
	s_mov_b32 m0, s43
	v_lshl_add_u64 v[236:237], v[234:235], 0, s[72:73]
	global_load_lds_dwordx4 v[234:235], off
	s_mov_b32 m0, s46
	s_nop 0
	global_load_lds_dwordx4 v[236:237], off
	s_waitcnt vmcnt(8) lgkmcnt(0)
	s_barrier
	v_mfma_f32_16x16x32_bf16 v[62:65], v[134:137], v[190:193], 0
	v_mfma_f32_16x16x32_bf16 v[62:65], v[144:147], v[194:197], v[62:65]
	v_mfma_f32_16x16x32_bf16 v[50:53], v[148:151], v[190:193], 0
	v_mfma_f32_16x16x32_bf16 v[50:53], v[152:155], v[194:197], v[50:53]
	v_mfma_f32_16x16x32_bf16 v[46:49], v[134:137], v[198:201], 0
	v_mfma_f32_16x16x32_bf16 v[46:49], v[144:147], v[214:217], v[46:49]
	v_mfma_f32_16x16x32_bf16 v[34:37], v[148:151], v[198:201], 0
	v_mfma_f32_16x16x32_bf16 v[34:37], v[152:155], v[214:217], v[34:37]
	v_mfma_f32_16x16x32_bf16 v[30:33], v[134:137], v[218:221], 0
	v_mfma_f32_16x16x32_bf16 v[30:33], v[144:147], v[222:225], v[30:33]
	v_mfma_f32_16x16x32_bf16 v[18:21], v[148:151], v[218:221], 0
	v_mfma_f32_16x16x32_bf16 v[18:21], v[152:155], v[222:225], v[18:21]
	v_mfma_f32_16x16x32_bf16 v[14:17], v[134:137], v[226:229], 0
	v_mfma_f32_16x16x32_bf16 v[14:17], v[144:147], v[230:233], v[14:17]
	v_mfma_f32_16x16x32_bf16 v[6:9], v[148:151], v[226:229], 0
	v_mfma_f32_16x16x32_bf16 v[6:9], v[152:155], v[230:233], v[6:9]
	v_mfma_f32_16x16x32_bf16 v[58:61], v[156:159], v[190:193], 0
	v_mfma_f32_16x16x32_bf16 v[58:61], v[160:163], v[194:197], v[58:61]
	v_mfma_f32_16x16x32_bf16 v[54:57], v[182:185], v[190:193], 0
	v_mfma_f32_16x16x32_bf16 v[54:57], v[186:189], v[194:197], v[54:57]
	v_mfma_f32_16x16x32_bf16 v[42:45], v[156:159], v[198:201], 0
	v_mfma_f32_16x16x32_bf16 v[42:45], v[160:163], v[214:217], v[42:45]
	v_mfma_f32_16x16x32_bf16 v[38:41], v[182:185], v[198:201], 0
	v_mfma_f32_16x16x32_bf16 v[38:41], v[186:189], v[214:217], v[38:41]
	v_mfma_f32_16x16x32_bf16 v[26:29], v[156:159], v[218:221], 0
	v_mfma_f32_16x16x32_bf16 v[26:29], v[160:163], v[222:225], v[26:29]
	v_mfma_f32_16x16x32_bf16 v[22:25], v[182:185], v[218:221], 0
	v_mfma_f32_16x16x32_bf16 v[22:25], v[186:189], v[222:225], v[22:25]
	v_mfma_f32_16x16x32_bf16 v[10:13], v[156:159], v[226:229], 0
	v_mfma_f32_16x16x32_bf16 v[10:13], v[160:163], v[230:233], v[10:13]
	v_mfma_f32_16x16x32_bf16 v[2:5], v[182:185], v[226:229], 0
	v_mfma_f32_16x16x32_bf16 v[2:5], v[186:189], v[230:233], v[2:5]
	s_barrier
	ds_read_b128 v[134:137], v243 offset:32768
	ds_read_b128 v[144:147], v243 offset:33792
	ds_read_b128 v[148:151], v243 offset:34816
	ds_read_b128 v[152:155], v243 offset:35840
	ds_read_b128 v[156:159], v243 offset:49152
	ds_read_b128 v[160:163], v243 offset:50176
	ds_read_b128 v[182:185], v243 offset:51200
	ds_read_b128 v[186:189], v243 offset:52224
	ds_read_b128 v[190:193], v142 offset:32768
	ds_read_b128 v[194:197], v142 offset:33792
	ds_read_b128 v[198:201], v142 offset:34816
	ds_read_b128 v[214:217], v142 offset:35840
	ds_read_b128 v[218:221], v142 offset:36864
	ds_read_b128 v[222:225], v142 offset:37888
	ds_read_b128 v[226:229], v142 offset:38912
	ds_read_b128 v[230:233], v142 offset:39936
	s_mov_b32 m0, s47
	v_lshl_add_u64 v[236:237], v[234:235], 0, s[28:29]
	global_load_lds_dwordx4 v[236:237], off
	v_lshl_add_u64 v[236:237], v[234:235], 0, s[82:83]
	s_mov_b32 m0, s78
	s_nop 0
	global_load_lds_dwordx4 v[236:237], off
	s_waitcnt vmcnt(8) lgkmcnt(0)
	s_barrier
	v_mfma_f32_16x16x32_bf16 v[126:129], v[134:137], v[190:193], v[126:129]
	v_mfma_f32_16x16x32_bf16 v[126:129], v[144:147], v[194:197], v[126:129]
	v_mfma_f32_16x16x32_bf16 v[114:117], v[148:151], v[190:193], v[114:117]
	v_mfma_f32_16x16x32_bf16 v[114:117], v[152:155], v[194:197], v[114:117]
	v_mfma_f32_16x16x32_bf16 v[110:113], v[134:137], v[198:201], v[110:113]
	v_mfma_f32_16x16x32_bf16 v[110:113], v[144:147], v[214:217], v[110:113]
	v_mfma_f32_16x16x32_bf16 v[98:101], v[148:151], v[198:201], v[98:101]
	v_mfma_f32_16x16x32_bf16 v[98:101], v[152:155], v[214:217], v[98:101]
	v_mfma_f32_16x16x32_bf16 v[94:97], v[134:137], v[218:221], v[94:97]
	v_mfma_f32_16x16x32_bf16 v[94:97], v[144:147], v[222:225], v[94:97]
	v_mfma_f32_16x16x32_bf16 v[82:85], v[148:151], v[218:221], v[82:85]
	v_mfma_f32_16x16x32_bf16 v[82:85], v[152:155], v[222:225], v[82:85]
	v_mfma_f32_16x16x32_bf16 v[78:81], v[134:137], v[226:229], v[78:81]
	v_mfma_f32_16x16x32_bf16 v[78:81], v[144:147], v[230:233], v[78:81]
	v_mfma_f32_16x16x32_bf16 v[66:69], v[148:151], v[226:229], v[66:69]
	v_mfma_f32_16x16x32_bf16 v[66:69], v[152:155], v[230:233], v[66:69]
	v_mfma_f32_16x16x32_bf16 v[122:125], v[156:159], v[190:193], v[122:125]
	v_mfma_f32_16x16x32_bf16 v[122:125], v[160:163], v[194:197], v[122:125]
	v_mfma_f32_16x16x32_bf16 v[118:121], v[182:185], v[190:193], v[118:121]
	v_mfma_f32_16x16x32_bf16 v[118:121], v[186:189], v[194:197], v[118:121]
	v_mfma_f32_16x16x32_bf16 v[106:109], v[156:159], v[198:201], v[106:109]
	v_mfma_f32_16x16x32_bf16 v[106:109], v[160:163], v[214:217], v[106:109]
	v_mfma_f32_16x16x32_bf16 v[102:105], v[182:185], v[198:201], v[102:105]
	v_mfma_f32_16x16x32_bf16 v[102:105], v[186:189], v[214:217], v[102:105]
	v_mfma_f32_16x16x32_bf16 v[90:93], v[156:159], v[218:221], v[90:93]
	v_mfma_f32_16x16x32_bf16 v[90:93], v[160:163], v[222:225], v[90:93]
	v_mfma_f32_16x16x32_bf16 v[86:89], v[182:185], v[218:221], v[86:89]
	v_mfma_f32_16x16x32_bf16 v[86:89], v[186:189], v[222:225], v[86:89]
	v_mfma_f32_16x16x32_bf16 v[74:77], v[156:159], v[226:229], v[74:77]
	v_mfma_f32_16x16x32_bf16 v[74:77], v[160:163], v[230:233], v[74:77]
	v_mfma_f32_16x16x32_bf16 v[70:73], v[182:185], v[226:229], v[70:73]
	v_mfma_f32_16x16x32_bf16 v[70:73], v[186:189], v[230:233], v[70:73]
	s_barrier
	ds_read_b128 v[190:193], v142 offset:49152
	ds_read_b128 v[194:197], v142 offset:50176
	ds_read_b128 v[198:201], v142 offset:51200
	ds_read_b128 v[214:217], v142 offset:52224
	ds_read_b128 v[218:221], v142 offset:53248
	ds_read_b128 v[222:225], v142 offset:54272
	ds_read_b128 v[226:229], v142 offset:55296
	ds_read_b128 v[230:233], v142 offset:56320
	s_add_i32 s20, s14, 0x18000
	s_mov_b32 m0, s20
	v_lshl_add_u64 v[236:237], v[202:203], 0, s[34:35]
	global_load_lds_dwordx4 v[236:237], off
	v_lshl_add_u64 v[236:237], v[202:203], 0, s[38:39]
	s_add_i32 m0, s20, 0x2000
	s_add_i32 s20, s14, 0x1c000
	global_load_lds_dwordx4 v[236:237], off
	v_lshl_add_u64 v[236:237], v[202:203], 0, s[44:45]
	s_mov_b32 m0, s20
	v_lshl_add_u64 v[202:203], v[202:203], 0, s[10:11]
	global_load_lds_dwordx4 v[236:237], off
	s_add_i32 m0, s20, 0x2000
	s_nop 0
	global_load_lds_dwordx4 v[202:203], off
	v_lshl_add_u64 v[202:203], v[234:235], 0, s[34:35]
	s_mov_b32 m0, s79
	s_nop 0
	global_load_lds_dwordx4 v[202:203], off
	v_lshl_add_u64 v[202:203], v[234:235], 0, s[38:39]
	s_mov_b32 m0, s88
	s_nop 0
	global_load_lds_dwordx4 v[202:203], off
	s_waitcnt vmcnt(8) lgkmcnt(0)
	s_barrier
	v_mfma_f32_16x16x32_bf16 v[62:65], v[134:137], v[190:193], v[62:65]
	v_mfma_f32_16x16x32_bf16 v[62:65], v[144:147], v[194:197], v[62:65]
	v_mfma_f32_16x16x32_bf16 v[50:53], v[148:151], v[190:193], v[50:53]
	v_mfma_f32_16x16x32_bf16 v[50:53], v[152:155], v[194:197], v[50:53]
	v_mfma_f32_16x16x32_bf16 v[46:49], v[134:137], v[198:201], v[46:49]
	v_mfma_f32_16x16x32_bf16 v[46:49], v[144:147], v[214:217], v[46:49]
	v_mfma_f32_16x16x32_bf16 v[34:37], v[148:151], v[198:201], v[34:37]
	v_mfma_f32_16x16x32_bf16 v[34:37], v[152:155], v[214:217], v[34:37]
	v_mfma_f32_16x16x32_bf16 v[30:33], v[134:137], v[218:221], v[30:33]
	v_mfma_f32_16x16x32_bf16 v[30:33], v[144:147], v[222:225], v[30:33]
	v_mfma_f32_16x16x32_bf16 v[18:21], v[148:151], v[218:221], v[18:21]
	v_mfma_f32_16x16x32_bf16 v[18:21], v[152:155], v[222:225], v[18:21]
	v_mfma_f32_16x16x32_bf16 v[14:17], v[134:137], v[226:229], v[14:17]
	v_mfma_f32_16x16x32_bf16 v[14:17], v[144:147], v[230:233], v[14:17]
	v_mfma_f32_16x16x32_bf16 v[6:9], v[148:151], v[226:229], v[6:9]
	v_mfma_f32_16x16x32_bf16 v[6:9], v[152:155], v[230:233], v[6:9]
	s_add_i32 s97, s97, 2
	s_add_u32 s68, s68, 0x100
	s_addc_u32 s69, s69, 0
	s_add_u32 s91, s91, 0x100
	s_addc_u32 s96, s96, 0
	v_mfma_f32_16x16x32_bf16 v[58:61], v[156:159], v[190:193], v[58:61]
	v_mfma_f32_16x16x32_bf16 v[58:61], v[160:163], v[194:197], v[58:61]
	v_mfma_f32_16x16x32_bf16 v[54:57], v[182:185], v[190:193], v[54:57]
	v_mfma_f32_16x16x32_bf16 v[54:57], v[186:189], v[194:197], v[54:57]
	v_mfma_f32_16x16x32_bf16 v[42:45], v[156:159], v[198:201], v[42:45]
	v_mfma_f32_16x16x32_bf16 v[42:45], v[160:163], v[214:217], v[42:45]
	v_mfma_f32_16x16x32_bf16 v[38:41], v[182:185], v[198:201], v[38:41]
	v_mfma_f32_16x16x32_bf16 v[38:41], v[186:189], v[214:217], v[38:41]
	v_mfma_f32_16x16x32_bf16 v[26:29], v[156:159], v[218:221], v[26:29]
	v_mfma_f32_16x16x32_bf16 v[26:29], v[160:163], v[222:225], v[26:29]
	v_mfma_f32_16x16x32_bf16 v[22:25], v[182:185], v[218:221], v[22:25]
	v_mfma_f32_16x16x32_bf16 v[22:25], v[186:189], v[222:225], v[22:25]
	v_mfma_f32_16x16x32_bf16 v[10:13], v[156:159], v[226:229], v[10:13]
	v_mfma_f32_16x16x32_bf16 v[10:13], v[160:163], v[230:233], v[10:13]
	v_mfma_f32_16x16x32_bf16 v[2:5], v[182:185], v[226:229], v[2:5]
	v_mfma_f32_16x16x32_bf16 v[2:5], v[186:189], v[230:233], v[2:5]
	s_barrier
	s_branch .LBB0_488
	.p2alignl 6, 3212836864
.LBB0_488:
	ds_read_b128 v[134:137], v243
	ds_read_b128 v[144:147], v243 offset:1024
	ds_read_b128 v[148:151], v243 offset:2048
	ds_read_b128 v[152:155], v243 offset:3072
	ds_read_b128 v[156:159], v243 offset:16384
	ds_read_b128 v[160:163], v243 offset:17408
	ds_read_b128 v[182:185], v243 offset:18432
	ds_read_b128 v[186:189], v243 offset:19456
	ds_read_b128 v[190:193], v142
	ds_read_b128 v[194:197], v142 offset:1024
	ds_read_b128 v[198:201], v142 offset:2048
	ds_read_b128 v[214:217], v142 offset:3072
	ds_read_b128 v[218:221], v142 offset:4096
	ds_read_b128 v[222:225], v142 offset:5120
	ds_read_b128 v[226:229], v142 offset:6144
	ds_read_b128 v[230:233], v142 offset:7168
	s_add_u32 s20, s68, 0xfffc0080
	s_addc_u32 s21, s69, -1
	s_cmp_eq_u32 s97, 12
	s_cselect_b32 s77, s57, s21
	s_cselect_b32 s76, s86, s20
	s_cselect_b32 s21, s51, s96
	s_cselect_b32 s20, s87, s91
	s_add_i32 m0, s43, 0xc000
	v_lshl_add_u64 v[202:203], s[68:69], 0, v[132:133]
	global_load_lds_dwordx4 v[202:203], off
	v_lshl_add_u64 v[202:203], v[202:203], 0, s[72:73]
	s_add_i32 m0, s43, 0xe000
	s_nop 0
	global_load_lds_dwordx4 v[202:203], off
	s_waitcnt vmcnt(8) lgkmcnt(0)
	s_barrier
	v_mfma_f32_16x16x32_bf16 v[126:129], v[134:137], v[190:193], v[126:129]
	v_mfma_f32_16x16x32_bf16 v[126:129], v[144:147], v[194:197], v[126:129]
	v_mfma_f32_16x16x32_bf16 v[114:117], v[148:151], v[190:193], v[114:117]
	v_mfma_f32_16x16x32_bf16 v[114:117], v[152:155], v[194:197], v[114:117]
	v_mfma_f32_16x16x32_bf16 v[110:113], v[134:137], v[198:201], v[110:113]
	v_mfma_f32_16x16x32_bf16 v[110:113], v[144:147], v[214:217], v[110:113]
	v_mfma_f32_16x16x32_bf16 v[98:101], v[148:151], v[198:201], v[98:101]
	v_mfma_f32_16x16x32_bf16 v[98:101], v[152:155], v[214:217], v[98:101]
	v_mfma_f32_16x16x32_bf16 v[94:97], v[134:137], v[218:221], v[94:97]
	v_mfma_f32_16x16x32_bf16 v[94:97], v[144:147], v[222:225], v[94:97]
	v_mfma_f32_16x16x32_bf16 v[82:85], v[148:151], v[218:221], v[82:85]
	v_mfma_f32_16x16x32_bf16 v[82:85], v[152:155], v[222:225], v[82:85]
	v_mfma_f32_16x16x32_bf16 v[78:81], v[134:137], v[226:229], v[78:81]
	v_mfma_f32_16x16x32_bf16 v[78:81], v[144:147], v[230:233], v[78:81]
	v_mfma_f32_16x16x32_bf16 v[66:69], v[148:151], v[226:229], v[66:69]
	v_mfma_f32_16x16x32_bf16 v[66:69], v[152:155], v[230:233], v[66:69]
	v_mfma_f32_16x16x32_bf16 v[122:125], v[156:159], v[190:193], v[122:125]
	v_mfma_f32_16x16x32_bf16 v[122:125], v[160:163], v[194:197], v[122:125]
	v_mfma_f32_16x16x32_bf16 v[118:121], v[182:185], v[190:193], v[118:121]
	v_mfma_f32_16x16x32_bf16 v[118:121], v[186:189], v[194:197], v[118:121]
	v_mfma_f32_16x16x32_bf16 v[106:109], v[156:159], v[198:201], v[106:109]
	v_mfma_f32_16x16x32_bf16 v[106:109], v[160:163], v[214:217], v[106:109]
	v_mfma_f32_16x16x32_bf16 v[102:105], v[182:185], v[198:201], v[102:105]
	v_mfma_f32_16x16x32_bf16 v[102:105], v[186:189], v[214:217], v[102:105]
	v_mfma_f32_16x16x32_bf16 v[90:93], v[156:159], v[218:221], v[90:93]
	v_mfma_f32_16x16x32_bf16 v[90:93], v[160:163], v[222:225], v[90:93]
	v_mfma_f32_16x16x32_bf16 v[86:89], v[182:185], v[218:221], v[86:89]
	v_mfma_f32_16x16x32_bf16 v[86:89], v[186:189], v[222:225], v[86:89]
	v_mfma_f32_16x16x32_bf16 v[74:77], v[156:159], v[226:229], v[74:77]
	v_mfma_f32_16x16x32_bf16 v[74:77], v[160:163], v[230:233], v[74:77]
	v_mfma_f32_16x16x32_bf16 v[70:73], v[182:185], v[226:229], v[70:73]
	v_mfma_f32_16x16x32_bf16 v[70:73], v[186:189], v[230:233], v[70:73]
	s_barrier
	ds_read_b128 v[190:193], v142 offset:16384
	ds_read_b128 v[194:197], v142 offset:17408
	ds_read_b128 v[198:201], v142 offset:18432
	ds_read_b128 v[214:217], v142 offset:19456
	ds_read_b128 v[218:221], v142 offset:20480
	ds_read_b128 v[222:225], v142 offset:21504
	ds_read_b128 v[226:229], v142 offset:22528
	ds_read_b128 v[230:233], v142 offset:23552
	v_lshl_add_u64 v[202:203], s[20:21], 0, v[0:1]
	s_add_i32 s20, s14, 0x10000
	s_mov_b32 m0, s20
	s_nop 0
	s_nop 0
	global_load_lds_dwordx4 v[202:203], off
	v_lshl_add_u64 v[234:235], v[202:203], 0, s[72:73]
	s_add_i32 m0, s20, 0x2000
	s_add_i32 s20, s14, 0x14000
	global_load_lds_dwordx4 v[234:235], off
	v_lshl_add_u64 v[234:235], v[202:203], 0, s[28:29]
	s_mov_b32 m0, s20
	s_nop 0
	global_load_lds_dwordx4 v[234:235], off
	v_lshl_add_u64 v[234:235], v[202:203], 0, s[82:83]
	s_add_i32 m0, s20, 0x2000
	s_nop 0
	global_load_lds_dwordx4 v[234:235], off
	v_lshl_add_u64 v[234:235], s[76:77], 0, v[130:131]
	s_mov_b32 m0, s43
	v_lshl_add_u64 v[236:237], v[234:235], 0, s[72:73]
	global_load_lds_dwordx4 v[234:235], off
	s_mov_b32 m0, s46
	s_nop 0
	global_load_lds_dwordx4 v[236:237], off
	s_waitcnt vmcnt(8) lgkmcnt(0)
	s_barrier
	v_mfma_f32_16x16x32_bf16 v[62:65], v[134:137], v[190:193], v[62:65]
	v_mfma_f32_16x16x32_bf16 v[62:65], v[144:147], v[194:197], v[62:65]
	v_mfma_f32_16x16x32_bf16 v[50:53], v[148:151], v[190:193], v[50:53]
	v_mfma_f32_16x16x32_bf16 v[50:53], v[152:155], v[194:197], v[50:53]
	v_mfma_f32_16x16x32_bf16 v[46:49], v[134:137], v[198:201], v[46:49]
	v_mfma_f32_16x16x32_bf16 v[46:49], v[144:147], v[214:217], v[46:49]
	v_mfma_f32_16x16x32_bf16 v[34:37], v[148:151], v[198:201], v[34:37]
	v_mfma_f32_16x16x32_bf16 v[34:37], v[152:155], v[214:217], v[34:37]
	v_mfma_f32_16x16x32_bf16 v[30:33], v[134:137], v[218:221], v[30:33]
	v_mfma_f32_16x16x32_bf16 v[30:33], v[144:147], v[222:225], v[30:33]
	v_mfma_f32_16x16x32_bf16 v[18:21], v[148:151], v[218:221], v[18:21]
	v_mfma_f32_16x16x32_bf16 v[18:21], v[152:155], v[222:225], v[18:21]
	v_mfma_f32_16x16x32_bf16 v[14:17], v[134:137], v[226:229], v[14:17]
	v_mfma_f32_16x16x32_bf16 v[14:17], v[144:147], v[230:233], v[14:17]
	v_mfma_f32_16x16x32_bf16 v[6:9], v[148:151], v[226:229], v[6:9]
	v_mfma_f32_16x16x32_bf16 v[6:9], v[152:155], v[230:233], v[6:9]
	v_mfma_f32_16x16x32_bf16 v[58:61], v[156:159], v[190:193], v[58:61]
	v_mfma_f32_16x16x32_bf16 v[58:61], v[160:163], v[194:197], v[58:61]
	v_mfma_f32_16x16x32_bf16 v[54:57], v[182:185], v[190:193], v[54:57]
	v_mfma_f32_16x16x32_bf16 v[54:57], v[186:189], v[194:197], v[54:57]
	v_mfma_f32_16x16x32_bf16 v[42:45], v[156:159], v[198:201], v[42:45]
	v_mfma_f32_16x16x32_bf16 v[42:45], v[160:163], v[214:217], v[42:45]
	v_mfma_f32_16x16x32_bf16 v[38:41], v[182:185], v[198:201], v[38:41]
	v_mfma_f32_16x16x32_bf16 v[38:41], v[186:189], v[214:217], v[38:41]
	v_mfma_f32_16x16x32_bf16 v[26:29], v[156:159], v[218:221], v[26:29]
	v_mfma_f32_16x16x32_bf16 v[26:29], v[160:163], v[222:225], v[26:29]
	v_mfma_f32_16x16x32_bf16 v[22:25], v[182:185], v[218:221], v[22:25]
	v_mfma_f32_16x16x32_bf16 v[22:25], v[186:189], v[222:225], v[22:25]
	v_mfma_f32_16x16x32_bf16 v[10:13], v[156:159], v[226:229], v[10:13]
	v_mfma_f32_16x16x32_bf16 v[10:13], v[160:163], v[230:233], v[10:13]
	v_mfma_f32_16x16x32_bf16 v[2:5], v[182:185], v[226:229], v[2:5]
	v_mfma_f32_16x16x32_bf16 v[2:5], v[186:189], v[230:233], v[2:5]
	s_barrier
	ds_read_b128 v[134:137], v243 offset:32768
	ds_read_b128 v[144:147], v243 offset:33792
	ds_read_b128 v[148:151], v243 offset:34816
	ds_read_b128 v[152:155], v243 offset:35840
	ds_read_b128 v[156:159], v243 offset:49152
	ds_read_b128 v[160:163], v243 offset:50176
	ds_read_b128 v[182:185], v243 offset:51200
	ds_read_b128 v[186:189], v243 offset:52224
	ds_read_b128 v[190:193], v142 offset:32768
	ds_read_b128 v[194:197], v142 offset:33792
	ds_read_b128 v[198:201], v142 offset:34816
	ds_read_b128 v[214:217], v142 offset:35840
	ds_read_b128 v[218:221], v142 offset:36864
	ds_read_b128 v[222:225], v142 offset:37888
	ds_read_b128 v[226:229], v142 offset:38912
	ds_read_b128 v[230:233], v142 offset:39936
	s_mov_b32 m0, s47
	v_lshl_add_u64 v[236:237], v[234:235], 0, s[28:29]
	global_load_lds_dwordx4 v[236:237], off
	v_lshl_add_u64 v[236:237], v[234:235], 0, s[82:83]
	s_mov_b32 m0, s78
	s_nop 0
	global_load_lds_dwordx4 v[236:237], off
	s_waitcnt vmcnt(8) lgkmcnt(0)
	s_barrier
	v_mfma_f32_16x16x32_bf16 v[126:129], v[134:137], v[190:193], v[126:129]
	v_mfma_f32_16x16x32_bf16 v[126:129], v[144:147], v[194:197], v[126:129]
	v_mfma_f32_16x16x32_bf16 v[114:117], v[148:151], v[190:193], v[114:117]
	v_mfma_f32_16x16x32_bf16 v[114:117], v[152:155], v[194:197], v[114:117]
	v_mfma_f32_16x16x32_bf16 v[110:113], v[134:137], v[198:201], v[110:113]
	v_mfma_f32_16x16x32_bf16 v[110:113], v[144:147], v[214:217], v[110:113]
	v_mfma_f32_16x16x32_bf16 v[98:101], v[148:151], v[198:201], v[98:101]
	v_mfma_f32_16x16x32_bf16 v[98:101], v[152:155], v[214:217], v[98:101]
	v_mfma_f32_16x16x32_bf16 v[94:97], v[134:137], v[218:221], v[94:97]
	v_mfma_f32_16x16x32_bf16 v[94:97], v[144:147], v[222:225], v[94:97]
	v_mfma_f32_16x16x32_bf16 v[82:85], v[148:151], v[218:221], v[82:85]
	v_mfma_f32_16x16x32_bf16 v[82:85], v[152:155], v[222:225], v[82:85]
	v_mfma_f32_16x16x32_bf16 v[78:81], v[134:137], v[226:229], v[78:81]
	v_mfma_f32_16x16x32_bf16 v[78:81], v[144:147], v[230:233], v[78:81]
	v_mfma_f32_16x16x32_bf16 v[66:69], v[148:151], v[226:229], v[66:69]
	v_mfma_f32_16x16x32_bf16 v[66:69], v[152:155], v[230:233], v[66:69]
	v_mfma_f32_16x16x32_bf16 v[122:125], v[156:159], v[190:193], v[122:125]
	v_mfma_f32_16x16x32_bf16 v[122:125], v[160:163], v[194:197], v[122:125]
	v_mfma_f32_16x16x32_bf16 v[118:121], v[182:185], v[190:193], v[118:121]
	v_mfma_f32_16x16x32_bf16 v[118:121], v[186:189], v[194:197], v[118:121]
	v_mfma_f32_16x16x32_bf16 v[106:109], v[156:159], v[198:201], v[106:109]
	v_mfma_f32_16x16x32_bf16 v[106:109], v[160:163], v[214:217], v[106:109]
	v_mfma_f32_16x16x32_bf16 v[102:105], v[182:185], v[198:201], v[102:105]
	v_mfma_f32_16x16x32_bf16 v[102:105], v[186:189], v[214:217], v[102:105]
	v_mfma_f32_16x16x32_bf16 v[90:93], v[156:159], v[218:221], v[90:93]
	v_mfma_f32_16x16x32_bf16 v[90:93], v[160:163], v[222:225], v[90:93]
	v_mfma_f32_16x16x32_bf16 v[86:89], v[182:185], v[218:221], v[86:89]
	v_mfma_f32_16x16x32_bf16 v[86:89], v[186:189], v[222:225], v[86:89]
	v_mfma_f32_16x16x32_bf16 v[74:77], v[156:159], v[226:229], v[74:77]
	v_mfma_f32_16x16x32_bf16 v[74:77], v[160:163], v[230:233], v[74:77]
	v_mfma_f32_16x16x32_bf16 v[70:73], v[182:185], v[226:229], v[70:73]
	v_mfma_f32_16x16x32_bf16 v[70:73], v[186:189], v[230:233], v[70:73]
	s_barrier
	ds_read_b128 v[190:193], v142 offset:49152
	ds_read_b128 v[194:197], v142 offset:50176
	ds_read_b128 v[198:201], v142 offset:51200
	ds_read_b128 v[214:217], v142 offset:52224
	ds_read_b128 v[218:221], v142 offset:53248
	ds_read_b128 v[222:225], v142 offset:54272
	ds_read_b128 v[226:229], v142 offset:55296
	ds_read_b128 v[230:233], v142 offset:56320
	s_add_i32 s20, s14, 0x18000
	s_mov_b32 m0, s20
	v_lshl_add_u64 v[236:237], v[202:203], 0, s[34:35]
	global_load_lds_dwordx4 v[236:237], off
	v_lshl_add_u64 v[236:237], v[202:203], 0, s[38:39]
	s_add_i32 m0, s20, 0x2000
	s_add_i32 s20, s14, 0x1c000
	global_load_lds_dwordx4 v[236:237], off
	v_lshl_add_u64 v[236:237], v[202:203], 0, s[44:45]
	s_mov_b32 m0, s20
	v_lshl_add_u64 v[202:203], v[202:203], 0, s[10:11]
	global_load_lds_dwordx4 v[236:237], off
	s_add_i32 m0, s20, 0x2000
	s_nop 0
	global_load_lds_dwordx4 v[202:203], off
	v_lshl_add_u64 v[202:203], v[234:235], 0, s[34:35]
	s_mov_b32 m0, s79
	s_nop 0
	global_load_lds_dwordx4 v[202:203], off
	v_lshl_add_u64 v[202:203], v[234:235], 0, s[38:39]
	s_mov_b32 m0, s88
	s_nop 0
	global_load_lds_dwordx4 v[202:203], off
	s_waitcnt vmcnt(8) lgkmcnt(0)
	s_barrier
	v_mfma_f32_16x16x32_bf16 v[62:65], v[134:137], v[190:193], v[62:65]
	v_mfma_f32_16x16x32_bf16 v[62:65], v[144:147], v[194:197], v[62:65]
	v_mfma_f32_16x16x32_bf16 v[50:53], v[148:151], v[190:193], v[50:53]
	v_mfma_f32_16x16x32_bf16 v[50:53], v[152:155], v[194:197], v[50:53]
	v_mfma_f32_16x16x32_bf16 v[46:49], v[134:137], v[198:201], v[46:49]
	v_mfma_f32_16x16x32_bf16 v[46:49], v[144:147], v[214:217], v[46:49]
	v_mfma_f32_16x16x32_bf16 v[34:37], v[148:151], v[198:201], v[34:37]
	v_mfma_f32_16x16x32_bf16 v[34:37], v[152:155], v[214:217], v[34:37]
	v_mfma_f32_16x16x32_bf16 v[30:33], v[134:137], v[218:221], v[30:33]
	v_mfma_f32_16x16x32_bf16 v[30:33], v[144:147], v[222:225], v[30:33]
	v_mfma_f32_16x16x32_bf16 v[18:21], v[148:151], v[218:221], v[18:21]
	v_mfma_f32_16x16x32_bf16 v[18:21], v[152:155], v[222:225], v[18:21]
	v_mfma_f32_16x16x32_bf16 v[14:17], v[134:137], v[226:229], v[14:17]
	v_mfma_f32_16x16x32_bf16 v[14:17], v[144:147], v[230:233], v[14:17]
	v_mfma_f32_16x16x32_bf16 v[6:9], v[148:151], v[226:229], v[6:9]
	v_mfma_f32_16x16x32_bf16 v[6:9], v[152:155], v[230:233], v[6:9]
	s_add_i32 s97, s97, 2
	s_add_u32 s68, s68, 0x100
	s_addc_u32 s69, s69, 0
	s_add_u32 s91, s91, 0x100
	s_addc_u32 s96, s96, 0
	v_mfma_f32_16x16x32_bf16 v[58:61], v[156:159], v[190:193], v[58:61]
	v_mfma_f32_16x16x32_bf16 v[58:61], v[160:163], v[194:197], v[58:61]
	v_mfma_f32_16x16x32_bf16 v[54:57], v[182:185], v[190:193], v[54:57]
	v_mfma_f32_16x16x32_bf16 v[54:57], v[186:189], v[194:197], v[54:57]
	v_mfma_f32_16x16x32_bf16 v[42:45], v[156:159], v[198:201], v[42:45]
	v_mfma_f32_16x16x32_bf16 v[42:45], v[160:163], v[214:217], v[42:45]
	v_mfma_f32_16x16x32_bf16 v[38:41], v[182:185], v[198:201], v[38:41]
	v_mfma_f32_16x16x32_bf16 v[38:41], v[186:189], v[214:217], v[38:41]
	v_mfma_f32_16x16x32_bf16 v[26:29], v[156:159], v[218:221], v[26:29]
	v_mfma_f32_16x16x32_bf16 v[26:29], v[160:163], v[222:225], v[26:29]
	v_mfma_f32_16x16x32_bf16 v[22:25], v[182:185], v[218:221], v[22:25]
	v_mfma_f32_16x16x32_bf16 v[22:25], v[186:189], v[222:225], v[22:25]
	v_mfma_f32_16x16x32_bf16 v[10:13], v[156:159], v[226:229], v[10:13]
	v_mfma_f32_16x16x32_bf16 v[10:13], v[160:163], v[230:233], v[10:13]
	v_mfma_f32_16x16x32_bf16 v[2:5], v[182:185], v[226:229], v[2:5]
	v_mfma_f32_16x16x32_bf16 v[2:5], v[186:189], v[230:233], v[2:5]
	s_barrier
	s_cmp_gt_u32 s97, 13
	s_cbranch_scc0 .LBB0_488
	s_setprio 0
	s_and_b64 vcc, exec, s[48:49]
	s_cbranch_vccz .LBB0_491
	s_barrier

.LBB0_603:
	s_ashr_i32 s51, s50, 31
	s_lshl_b64 s[20:21], s[50:51], 18
	s_add_u32 s78, s0, s20
	s_addc_u32 s79, s1, s21
	s_and_b64 s[20:21], s[56:57], exec
	s_cselect_b32 s42, s79, s7
	s_cselect_b32 s43, s78, s6
	s_ashr_i32 s49, s48, 31
	s_lshl_b64 s[20:21], s[48:49], 18
	s_add_u32 s40, s76, s20
	s_addc_u32 s41, s77, s21
	s_and_b64 s[20:21], s[56:57], exec
	s_cselect_b32 s46, s41, s69
	s_cselect_b32 s47, s40, s68
	s_add_u32 s6, s6, 0x20080
	s_addc_u32 s7, s7, 0
	s_add_u32 s49, s68, 0x100
	v_mov_b32_e32 v2, 0
	s_addc_u32 s51, s69, 0
	s_mov_b32 s84, -2
	s_waitcnt lgkmcnt(0)
	v_add_u32_e32 v243, 0x10000, v139
	ds_read_b128 v[134:137], v243
	ds_read_b128 v[142:145], v243 offset:1024
	ds_read_b128 v[146:149], v243 offset:2048
	ds_read_b128 v[150:153], v243 offset:3072
	ds_read_b128 v[154:157], v243 offset:16384
	ds_read_b128 v[158:161], v243 offset:17408
	ds_read_b128 v[182:185], v243 offset:18432
	ds_read_b128 v[186:189], v243 offset:19456
	ds_read_b128 v[190:193], v141
	ds_read_b128 v[194:197], v141 offset:1024
	ds_read_b128 v[198:201], v141 offset:2048
	ds_read_b128 v[214:217], v141 offset:3072
	ds_read_b128 v[218:221], v141 offset:4096
	ds_read_b128 v[222:225], v141 offset:5120
	ds_read_b128 v[226:229], v141 offset:6144
	ds_read_b128 v[230:233], v141 offset:7168
	s_cmp_eq_u64 s[52:53], 0
	s_cbranch_scc0 .Lpr_604
	s_setprio 1

.Lmid1_604:
	s_add_u32 s20, s6, 0xfffe0080
	s_addc_u32 s21, s7, -1
	s_cmp_eq_u32 s84, 4
	s_cselect_b32 s69, s42, s21
	s_cselect_b32 s68, s43, s20
	s_cselect_b32 s21, s46, s51
	s_cselect_b32 s20, s47, s49
	s_add_i32 m0, s89, 0xc000
	v_lshl_add_u64 v[162:163], s[6:7], 0, v[132:133]
	global_load_lds_dwordx4 v[162:163], off
	v_lshl_add_u64 v[162:163], v[162:163], 0, s[64:65]
	s_add_i32 m0, s89, 0xe000
	s_nop 0
	global_load_lds_dwordx4 v[162:163], off
	s_waitcnt vmcnt(8) lgkmcnt(0)
	s_barrier
	v_mfma_f32_16x16x32_bf16 v[126:129], v[134:137], v[190:193], 0
	v_mfma_f32_16x16x32_bf16 v[126:129], v[142:145], v[194:197], v[126:129]
	v_mfma_f32_16x16x32_bf16 v[122:125], v[146:149], v[190:193], 0
	v_mfma_f32_16x16x32_bf16 v[122:125], v[150:153], v[194:197], v[122:125]
	v_mfma_f32_16x16x32_bf16 v[110:113], v[134:137], v[198:201], 0
	v_mfma_f32_16x16x32_bf16 v[110:113], v[142:145], v[214:217], v[110:113]
	v_mfma_f32_16x16x32_bf16 v[106:109], v[146:149], v[198:201], 0
	v_mfma_f32_16x16x32_bf16 v[106:109], v[150:153], v[214:217], v[106:109]
	v_mfma_f32_16x16x32_bf16 v[94:97], v[134:137], v[218:221], 0
	v_mfma_f32_16x16x32_bf16 v[94:97], v[142:145], v[222:225], v[94:97]
	v_mfma_f32_16x16x32_bf16 v[90:93], v[146:149], v[218:221], 0
	v_mfma_f32_16x16x32_bf16 v[90:93], v[150:153], v[222:225], v[90:93]
	v_mfma_f32_16x16x32_bf16 v[78:81], v[134:137], v[226:229], 0
	v_mfma_f32_16x16x32_bf16 v[78:81], v[142:145], v[230:233], v[78:81]
	v_mfma_f32_16x16x32_bf16 v[74:77], v[146:149], v[226:229], 0
	v_mfma_f32_16x16x32_bf16 v[74:77], v[150:153], v[230:233], v[74:77]
	v_mfma_f32_16x16x32_bf16 v[118:121], v[154:157], v[190:193], 0
	v_mfma_f32_16x16x32_bf16 v[118:121], v[158:161], v[194:197], v[118:121]
	v_mfma_f32_16x16x32_bf16 v[114:117], v[182:185], v[190:193], 0
	v_mfma_f32_16x16x32_bf16 v[114:117], v[186:189], v[194:197], v[114:117]
	v_mfma_f32_16x16x32_bf16 v[102:105], v[154:157], v[198:201], 0
	v_mfma_f32_16x16x32_bf16 v[102:105], v[158:161], v[214:217], v[102:105]
	v_mfma_f32_16x16x32_bf16 v[98:101], v[182:185], v[198:201], 0
	v_mfma_f32_16x16x32_bf16 v[98:101], v[186:189], v[214:217], v[98:101]
	v_mfma_f32_16x16x32_bf16 v[86:89], v[154:157], v[218:221], 0
	v_mfma_f32_16x16x32_bf16 v[86:89], v[158:161], v[222:225], v[86:89]
	v_mfma_f32_16x16x32_bf16 v[82:85], v[182:185], v[218:221], 0
	v_mfma_f32_16x16x32_bf16 v[82:85], v[186:189], v[222:225], v[82:85]
	v_mfma_f32_16x16x32_bf16 v[70:73], v[154:157], v[226:229], 0
	v_mfma_f32_16x16x32_bf16 v[70:73], v[158:161], v[230:233], v[70:73]
	v_mfma_f32_16x16x32_bf16 v[66:69], v[182:185], v[226:229], 0
	v_mfma_f32_16x16x32_bf16 v[66:69], v[186:189], v[230:233], v[66:69]
	s_barrier
	ds_read_b128 v[190:193], v141 offset:16384
	ds_read_b128 v[194:197], v141 offset:17408
	ds_read_b128 v[198:201], v141 offset:18432
	ds_read_b128 v[214:217], v141 offset:19456
	ds_read_b128 v[218:221], v141 offset:20480
	ds_read_b128 v[222:225], v141 offset:21504
	ds_read_b128 v[226:229], v141 offset:22528
	ds_read_b128 v[230:233], v141 offset:23552
	v_lshl_add_u64 v[162:163], s[20:21], 0, v[0:1]
	s_add_i32 s20, s88, 0x10000
	s_mov_b32 m0, s20
	s_nop 0
	s_nop 0
	global_load_lds_dwordx4 v[162:163], off
	v_lshl_add_u64 v[202:203], v[162:163], 0, s[64:65]
	s_add_i32 m0, s20, 0x2000
	s_add_i32 s20, s88, 0x14000
	global_load_lds_dwordx4 v[202:203], off
	v_lshl_add_u64 v[202:203], v[162:163], 0, s[72:73]
	s_mov_b32 m0, s20
	s_nop 0
	global_load_lds_dwordx4 v[202:203], off
	v_lshl_add_u64 v[202:203], v[162:163], 0, s[74:75]
	s_add_i32 m0, s20, 0x2000
	s_nop 0
	global_load_lds_dwordx4 v[202:203], off
	v_lshl_add_u64 v[202:203], s[68:69], 0, v[130:131]
	s_mov_b32 m0, s89
	v_lshl_add_u64 v[234:235], v[202:203], 0, s[64:65]
	global_load_lds_dwordx4 v[202:203], off
	s_mov_b32 m0, s90
	s_nop 0
	global_load_lds_dwordx4 v[234:235], off
	s_waitcnt vmcnt(8) lgkmcnt(0)
	s_barrier
	v_mfma_f32_16x16x32_bf16 v[62:65], v[134:137], v[190:193], 0
	v_mfma_f32_16x16x32_bf16 v[62:65], v[142:145], v[194:197], v[62:65]
	v_mfma_f32_16x16x32_bf16 v[58:61], v[146:149], v[190:193], 0
	v_mfma_f32_16x16x32_bf16 v[58:61], v[150:153], v[194:197], v[58:61]
	v_mfma_f32_16x16x32_bf16 v[46:49], v[134:137], v[198:201], 0
	v_mfma_f32_16x16x32_bf16 v[46:49], v[142:145], v[214:217], v[46:49]
	v_mfma_f32_16x16x32_bf16 v[42:45], v[146:149], v[198:201], 0
	v_mfma_f32_16x16x32_bf16 v[42:45], v[150:153], v[214:217], v[42:45]
	v_mfma_f32_16x16x32_bf16 v[30:33], v[134:137], v[218:221], 0
	v_mfma_f32_16x16x32_bf16 v[30:33], v[142:145], v[222:225], v[30:33]
	v_mfma_f32_16x16x32_bf16 v[26:29], v[146:149], v[218:221], 0
	v_mfma_f32_16x16x32_bf16 v[26:29], v[150:153], v[222:225], v[26:29]
	v_mfma_f32_16x16x32_bf16 v[14:17], v[134:137], v[226:229], 0
	v_mfma_f32_16x16x32_bf16 v[14:17], v[142:145], v[230:233], v[14:17]
	v_mfma_f32_16x16x32_bf16 v[10:13], v[146:149], v[226:229], 0
	v_mfma_f32_16x16x32_bf16 v[10:13], v[150:153], v[230:233], v[10:13]
	v_mfma_f32_16x16x32_bf16 v[54:57], v[154:157], v[190:193], 0
	v_mfma_f32_16x16x32_bf16 v[54:57], v[158:161], v[194:197], v[54:57]
	v_mfma_f32_16x16x32_bf16 v[50:53], v[182:185], v[190:193], 0
	v_mfma_f32_16x16x32_bf16 v[50:53], v[186:189], v[194:197], v[50:53]
	v_mfma_f32_16x16x32_bf16 v[38:41], v[154:157], v[198:201], 0
	v_mfma_f32_16x16x32_bf16 v[38:41], v[158:161], v[214:217], v[38:41]
	v_mfma_f32_16x16x32_bf16 v[34:37], v[182:185], v[198:201], 0
	v_mfma_f32_16x16x32_bf16 v[34:37], v[186:189], v[214:217], v[34:37]
	v_mfma_f32_16x16x32_bf16 v[22:25], v[154:157], v[218:221], 0
	v_mfma_f32_16x16x32_bf16 v[22:25], v[158:161], v[222:225], v[22:25]
	v_mfma_f32_16x16x32_bf16 v[18:21], v[182:185], v[218:221], 0
	v_mfma_f32_16x16x32_bf16 v[18:21], v[186:189], v[222:225], v[18:21]
	v_mfma_f32_16x16x32_bf16 v[6:9], v[154:157], v[226:229], 0
	v_mfma_f32_16x16x32_bf16 v[6:9], v[158:161], v[230:233], v[6:9]
	v_mfma_f32_16x16x32_bf16 v[2:5], v[182:185], v[226:229], 0
	v_mfma_f32_16x16x32_bf16 v[2:5], v[186:189], v[230:233], v[2:5]
	s_barrier
	ds_read_b128 v[134:137], v243 offset:32768
	ds_read_b128 v[142:145], v243 offset:33792
	ds_read_b128 v[146:149], v243 offset:34816
	ds_read_b128 v[150:153], v243 offset:35840
	ds_read_b128 v[154:157], v243 offset:49152
	ds_read_b128 v[158:161], v243 offset:50176
	ds_read_b128 v[182:185], v243 offset:51200
	ds_read_b128 v[186:189], v243 offset:52224
	ds_read_b128 v[190:193], v141 offset:32768
	ds_read_b128 v[194:197], v141 offset:33792
	ds_read_b128 v[198:201], v141 offset:34816
	ds_read_b128 v[214:217], v141 offset:35840
	ds_read_b128 v[218:221], v141 offset:36864
	ds_read_b128 v[222:225], v141 offset:37888
	ds_read_b128 v[226:229], v141 offset:38912
	ds_read_b128 v[230:233], v141 offset:39936
	s_mov_b32 m0, s91
	v_lshl_add_u64 v[234:235], v[202:203], 0, s[72:73]
	global_load_lds_dwordx4 v[234:235], off
	v_lshl_add_u64 v[234:235], v[202:203], 0, s[74:75]
	s_mov_b32 m0, s96
	s_nop 0
	global_load_lds_dwordx4 v[234:235], off
	s_waitcnt vmcnt(8) lgkmcnt(0)
	s_barrier
	v_mfma_f32_16x16x32_bf16 v[126:129], v[134:137], v[190:193], v[126:129]
	v_mfma_f32_16x16x32_bf16 v[126:129], v[142:145], v[194:197], v[126:129]
	v_mfma_f32_16x16x32_bf16 v[122:125], v[146:149], v[190:193], v[122:125]
	v_mfma_f32_16x16x32_bf16 v[122:125], v[150:153], v[194:197], v[122:125]
	v_mfma_f32_16x16x32_bf16 v[110:113], v[134:137], v[198:201], v[110:113]
	v_mfma_f32_16x16x32_bf16 v[110:113], v[142:145], v[214:217], v[110:113]
	v_mfma_f32_16x16x32_bf16 v[106:109], v[146:149], v[198:201], v[106:109]
	v_mfma_f32_16x16x32_bf16 v[106:109], v[150:153], v[214:217], v[106:109]
	v_mfma_f32_16x16x32_bf16 v[94:97], v[134:137], v[218:221], v[94:97]
	v_mfma_f32_16x16x32_bf16 v[94:97], v[142:145], v[222:225], v[94:97]
	v_mfma_f32_16x16x32_bf16 v[90:93], v[146:149], v[218:221], v[90:93]
	v_mfma_f32_16x16x32_bf16 v[90:93], v[150:153], v[222:225], v[90:93]
	v_mfma_f32_16x16x32_bf16 v[78:81], v[134:137], v[226:229], v[78:81]
	v_mfma_f32_16x16x32_bf16 v[78:81], v[142:145], v[230:233], v[78:81]
	v_mfma_f32_16x16x32_bf16 v[74:77], v[146:149], v[226:229], v[74:77]
	v_mfma_f32_16x16x32_bf16 v[74:77], v[150:153], v[230:233], v[74:77]
	v_mfma_f32_16x16x32_bf16 v[118:121], v[154:157], v[190:193], v[118:121]
	v_mfma_f32_16x16x32_bf16 v[118:121], v[158:161], v[194:197], v[118:121]
	v_mfma_f32_16x16x32_bf16 v[114:117], v[182:185], v[190:193], v[114:117]
	v_mfma_f32_16x16x32_bf16 v[114:117], v[186:189], v[194:197], v[114:117]
	v_mfma_f32_16x16x32_bf16 v[102:105], v[154:157], v[198:201], v[102:105]
	v_mfma_f32_16x16x32_bf16 v[102:105], v[158:161], v[214:217], v[102:105]
	v_mfma_f32_16x16x32_bf16 v[98:101], v[182:185], v[198:201], v[98:101]
	v_mfma_f32_16x16x32_bf16 v[98:101], v[186:189], v[214:217], v[98:101]
	v_mfma_f32_16x16x32_bf16 v[86:89], v[154:157], v[218:221], v[86:89]
	v_mfma_f32_16x16x32_bf16 v[86:89], v[158:161], v[222:225], v[86:89]
	v_mfma_f32_16x16x32_bf16 v[82:85], v[182:185], v[218:221], v[82:85]
	v_mfma_f32_16x16x32_bf16 v[82:85], v[186:189], v[222:225], v[82:85]
	v_mfma_f32_16x16x32_bf16 v[70:73], v[154:157], v[226:229], v[70:73]
	v_mfma_f32_16x16x32_bf16 v[70:73], v[158:161], v[230:233], v[70:73]
	v_mfma_f32_16x16x32_bf16 v[66:69], v[182:185], v[226:229], v[66:69]
	v_mfma_f32_16x16x32_bf16 v[66:69], v[186:189], v[230:233], v[66:69]
	s_barrier
	ds_read_b128 v[190:193], v141 offset:49152
	ds_read_b128 v[194:197], v141 offset:50176
	ds_read_b128 v[198:201], v141 offset:51200
	ds_read_b128 v[214:217], v141 offset:52224
	ds_read_b128 v[218:221], v141 offset:53248
	ds_read_b128 v[222:225], v141 offset:54272
	ds_read_b128 v[226:229], v141 offset:55296
	ds_read_b128 v[230:233], v141 offset:56320
	s_add_i32 s20, s88, 0x18000
	s_mov_b32 m0, s20
	v_lshl_add_u64 v[234:235], v[162:163], 0, s[34:35]
	global_load_lds_dwordx4 v[234:235], off
	v_lshl_add_u64 v[234:235], v[162:163], 0, s[80:81]
	s_add_i32 m0, s20, 0x2000
	s_add_i32 s20, s88, 0x1c000
	global_load_lds_dwordx4 v[234:235], off
	v_lshl_add_u64 v[234:235], v[162:163], 0, s[38:39]
	s_mov_b32 m0, s20
	v_lshl_add_u64 v[162:163], v[162:163], 0, s[86:87]
	global_load_lds_dwordx4 v[234:235], off
	s_add_i32 m0, s20, 0x2000
	s_nop 0
	global_load_lds_dwordx4 v[162:163], off
	v_lshl_add_u64 v[162:163], v[202:203], 0, s[34:35]
	s_mov_b32 m0, s97
	s_nop 0
	global_load_lds_dwordx4 v[162:163], off
	v_lshl_add_u64 v[162:163], v[202:203], 0, s[80:81]
	s_mov_b32 m0, s58
	s_nop 0
	global_load_lds_dwordx4 v[162:163], off
	s_waitcnt vmcnt(8) lgkmcnt(0)
	s_barrier
	v_mfma_f32_16x16x32_bf16 v[62:65], v[134:137], v[190:193], v[62:65]
	v_mfma_f32_16x16x32_bf16 v[62:65], v[142:145], v[194:197], v[62:65]
	v_mfma_f32_16x16x32_bf16 v[58:61], v[146:149], v[190:193], v[58:61]
	v_mfma_f32_16x16x32_bf16 v[58:61], v[150:153], v[194:197], v[58:61]
	v_mfma_f32_16x16x32_bf16 v[46:49], v[134:137], v[198:201], v[46:49]
	v_mfma_f32_16x16x32_bf16 v[46:49], v[142:145], v[214:217], v[46:49]
	v_mfma_f32_16x16x32_bf16 v[42:45], v[146:149], v[198:201], v[42:45]
	v_mfma_f32_16x16x32_bf16 v[42:45], v[150:153], v[214:217], v[42:45]
	v_mfma_f32_16x16x32_bf16 v[30:33], v[134:137], v[218:221], v[30:33]
	v_mfma_f32_16x16x32_bf16 v[30:33], v[142:145], v[222:225], v[30:33]
	v_mfma_f32_16x16x32_bf16 v[26:29], v[146:149], v[218:221], v[26:29]
	v_mfma_f32_16x16x32_bf16 v[26:29], v[150:153], v[222:225], v[26:29]
	v_mfma_f32_16x16x32_bf16 v[14:17], v[134:137], v[226:229], v[14:17]
	v_mfma_f32_16x16x32_bf16 v[14:17], v[142:145], v[230:233], v[14:17]
	v_mfma_f32_16x16x32_bf16 v[10:13], v[146:149], v[226:229], v[10:13]
	v_mfma_f32_16x16x32_bf16 v[10:13], v[150:153], v[230:233], v[10:13]
	s_add_i32 s84, s84, 2
	s_add_u32 s6, s6, 0x100
	s_addc_u32 s7, s7, 0
	s_add_u32 s49, s49, 0x100
	s_addc_u32 s51, s51, 0
	v_mfma_f32_16x16x32_bf16 v[54:57], v[154:157], v[190:193], v[54:57]
	v_mfma_f32_16x16x32_bf16 v[54:57], v[158:161], v[194:197], v[54:57]
	v_mfma_f32_16x16x32_bf16 v[50:53], v[182:185], v[190:193], v[50:53]
	v_mfma_f32_16x16x32_bf16 v[50:53], v[186:189], v[194:197], v[50:53]
	v_mfma_f32_16x16x32_bf16 v[38:41], v[154:157], v[198:201], v[38:41]
	v_mfma_f32_16x16x32_bf16 v[38:41], v[158:161], v[214:217], v[38:41]
	v_mfma_f32_16x16x32_bf16 v[34:37], v[182:185], v[198:201], v[34:37]
	v_mfma_f32_16x16x32_bf16 v[34:37], v[186:189], v[214:217], v[34:37]
	v_mfma_f32_16x16x32_bf16 v[22:25], v[154:157], v[218:221], v[22:25]
	v_mfma_f32_16x16x32_bf16 v[22:25], v[158:161], v[222:225], v[22:25]
	v_mfma_f32_16x16x32_bf16 v[18:21], v[182:185], v[218:221], v[18:21]
	v_mfma_f32_16x16x32_bf16 v[18:21], v[186:189], v[222:225], v[18:21]
	v_mfma_f32_16x16x32_bf16 v[6:9], v[154:157], v[226:229], v[6:9]
	v_mfma_f32_16x16x32_bf16 v[6:9], v[158:161], v[230:233], v[6:9]
	v_mfma_f32_16x16x32_bf16 v[2:5], v[182:185], v[226:229], v[2:5]
	v_mfma_f32_16x16x32_bf16 v[2:5], v[186:189], v[230:233], v[2:5]
	s_barrier
	s_branch .LBB0_604
	.p2alignl 6, 3212836864
.LBB0_604:
	ds_read_b128 v[134:137], v243
	ds_read_b128 v[142:145], v243 offset:1024
	ds_read_b128 v[146:149], v243 offset:2048
	ds_read_b128 v[150:153], v243 offset:3072
	ds_read_b128 v[154:157], v243 offset:16384
	ds_read_b128 v[158:161], v243 offset:17408
	ds_read_b128 v[182:185], v243 offset:18432
	ds_read_b128 v[186:189], v243 offset:19456
	ds_read_b128 v[190:193], v141
	ds_read_b128 v[194:197], v141 offset:1024
	ds_read_b128 v[198:201], v141 offset:2048
	ds_read_b128 v[214:217], v141 offset:3072
	ds_read_b128 v[218:221], v141 offset:4096
	ds_read_b128 v[222:225], v141 offset:5120
	ds_read_b128 v[226:229], v141 offset:6144
	ds_read_b128 v[230:233], v141 offset:7168
	s_add_u32 s20, s6, 0xfffe0080
	s_addc_u32 s21, s7, -1
	s_cmp_eq_u32 s84, 4
	s_cselect_b32 s69, s42, s21
	s_cselect_b32 s68, s43, s20
	s_cselect_b32 s21, s46, s51
	s_cselect_b32 s20, s47, s49
	s_add_i32 m0, s89, 0xc000
	v_lshl_add_u64 v[162:163], s[6:7], 0, v[132:133]
	global_load_lds_dwordx4 v[162:163], off
	v_lshl_add_u64 v[162:163], v[162:163], 0, s[64:65]
	s_add_i32 m0, s89, 0xe000
	s_nop 0
	global_load_lds_dwordx4 v[162:163], off
	s_waitcnt vmcnt(8) lgkmcnt(0)
	s_barrier
	v_mfma_f32_16x16x32_bf16 v[126:129], v[134:137], v[190:193], v[126:129]
	v_mfma_f32_16x16x32_bf16 v[126:129], v[142:145], v[194:197], v[126:129]
	v_mfma_f32_16x16x32_bf16 v[122:125], v[146:149], v[190:193], v[122:125]
	v_mfma_f32_16x16x32_bf16 v[122:125], v[150:153], v[194:197], v[122:125]
	v_mfma_f32_16x16x32_bf16 v[110:113], v[134:137], v[198:201], v[110:113]
	v_mfma_f32_16x16x32_bf16 v[110:113], v[142:145], v[214:217], v[110:113]
	v_mfma_f32_16x16x32_bf16 v[106:109], v[146:149], v[198:201], v[106:109]
	v_mfma_f32_16x16x32_bf16 v[106:109], v[150:153], v[214:217], v[106:109]
	v_mfma_f32_16x16x32_bf16 v[94:97], v[134:137], v[218:221], v[94:97]
	v_mfma_f32_16x16x32_bf16 v[94:97], v[142:145], v[222:225], v[94:97]
	v_mfma_f32_16x16x32_bf16 v[90:93], v[146:149], v[218:221], v[90:93]
	v_mfma_f32_16x16x32_bf16 v[90:93], v[150:153], v[222:225], v[90:93]
	v_mfma_f32_16x16x32_bf16 v[78:81], v[134:137], v[226:229], v[78:81]
	v_mfma_f32_16x16x32_bf16 v[78:81], v[142:145], v[230:233], v[78:81]
	v_mfma_f32_16x16x32_bf16 v[74:77], v[146:149], v[226:229], v[74:77]
	v_mfma_f32_16x16x32_bf16 v[74:77], v[150:153], v[230:233], v[74:77]
	v_mfma_f32_16x16x32_bf16 v[118:121], v[154:157], v[190:193], v[118:121]
	v_mfma_f32_16x16x32_bf16 v[118:121], v[158:161], v[194:197], v[118:121]
	v_mfma_f32_16x16x32_bf16 v[114:117], v[182:185], v[190:193], v[114:117]
	v_mfma_f32_16x16x32_bf16 v[114:117], v[186:189], v[194:197], v[114:117]
	v_mfma_f32_16x16x32_bf16 v[102:105], v[154:157], v[198:201], v[102:105]
	v_mfma_f32_16x16x32_bf16 v[102:105], v[158:161], v[214:217], v[102:105]
	v_mfma_f32_16x16x32_bf16 v[98:101], v[182:185], v[198:201], v[98:101]
	v_mfma_f32_16x16x32_bf16 v[98:101], v[186:189], v[214:217], v[98:101]
	v_mfma_f32_16x16x32_bf16 v[86:89], v[154:157], v[218:221], v[86:89]
	v_mfma_f32_16x16x32_bf16 v[86:89], v[158:161], v[222:225], v[86:89]
	v_mfma_f32_16x16x32_bf16 v[82:85], v[182:185], v[218:221], v[82:85]
	v_mfma_f32_16x16x32_bf16 v[82:85], v[186:189], v[222:225], v[82:85]
	v_mfma_f32_16x16x32_bf16 v[70:73], v[154:157], v[226:229], v[70:73]
	v_mfma_f32_16x16x32_bf16 v[70:73], v[158:161], v[230:233], v[70:73]
	v_mfma_f32_16x16x32_bf16 v[66:69], v[182:185], v[226:229], v[66:69]
	v_mfma_f32_16x16x32_bf16 v[66:69], v[186:189], v[230:233], v[66:69]
	s_barrier
	ds_read_b128 v[190:193], v141 offset:16384
	ds_read_b128 v[194:197], v141 offset:17408
	ds_read_b128 v[198:201], v141 offset:18432
	ds_read_b128 v[214:217], v141 offset:19456
	ds_read_b128 v[218:221], v141 offset:20480
	ds_read_b128 v[222:225], v141 offset:21504
	ds_read_b128 v[226:229], v141 offset:22528
	ds_read_b128 v[230:233], v141 offset:23552
	v_lshl_add_u64 v[162:163], s[20:21], 0, v[0:1]
	s_add_i32 s20, s88, 0x10000
	s_mov_b32 m0, s20
	s_nop 0
	s_nop 0
	global_load_lds_dwordx4 v[162:163], off
	v_lshl_add_u64 v[202:203], v[162:163], 0, s[64:65]
	s_add_i32 m0, s20, 0x2000
	s_add_i32 s20, s88, 0x14000
	global_load_lds_dwordx4 v[202:203], off
	v_lshl_add_u64 v[202:203], v[162:163], 0, s[72:73]
	s_mov_b32 m0, s20
	s_nop 0
	global_load_lds_dwordx4 v[202:203], off
	v_lshl_add_u64 v[202:203], v[162:163], 0, s[74:75]
	s_add_i32 m0, s20, 0x2000
	s_nop 0
	global_load_lds_dwordx4 v[202:203], off
	v_lshl_add_u64 v[202:203], s[68:69], 0, v[130:131]
	s_mov_b32 m0, s89
	v_lshl_add_u64 v[234:235], v[202:203], 0, s[64:65]
	global_load_lds_dwordx4 v[202:203], off
	s_mov_b32 m0, s90
	s_nop 0
	global_load_lds_dwordx4 v[234:235], off
	s_waitcnt vmcnt(8) lgkmcnt(0)
	s_barrier
	v_mfma_f32_16x16x32_bf16 v[62:65], v[134:137], v[190:193], v[62:65]
	v_mfma_f32_16x16x32_bf16 v[62:65], v[142:145], v[194:197], v[62:65]
	v_mfma_f32_16x16x32_bf16 v[58:61], v[146:149], v[190:193], v[58:61]
	v_mfma_f32_16x16x32_bf16 v[58:61], v[150:153], v[194:197], v[58:61]
	v_mfma_f32_16x16x32_bf16 v[46:49], v[134:137], v[198:201], v[46:49]
	v_mfma_f32_16x16x32_bf16 v[46:49], v[142:145], v[214:217], v[46:49]
	v_mfma_f32_16x16x32_bf16 v[42:45], v[146:149], v[198:201], v[42:45]
	v_mfma_f32_16x16x32_bf16 v[42:45], v[150:153], v[214:217], v[42:45]
	v_mfma_f32_16x16x32_bf16 v[30:33], v[134:137], v[218:221], v[30:33]
	v_mfma_f32_16x16x32_bf16 v[30:33], v[142:145], v[222:225], v[30:33]
	v_mfma_f32_16x16x32_bf16 v[26:29], v[146:149], v[218:221], v[26:29]
	v_mfma_f32_16x16x32_bf16 v[26:29], v[150:153], v[222:225], v[26:29]
	v_mfma_f32_16x16x32_bf16 v[14:17], v[134:137], v[226:229], v[14:17]
	v_mfma_f32_16x16x32_bf16 v[14:17], v[142:145], v[230:233], v[14:17]
	v_mfma_f32_16x16x32_bf16 v[10:13], v[146:149], v[226:229], v[10:13]
	v_mfma_f32_16x16x32_bf16 v[10:13], v[150:153], v[230:233], v[10:13]
	v_mfma_f32_16x16x32_bf16 v[54:57], v[154:157], v[190:193], v[54:57]
	v_mfma_f32_16x16x32_bf16 v[54:57], v[158:161], v[194:197], v[54:57]
	v_mfma_f32_16x16x32_bf16 v[50:53], v[182:185], v[190:193], v[50:53]
	v_mfma_f32_16x16x32_bf16 v[50:53], v[186:189], v[194:197], v[50:53]
	v_mfma_f32_16x16x32_bf16 v[38:41], v[154:157], v[198:201], v[38:41]
	v_mfma_f32_16x16x32_bf16 v[38:41], v[158:161], v[214:217], v[38:41]
	v_mfma_f32_16x16x32_bf16 v[34:37], v[182:185], v[198:201], v[34:37]
	v_mfma_f32_16x16x32_bf16 v[34:37], v[186:189], v[214:217], v[34:37]
	v_mfma_f32_16x16x32_bf16 v[22:25], v[154:157], v[218:221], v[22:25]
	v_mfma_f32_16x16x32_bf16 v[22:25], v[158:161], v[222:225], v[22:25]
	v_mfma_f32_16x16x32_bf16 v[18:21], v[182:185], v[218:221], v[18:21]
	v_mfma_f32_16x16x32_bf16 v[18:21], v[186:189], v[222:225], v[18:21]
	v_mfma_f32_16x16x32_bf16 v[6:9], v[154:157], v[226:229], v[6:9]
	v_mfma_f32_16x16x32_bf16 v[6:9], v[158:161], v[230:233], v[6:9]
	v_mfma_f32_16x16x32_bf16 v[2:5], v[182:185], v[226:229], v[2:5]
	v_mfma_f32_16x16x32_bf16 v[2:5], v[186:189], v[230:233], v[2:5]
	s_barrier
	ds_read_b128 v[134:137], v243 offset:32768
	ds_read_b128 v[142:145], v243 offset:33792
	ds_read_b128 v[146:149], v243 offset:34816
	ds_read_b128 v[150:153], v243 offset:35840
	ds_read_b128 v[154:157], v243 offset:49152
	ds_read_b128 v[158:161], v243 offset:50176
	ds_read_b128 v[182:185], v243 offset:51200
	ds_read_b128 v[186:189], v243 offset:52224
	ds_read_b128 v[190:193], v141 offset:32768
	ds_read_b128 v[194:197], v141 offset:33792
	ds_read_b128 v[198:201], v141 offset:34816
	ds_read_b128 v[214:217], v141 offset:35840
	ds_read_b128 v[218:221], v141 offset:36864
	ds_read_b128 v[222:225], v141 offset:37888
	ds_read_b128 v[226:229], v141 offset:38912
	ds_read_b128 v[230:233], v141 offset:39936
	s_mov_b32 m0, s91
	v_lshl_add_u64 v[234:235], v[202:203], 0, s[72:73]
	global_load_lds_dwordx4 v[234:235], off
	v_lshl_add_u64 v[234:235], v[202:203], 0, s[74:75]
	s_mov_b32 m0, s96
	s_nop 0
	global_load_lds_dwordx4 v[234:235], off
	s_waitcnt vmcnt(8) lgkmcnt(0)
	s_barrier
	v_mfma_f32_16x16x32_bf16 v[126:129], v[134:137], v[190:193], v[126:129]
	v_mfma_f32_16x16x32_bf16 v[126:129], v[142:145], v[194:197], v[126:129]
	v_mfma_f32_16x16x32_bf16 v[122:125], v[146:149], v[190:193], v[122:125]
	v_mfma_f32_16x16x32_bf16 v[122:125], v[150:153], v[194:197], v[122:125]
	v_mfma_f32_16x16x32_bf16 v[110:113], v[134:137], v[198:201], v[110:113]
	v_mfma_f32_16x16x32_bf16 v[110:113], v[142:145], v[214:217], v[110:113]
	v_mfma_f32_16x16x32_bf16 v[106:109], v[146:149], v[198:201], v[106:109]
	v_mfma_f32_16x16x32_bf16 v[106:109], v[150:153], v[214:217], v[106:109]
	v_mfma_f32_16x16x32_bf16 v[94:97], v[134:137], v[218:221], v[94:97]
	v_mfma_f32_16x16x32_bf16 v[94:97], v[142:145], v[222:225], v[94:97]
	v_mfma_f32_16x16x32_bf16 v[90:93], v[146:149], v[218:221], v[90:93]
	v_mfma_f32_16x16x32_bf16 v[90:93], v[150:153], v[222:225], v[90:93]
	v_mfma_f32_16x16x32_bf16 v[78:81], v[134:137], v[226:229], v[78:81]
	v_mfma_f32_16x16x32_bf16 v[78:81], v[142:145], v[230:233], v[78:81]
	v_mfma_f32_16x16x32_bf16 v[74:77], v[146:149], v[226:229], v[74:77]
	v_mfma_f32_16x16x32_bf16 v[74:77], v[150:153], v[230:233], v[74:77]
	v_mfma_f32_16x16x32_bf16 v[118:121], v[154:157], v[190:193], v[118:121]
	v_mfma_f32_16x16x32_bf16 v[118:121], v[158:161], v[194:197], v[118:121]
	v_mfma_f32_16x16x32_bf16 v[114:117], v[182:185], v[190:193], v[114:117]
	v_mfma_f32_16x16x32_bf16 v[114:117], v[186:189], v[194:197], v[114:117]
	v_mfma_f32_16x16x32_bf16 v[102:105], v[154:157], v[198:201], v[102:105]
	v_mfma_f32_16x16x32_bf16 v[102:105], v[158:161], v[214:217], v[102:105]
	v_mfma_f32_16x16x32_bf16 v[98:101], v[182:185], v[198:201], v[98:101]
	v_mfma_f32_16x16x32_bf16 v[98:101], v[186:189], v[214:217], v[98:101]
	v_mfma_f32_16x16x32_bf16 v[86:89], v[154:157], v[218:221], v[86:89]
	v_mfma_f32_16x16x32_bf16 v[86:89], v[158:161], v[222:225], v[86:89]
	v_mfma_f32_16x16x32_bf16 v[82:85], v[182:185], v[218:221], v[82:85]
	v_mfma_f32_16x16x32_bf16 v[82:85], v[186:189], v[222:225], v[82:85]
	v_mfma_f32_16x16x32_bf16 v[70:73], v[154:157], v[226:229], v[70:73]
	v_mfma_f32_16x16x32_bf16 v[70:73], v[158:161], v[230:233], v[70:73]
	v_mfma_f32_16x16x32_bf16 v[66:69], v[182:185], v[226:229], v[66:69]
	v_mfma_f32_16x16x32_bf16 v[66:69], v[186:189], v[230:233], v[66:69]
	s_barrier
	ds_read_b128 v[190:193], v141 offset:49152
	ds_read_b128 v[194:197], v141 offset:50176
	ds_read_b128 v[198:201], v141 offset:51200
	ds_read_b128 v[214:217], v141 offset:52224
	ds_read_b128 v[218:221], v141 offset:53248
	ds_read_b128 v[222:225], v141 offset:54272
	ds_read_b128 v[226:229], v141 offset:55296
	ds_read_b128 v[230:233], v141 offset:56320
	s_add_i32 s20, s88, 0x18000
	s_mov_b32 m0, s20
	v_lshl_add_u64 v[234:235], v[162:163], 0, s[34:35]
	global_load_lds_dwordx4 v[234:235], off
	v_lshl_add_u64 v[234:235], v[162:163], 0, s[80:81]
	s_add_i32 m0, s20, 0x2000
	s_add_i32 s20, s88, 0x1c000
	global_load_lds_dwordx4 v[234:235], off
	v_lshl_add_u64 v[234:235], v[162:163], 0, s[38:39]
	s_mov_b32 m0, s20
	v_lshl_add_u64 v[162:163], v[162:163], 0, s[86:87]
	global_load_lds_dwordx4 v[234:235], off
	s_add_i32 m0, s20, 0x2000
	s_nop 0
	global_load_lds_dwordx4 v[162:163], off
	v_lshl_add_u64 v[162:163], v[202:203], 0, s[34:35]
	s_mov_b32 m0, s97
	s_nop 0
	global_load_lds_dwordx4 v[162:163], off
	v_lshl_add_u64 v[162:163], v[202:203], 0, s[80:81]
	s_mov_b32 m0, s58
	s_nop 0
	global_load_lds_dwordx4 v[162:163], off
	s_waitcnt vmcnt(8) lgkmcnt(0)
	s_barrier
	v_mfma_f32_16x16x32_bf16 v[62:65], v[134:137], v[190:193], v[62:65]
	v_mfma_f32_16x16x32_bf16 v[62:65], v[142:145], v[194:197], v[62:65]
	v_mfma_f32_16x16x32_bf16 v[58:61], v[146:149], v[190:193], v[58:61]
	v_mfma_f32_16x16x32_bf16 v[58:61], v[150:153], v[194:197], v[58:61]
	v_mfma_f32_16x16x32_bf16 v[46:49], v[134:137], v[198:201], v[46:49]
	v_mfma_f32_16x16x32_bf16 v[46:49], v[142:145], v[214:217], v[46:49]
	v_mfma_f32_16x16x32_bf16 v[42:45], v[146:149], v[198:201], v[42:45]
	v_mfma_f32_16x16x32_bf16 v[42:45], v[150:153], v[214:217], v[42:45]
	v_mfma_f32_16x16x32_bf16 v[30:33], v[134:137], v[218:221], v[30:33]
	v_mfma_f32_16x16x32_bf16 v[30:33], v[142:145], v[222:225], v[30:33]
	v_mfma_f32_16x16x32_bf16 v[26:29], v[146:149], v[218:221], v[26:29]
	v_mfma_f32_16x16x32_bf16 v[26:29], v[150:153], v[222:225], v[26:29]
	v_mfma_f32_16x16x32_bf16 v[14:17], v[134:137], v[226:229], v[14:17]
	v_mfma_f32_16x16x32_bf16 v[14:17], v[142:145], v[230:233], v[14:17]
	v_mfma_f32_16x16x32_bf16 v[10:13], v[146:149], v[226:229], v[10:13]
	v_mfma_f32_16x16x32_bf16 v[10:13], v[150:153], v[230:233], v[10:13]
	s_add_i32 s84, s84, 2
	s_add_u32 s6, s6, 0x100
	s_addc_u32 s7, s7, 0
	s_add_u32 s49, s49, 0x100
	s_addc_u32 s51, s51, 0
	v_mfma_f32_16x16x32_bf16 v[54:57], v[154:157], v[190:193], v[54:57]
	v_mfma_f32_16x16x32_bf16 v[54:57], v[158:161], v[194:197], v[54:57]
	v_mfma_f32_16x16x32_bf16 v[50:53], v[182:185], v[190:193], v[50:53]
	v_mfma_f32_16x16x32_bf16 v[50:53], v[186:189], v[194:197], v[50:53]
	v_mfma_f32_16x16x32_bf16 v[38:41], v[154:157], v[198:201], v[38:41]
	v_mfma_f32_16x16x32_bf16 v[38:41], v[158:161], v[214:217], v[38:41]
	v_mfma_f32_16x16x32_bf16 v[34:37], v[182:185], v[198:201], v[34:37]
	v_mfma_f32_16x16x32_bf16 v[34:37], v[186:189], v[214:217], v[34:37]
	v_mfma_f32_16x16x32_bf16 v[22:25], v[154:157], v[218:221], v[22:25]
	v_mfma_f32_16x16x32_bf16 v[22:25], v[158:161], v[222:225], v[22:25]
	v_mfma_f32_16x16x32_bf16 v[18:21], v[182:185], v[218:221], v[18:21]
	v_mfma_f32_16x16x32_bf16 v[18:21], v[186:189], v[222:225], v[18:21]
	v_mfma_f32_16x16x32_bf16 v[6:9], v[154:157], v[226:229], v[6:9]
	v_mfma_f32_16x16x32_bf16 v[6:9], v[158:161], v[230:233], v[6:9]
	v_mfma_f32_16x16x32_bf16 v[2:5], v[182:185], v[226:229], v[2:5]
	v_mfma_f32_16x16x32_bf16 v[2:5], v[186:189], v[230:233], v[2:5]
	s_barrier
	s_cmp_gt_u32 s84, 5
	s_cbranch_scc0 .LBB0_604
	s_setprio 0
	s_and_b64 vcc, exec, s[52:53]
	s_cbranch_vccz .LBB0_607
	s_barrier

.LBB0_777:
	s_ashr_i32 s61, s60, 31
	s_lshl_b64 s[20:21], s[60:61], 19
	s_add_u32 s62, s94, s20
	s_addc_u32 s63, s95, s21
	s_and_b64 s[20:21], s[56:57], exec
	s_cselect_b32 s61, s63, s77
	s_cselect_b32 s85, s62, s76
	s_ashr_i32 s59, s58, 31
	s_lshl_b64 s[20:21], s[58:59], 19
	s_add_u32 s68, s15, s20
	s_addc_u32 s69, s42, s21
	s_and_b64 s[20:21], s[56:57], exec
	s_cselect_b32 s59, s69, s79
	s_cselect_b32 s86, s68, s78
	s_add_u32 s76, s76, 0x40080
	s_addc_u32 s77, s77, 0
	s_add_u32 s87, s78, 0x100
	v_mov_b32_e32 v2, 0
	s_addc_u32 vcc_lo, s79, 0
	s_mov_b32 vcc_hi, -2
	s_waitcnt lgkmcnt(0)
	v_add_u32_e32 v243, 0x10000, v193
	ds_read_b128 v[130:133], v243
	ds_read_b128 v[134:137], v243 offset:1024
	ds_read_b128 v[138:141], v243 offset:2048
	ds_read_b128 v[142:145], v243 offset:3072
	ds_read_b128 v[146:149], v243 offset:16384
	ds_read_b128 v[150:153], v243 offset:17408
	ds_read_b128 v[154:157], v243 offset:18432
	ds_read_b128 v[158:161], v243 offset:19456
	ds_read_b128 v[184:187], v196
	ds_read_b128 v[188:191], v196 offset:1024
	ds_read_b128 v[198:201], v196 offset:2048
	ds_read_b128 v[214:217], v196 offset:3072
	ds_read_b128 v[218:221], v196 offset:4096
	ds_read_b128 v[222:225], v196 offset:5120
	ds_read_b128 v[226:229], v196 offset:6144
	ds_read_b128 v[230:233], v196 offset:7168
	s_cmp_eq_u64 s[50:51], 0
	s_cbranch_scc0 .Lpr_778
	s_setprio 1

.Lmid1_778:
	s_add_u32 s20, s76, 0xfffc0080
	s_addc_u32 s21, s77, -1
	s_cmp_eq_u32 vcc_hi, 12
	s_cselect_b32 s79, s61, s21
	s_cselect_b32 s78, s85, s20
	s_cselect_b32 s21, s59, vcc_lo
	s_cselect_b32 s20, s86, s87
	s_add_i32 m0, s43, 0xc000
	v_lshl_add_u64 v[202:203], s[76:77], 0, v[182:183]
	global_load_lds_dwordx4 v[202:203], off
	v_lshl_add_u64 v[202:203], v[202:203], 0, s[72:73]
	s_add_i32 m0, s43, 0xe000
	s_nop 0
	global_load_lds_dwordx4 v[202:203], off
	s_waitcnt vmcnt(8) lgkmcnt(0)
	s_barrier
	v_mfma_f32_16x16x32_bf16 v[126:129], v[130:133], v[184:187], 0
	v_mfma_f32_16x16x32_bf16 v[126:129], v[134:137], v[188:191], v[126:129]
	v_mfma_f32_16x16x32_bf16 v[122:125], v[138:141], v[184:187], 0
	v_mfma_f32_16x16x32_bf16 v[122:125], v[142:145], v[188:191], v[122:125]
	v_mfma_f32_16x16x32_bf16 v[110:113], v[130:133], v[198:201], 0
	v_mfma_f32_16x16x32_bf16 v[110:113], v[134:137], v[214:217], v[110:113]
	v_mfma_f32_16x16x32_bf16 v[106:109], v[138:141], v[198:201], 0
	v_mfma_f32_16x16x32_bf16 v[106:109], v[142:145], v[214:217], v[106:109]
	v_mfma_f32_16x16x32_bf16 v[94:97], v[130:133], v[218:221], 0
	v_mfma_f32_16x16x32_bf16 v[94:97], v[134:137], v[222:225], v[94:97]
	v_mfma_f32_16x16x32_bf16 v[90:93], v[138:141], v[218:221], 0
	v_mfma_f32_16x16x32_bf16 v[90:93], v[142:145], v[222:225], v[90:93]
	v_mfma_f32_16x16x32_bf16 v[78:81], v[130:133], v[226:229], 0
	v_mfma_f32_16x16x32_bf16 v[78:81], v[134:137], v[230:233], v[78:81]
	v_mfma_f32_16x16x32_bf16 v[74:77], v[138:141], v[226:229], 0
	v_mfma_f32_16x16x32_bf16 v[74:77], v[142:145], v[230:233], v[74:77]
	v_mfma_f32_16x16x32_bf16 v[118:121], v[146:149], v[184:187], 0
	v_mfma_f32_16x16x32_bf16 v[118:121], v[150:153], v[188:191], v[118:121]
	v_mfma_f32_16x16x32_bf16 v[114:117], v[154:157], v[184:187], 0
	v_mfma_f32_16x16x32_bf16 v[114:117], v[158:161], v[188:191], v[114:117]
	v_mfma_f32_16x16x32_bf16 v[102:105], v[146:149], v[198:201], 0
	v_mfma_f32_16x16x32_bf16 v[102:105], v[150:153], v[214:217], v[102:105]
	v_mfma_f32_16x16x32_bf16 v[98:101], v[154:157], v[198:201], 0
	v_mfma_f32_16x16x32_bf16 v[98:101], v[158:161], v[214:217], v[98:101]
	v_mfma_f32_16x16x32_bf16 v[86:89], v[146:149], v[218:221], 0
	v_mfma_f32_16x16x32_bf16 v[86:89], v[150:153], v[222:225], v[86:89]
	v_mfma_f32_16x16x32_bf16 v[82:85], v[154:157], v[218:221], 0
	v_mfma_f32_16x16x32_bf16 v[82:85], v[158:161], v[222:225], v[82:85]
	v_mfma_f32_16x16x32_bf16 v[70:73], v[146:149], v[226:229], 0
	v_mfma_f32_16x16x32_bf16 v[70:73], v[150:153], v[230:233], v[70:73]
	v_mfma_f32_16x16x32_bf16 v[66:69], v[154:157], v[226:229], 0
	v_mfma_f32_16x16x32_bf16 v[66:69], v[158:161], v[230:233], v[66:69]
	s_barrier
	ds_read_b128 v[184:187], v196 offset:16384
	ds_read_b128 v[188:191], v196 offset:17408
	ds_read_b128 v[198:201], v196 offset:18432
	ds_read_b128 v[214:217], v196 offset:19456
	ds_read_b128 v[218:221], v196 offset:20480
	ds_read_b128 v[222:225], v196 offset:21504
	ds_read_b128 v[226:229], v196 offset:22528
	ds_read_b128 v[230:233], v196 offset:23552
	v_lshl_add_u64 v[202:203], s[20:21], 0, v[0:1]
	s_add_i32 s20, s14, 0x10000
	s_mov_b32 m0, s20
	s_nop 0
	s_nop 0
	global_load_lds_dwordx4 v[202:203], off
	v_lshl_add_u64 v[234:235], v[202:203], 0, s[72:73]
	s_add_i32 m0, s20, 0x2000
	s_add_i32 s20, s14, 0x14000
	global_load_lds_dwordx4 v[234:235], off
	v_lshl_add_u64 v[234:235], v[202:203], 0, s[28:29]
	s_mov_b32 m0, s20
	s_nop 0
	global_load_lds_dwordx4 v[234:235], off
	v_lshl_add_u64 v[234:235], v[202:203], 0, s[82:83]
	s_add_i32 m0, s20, 0x2000
	s_nop 0
	global_load_lds_dwordx4 v[234:235], off
	v_lshl_add_u64 v[234:235], s[78:79], 0, v[162:163]
	s_mov_b32 m0, s43
	v_lshl_add_u64 v[236:237], v[234:235], 0, s[72:73]
	global_load_lds_dwordx4 v[234:235], off
	s_mov_b32 m0, s46
	s_nop 0
	global_load_lds_dwordx4 v[236:237], off
	s_waitcnt vmcnt(8) lgkmcnt(0)
	s_barrier
	v_mfma_f32_16x16x32_bf16 v[62:65], v[130:133], v[184:187], 0
	v_mfma_f32_16x16x32_bf16 v[62:65], v[134:137], v[188:191], v[62:65]
	v_mfma_f32_16x16x32_bf16 v[58:61], v[138:141], v[184:187], 0
	v_mfma_f32_16x16x32_bf16 v[58:61], v[142:145], v[188:191], v[58:61]
	v_mfma_f32_16x16x32_bf16 v[46:49], v[130:133], v[198:201], 0
	v_mfma_f32_16x16x32_bf16 v[46:49], v[134:137], v[214:217], v[46:49]
	v_mfma_f32_16x16x32_bf16 v[42:45], v[138:141], v[198:201], 0
	v_mfma_f32_16x16x32_bf16 v[42:45], v[142:145], v[214:217], v[42:45]
	v_mfma_f32_16x16x32_bf16 v[30:33], v[130:133], v[218:221], 0
	v_mfma_f32_16x16x32_bf16 v[30:33], v[134:137], v[222:225], v[30:33]
	v_mfma_f32_16x16x32_bf16 v[26:29], v[138:141], v[218:221], 0
	v_mfma_f32_16x16x32_bf16 v[26:29], v[142:145], v[222:225], v[26:29]
	v_mfma_f32_16x16x32_bf16 v[14:17], v[130:133], v[226:229], 0
	v_mfma_f32_16x16x32_bf16 v[14:17], v[134:137], v[230:233], v[14:17]
	v_mfma_f32_16x16x32_bf16 v[10:13], v[138:141], v[226:229], 0
	v_mfma_f32_16x16x32_bf16 v[10:13], v[142:145], v[230:233], v[10:13]
	v_mfma_f32_16x16x32_bf16 v[54:57], v[146:149], v[184:187], 0
	v_mfma_f32_16x16x32_bf16 v[54:57], v[150:153], v[188:191], v[54:57]
	v_mfma_f32_16x16x32_bf16 v[50:53], v[154:157], v[184:187], 0
	v_mfma_f32_16x16x32_bf16 v[50:53], v[158:161], v[188:191], v[50:53]
	v_mfma_f32_16x16x32_bf16 v[38:41], v[146:149], v[198:201], 0
	v_mfma_f32_16x16x32_bf16 v[38:41], v[150:153], v[214:217], v[38:41]
	v_mfma_f32_16x16x32_bf16 v[34:37], v[154:157], v[198:201], 0
	v_mfma_f32_16x16x32_bf16 v[34:37], v[158:161], v[214:217], v[34:37]
	v_mfma_f32_16x16x32_bf16 v[22:25], v[146:149], v[218:221], 0
	v_mfma_f32_16x16x32_bf16 v[22:25], v[150:153], v[222:225], v[22:25]
	v_mfma_f32_16x16x32_bf16 v[18:21], v[154:157], v[218:221], 0
	v_mfma_f32_16x16x32_bf16 v[18:21], v[158:161], v[222:225], v[18:21]
	v_mfma_f32_16x16x32_bf16 v[6:9], v[146:149], v[226:229], 0
	v_mfma_f32_16x16x32_bf16 v[6:9], v[150:153], v[230:233], v[6:9]
	v_mfma_f32_16x16x32_bf16 v[2:5], v[154:157], v[226:229], 0
	v_mfma_f32_16x16x32_bf16 v[2:5], v[158:161], v[230:233], v[2:5]
	s_barrier
	ds_read_b128 v[130:133], v243 offset:32768
	ds_read_b128 v[134:137], v243 offset:33792
	ds_read_b128 v[138:141], v243 offset:34816
	ds_read_b128 v[142:145], v243 offset:35840
	ds_read_b128 v[146:149], v243 offset:49152
	ds_read_b128 v[150:153], v243 offset:50176
	ds_read_b128 v[154:157], v243 offset:51200
	ds_read_b128 v[158:161], v243 offset:52224
	ds_read_b128 v[184:187], v196 offset:32768
	ds_read_b128 v[188:191], v196 offset:33792
	ds_read_b128 v[198:201], v196 offset:34816
	ds_read_b128 v[214:217], v196 offset:35840
	ds_read_b128 v[218:221], v196 offset:36864
	ds_read_b128 v[222:225], v196 offset:37888
	ds_read_b128 v[226:229], v196 offset:38912
	ds_read_b128 v[230:233], v196 offset:39936
	s_mov_b32 m0, s47
	v_lshl_add_u64 v[236:237], v[234:235], 0, s[28:29]
	global_load_lds_dwordx4 v[236:237], off
	v_lshl_add_u64 v[236:237], v[234:235], 0, s[82:83]
	s_mov_b32 m0, s88
	s_nop 0
	global_load_lds_dwordx4 v[236:237], off
	s_waitcnt vmcnt(8) lgkmcnt(0)
	s_barrier
	v_mfma_f32_16x16x32_bf16 v[126:129], v[130:133], v[184:187], v[126:129]
	v_mfma_f32_16x16x32_bf16 v[126:129], v[134:137], v[188:191], v[126:129]
	v_mfma_f32_16x16x32_bf16 v[122:125], v[138:141], v[184:187], v[122:125]
	v_mfma_f32_16x16x32_bf16 v[122:125], v[142:145], v[188:191], v[122:125]
	v_mfma_f32_16x16x32_bf16 v[110:113], v[130:133], v[198:201], v[110:113]
	v_mfma_f32_16x16x32_bf16 v[110:113], v[134:137], v[214:217], v[110:113]
	v_mfma_f32_16x16x32_bf16 v[106:109], v[138:141], v[198:201], v[106:109]
	v_mfma_f32_16x16x32_bf16 v[106:109], v[142:145], v[214:217], v[106:109]
	v_mfma_f32_16x16x32_bf16 v[94:97], v[130:133], v[218:221], v[94:97]
	v_mfma_f32_16x16x32_bf16 v[94:97], v[134:137], v[222:225], v[94:97]
	v_mfma_f32_16x16x32_bf16 v[90:93], v[138:141], v[218:221], v[90:93]
	v_mfma_f32_16x16x32_bf16 v[90:93], v[142:145], v[222:225], v[90:93]
	v_mfma_f32_16x16x32_bf16 v[78:81], v[130:133], v[226:229], v[78:81]
	v_mfma_f32_16x16x32_bf16 v[78:81], v[134:137], v[230:233], v[78:81]
	v_mfma_f32_16x16x32_bf16 v[74:77], v[138:141], v[226:229], v[74:77]
	v_mfma_f32_16x16x32_bf16 v[74:77], v[142:145], v[230:233], v[74:77]
	v_mfma_f32_16x16x32_bf16 v[118:121], v[146:149], v[184:187], v[118:121]
	v_mfma_f32_16x16x32_bf16 v[118:121], v[150:153], v[188:191], v[118:121]
	v_mfma_f32_16x16x32_bf16 v[114:117], v[154:157], v[184:187], v[114:117]
	v_mfma_f32_16x16x32_bf16 v[114:117], v[158:161], v[188:191], v[114:117]
	v_mfma_f32_16x16x32_bf16 v[102:105], v[146:149], v[198:201], v[102:105]
	v_mfma_f32_16x16x32_bf16 v[102:105], v[150:153], v[214:217], v[102:105]
	v_mfma_f32_16x16x32_bf16 v[98:101], v[154:157], v[198:201], v[98:101]
	v_mfma_f32_16x16x32_bf16 v[98:101], v[158:161], v[214:217], v[98:101]
	v_mfma_f32_16x16x32_bf16 v[86:89], v[146:149], v[218:221], v[86:89]
	v_mfma_f32_16x16x32_bf16 v[86:89], v[150:153], v[222:225], v[86:89]
	v_mfma_f32_16x16x32_bf16 v[82:85], v[154:157], v[218:221], v[82:85]
	v_mfma_f32_16x16x32_bf16 v[82:85], v[158:161], v[222:225], v[82:85]
	v_mfma_f32_16x16x32_bf16 v[70:73], v[146:149], v[226:229], v[70:73]
	v_mfma_f32_16x16x32_bf16 v[70:73], v[150:153], v[230:233], v[70:73]
	v_mfma_f32_16x16x32_bf16 v[66:69], v[154:157], v[226:229], v[66:69]
	v_mfma_f32_16x16x32_bf16 v[66:69], v[158:161], v[230:233], v[66:69]
	s_barrier
	ds_read_b128 v[184:187], v196 offset:49152
	ds_read_b128 v[188:191], v196 offset:50176
	ds_read_b128 v[198:201], v196 offset:51200
	ds_read_b128 v[214:217], v196 offset:52224
	ds_read_b128 v[218:221], v196 offset:53248
	ds_read_b128 v[222:225], v196 offset:54272
	ds_read_b128 v[226:229], v196 offset:55296
	ds_read_b128 v[230:233], v196 offset:56320
	s_add_i32 s20, s14, 0x18000
	s_mov_b32 m0, s20
	v_lshl_add_u64 v[236:237], v[202:203], 0, s[34:35]
	global_load_lds_dwordx4 v[236:237], off
	v_lshl_add_u64 v[236:237], v[202:203], 0, s[38:39]
	s_add_i32 m0, s20, 0x2000
	s_add_i32 s20, s14, 0x1c000
	global_load_lds_dwordx4 v[236:237], off
	v_lshl_add_u64 v[236:237], v[202:203], 0, s[44:45]
	s_mov_b32 m0, s20
	v_lshl_add_u64 v[202:203], v[202:203], 0, s[10:11]
	global_load_lds_dwordx4 v[236:237], off
	s_add_i32 m0, s20, 0x2000
	s_nop 0
	global_load_lds_dwordx4 v[202:203], off
	v_lshl_add_u64 v[202:203], v[234:235], 0, s[34:35]
	s_mov_b32 m0, s89
	s_nop 0
	global_load_lds_dwordx4 v[202:203], off
	v_lshl_add_u64 v[202:203], v[234:235], 0, s[38:39]
	s_mov_b32 m0, s90
	s_nop 0
	global_load_lds_dwordx4 v[202:203], off
	s_waitcnt vmcnt(8) lgkmcnt(0)
	s_barrier
	v_mfma_f32_16x16x32_bf16 v[62:65], v[130:133], v[184:187], v[62:65]
	v_mfma_f32_16x16x32_bf16 v[62:65], v[134:137], v[188:191], v[62:65]
	v_mfma_f32_16x16x32_bf16 v[58:61], v[138:141], v[184:187], v[58:61]
	v_mfma_f32_16x16x32_bf16 v[58:61], v[142:145], v[188:191], v[58:61]
	v_mfma_f32_16x16x32_bf16 v[46:49], v[130:133], v[198:201], v[46:49]
	v_mfma_f32_16x16x32_bf16 v[46:49], v[134:137], v[214:217], v[46:49]
	v_mfma_f32_16x16x32_bf16 v[42:45], v[138:141], v[198:201], v[42:45]
	v_mfma_f32_16x16x32_bf16 v[42:45], v[142:145], v[214:217], v[42:45]
	v_mfma_f32_16x16x32_bf16 v[30:33], v[130:133], v[218:221], v[30:33]
	v_mfma_f32_16x16x32_bf16 v[30:33], v[134:137], v[222:225], v[30:33]
	v_mfma_f32_16x16x32_bf16 v[26:29], v[138:141], v[218:221], v[26:29]
	v_mfma_f32_16x16x32_bf16 v[26:29], v[142:145], v[222:225], v[26:29]
	v_mfma_f32_16x16x32_bf16 v[14:17], v[130:133], v[226:229], v[14:17]
	v_mfma_f32_16x16x32_bf16 v[14:17], v[134:137], v[230:233], v[14:17]
	v_mfma_f32_16x16x32_bf16 v[10:13], v[138:141], v[226:229], v[10:13]
	v_mfma_f32_16x16x32_bf16 v[10:13], v[142:145], v[230:233], v[10:13]
	s_add_i32 vcc_hi, vcc_hi, 2
	s_add_u32 s76, s76, 0x100
	s_addc_u32 s77, s77, 0
	s_add_u32 s87, s87, 0x100
	s_addc_u32 vcc_lo, vcc_lo, 0
	v_mfma_f32_16x16x32_bf16 v[54:57], v[146:149], v[184:187], v[54:57]
	v_mfma_f32_16x16x32_bf16 v[54:57], v[150:153], v[188:191], v[54:57]
	v_mfma_f32_16x16x32_bf16 v[50:53], v[154:157], v[184:187], v[50:53]
	v_mfma_f32_16x16x32_bf16 v[50:53], v[158:161], v[188:191], v[50:53]
	v_mfma_f32_16x16x32_bf16 v[38:41], v[146:149], v[198:201], v[38:41]
	v_mfma_f32_16x16x32_bf16 v[38:41], v[150:153], v[214:217], v[38:41]
	v_mfma_f32_16x16x32_bf16 v[34:37], v[154:157], v[198:201], v[34:37]
	v_mfma_f32_16x16x32_bf16 v[34:37], v[158:161], v[214:217], v[34:37]
	v_mfma_f32_16x16x32_bf16 v[22:25], v[146:149], v[218:221], v[22:25]
	v_mfma_f32_16x16x32_bf16 v[22:25], v[150:153], v[222:225], v[22:25]
	v_mfma_f32_16x16x32_bf16 v[18:21], v[154:157], v[218:221], v[18:21]
	v_mfma_f32_16x16x32_bf16 v[18:21], v[158:161], v[222:225], v[18:21]
	v_mfma_f32_16x16x32_bf16 v[6:9], v[146:149], v[226:229], v[6:9]
	v_mfma_f32_16x16x32_bf16 v[6:9], v[150:153], v[230:233], v[6:9]
	v_mfma_f32_16x16x32_bf16 v[2:5], v[154:157], v[226:229], v[2:5]
	v_mfma_f32_16x16x32_bf16 v[2:5], v[158:161], v[230:233], v[2:5]
	s_barrier
	s_branch .LBB0_778
	.p2alignl 6, 3212836864
.LBB0_778:
	ds_read_b128 v[130:133], v243
	ds_read_b128 v[134:137], v243 offset:1024
	ds_read_b128 v[138:141], v243 offset:2048
	ds_read_b128 v[142:145], v243 offset:3072
	ds_read_b128 v[146:149], v243 offset:16384
	ds_read_b128 v[150:153], v243 offset:17408
	ds_read_b128 v[154:157], v243 offset:18432
	ds_read_b128 v[158:161], v243 offset:19456
	ds_read_b128 v[184:187], v196
	ds_read_b128 v[188:191], v196 offset:1024
	ds_read_b128 v[198:201], v196 offset:2048
	ds_read_b128 v[214:217], v196 offset:3072
	ds_read_b128 v[218:221], v196 offset:4096
	ds_read_b128 v[222:225], v196 offset:5120
	ds_read_b128 v[226:229], v196 offset:6144
	ds_read_b128 v[230:233], v196 offset:7168
	s_add_u32 s20, s76, 0xfffc0080
	s_addc_u32 s21, s77, -1
	s_cmp_eq_u32 vcc_hi, 12
	s_cselect_b32 s79, s61, s21
	s_cselect_b32 s78, s85, s20
	s_cselect_b32 s21, s59, vcc_lo
	s_cselect_b32 s20, s86, s87
	s_add_i32 m0, s43, 0xc000
	v_lshl_add_u64 v[202:203], s[76:77], 0, v[182:183]
	global_load_lds_dwordx4 v[202:203], off
	v_lshl_add_u64 v[202:203], v[202:203], 0, s[72:73]
	s_add_i32 m0, s43, 0xe000
	s_nop 0
	global_load_lds_dwordx4 v[202:203], off
	s_waitcnt vmcnt(8) lgkmcnt(0)
	s_barrier
	v_mfma_f32_16x16x32_bf16 v[126:129], v[130:133], v[184:187], v[126:129]
	v_mfma_f32_16x16x32_bf16 v[126:129], v[134:137], v[188:191], v[126:129]
	v_mfma_f32_16x16x32_bf16 v[122:125], v[138:141], v[184:187], v[122:125]
	v_mfma_f32_16x16x32_bf16 v[122:125], v[142:145], v[188:191], v[122:125]
	v_mfma_f32_16x16x32_bf16 v[110:113], v[130:133], v[198:201], v[110:113]
	v_mfma_f32_16x16x32_bf16 v[110:113], v[134:137], v[214:217], v[110:113]
	v_mfma_f32_16x16x32_bf16 v[106:109], v[138:141], v[198:201], v[106:109]
	v_mfma_f32_16x16x32_bf16 v[106:109], v[142:145], v[214:217], v[106:109]
	v_mfma_f32_16x16x32_bf16 v[94:97], v[130:133], v[218:221], v[94:97]
	v_mfma_f32_16x16x32_bf16 v[94:97], v[134:137], v[222:225], v[94:97]
	v_mfma_f32_16x16x32_bf16 v[90:93], v[138:141], v[218:221], v[90:93]
	v_mfma_f32_16x16x32_bf16 v[90:93], v[142:145], v[222:225], v[90:93]
	v_mfma_f32_16x16x32_bf16 v[78:81], v[130:133], v[226:229], v[78:81]
	v_mfma_f32_16x16x32_bf16 v[78:81], v[134:137], v[230:233], v[78:81]
	v_mfma_f32_16x16x32_bf16 v[74:77], v[138:141], v[226:229], v[74:77]
	v_mfma_f32_16x16x32_bf16 v[74:77], v[142:145], v[230:233], v[74:77]
	v_mfma_f32_16x16x32_bf16 v[118:121], v[146:149], v[184:187], v[118:121]
	v_mfma_f32_16x16x32_bf16 v[118:121], v[150:153], v[188:191], v[118:121]
	v_mfma_f32_16x16x32_bf16 v[114:117], v[154:157], v[184:187], v[114:117]
	v_mfma_f32_16x16x32_bf16 v[114:117], v[158:161], v[188:191], v[114:117]
	v_mfma_f32_16x16x32_bf16 v[102:105], v[146:149], v[198:201], v[102:105]
	v_mfma_f32_16x16x32_bf16 v[102:105], v[150:153], v[214:217], v[102:105]
	v_mfma_f32_16x16x32_bf16 v[98:101], v[154:157], v[198:201], v[98:101]
	v_mfma_f32_16x16x32_bf16 v[98:101], v[158:161], v[214:217], v[98:101]
	v_mfma_f32_16x16x32_bf16 v[86:89], v[146:149], v[218:221], v[86:89]
	v_mfma_f32_16x16x32_bf16 v[86:89], v[150:153], v[222:225], v[86:89]
	v_mfma_f32_16x16x32_bf16 v[82:85], v[154:157], v[218:221], v[82:85]
	v_mfma_f32_16x16x32_bf16 v[82:85], v[158:161], v[222:225], v[82:85]
	v_mfma_f32_16x16x32_bf16 v[70:73], v[146:149], v[226:229], v[70:73]
	v_mfma_f32_16x16x32_bf16 v[70:73], v[150:153], v[230:233], v[70:73]
	v_mfma_f32_16x16x32_bf16 v[66:69], v[154:157], v[226:229], v[66:69]
	v_mfma_f32_16x16x32_bf16 v[66:69], v[158:161], v[230:233], v[66:69]
	s_barrier
	ds_read_b128 v[184:187], v196 offset:16384
	ds_read_b128 v[188:191], v196 offset:17408
	ds_read_b128 v[198:201], v196 offset:18432
	ds_read_b128 v[214:217], v196 offset:19456
	ds_read_b128 v[218:221], v196 offset:20480
	ds_read_b128 v[222:225], v196 offset:21504
	ds_read_b128 v[226:229], v196 offset:22528
	ds_read_b128 v[230:233], v196 offset:23552
	v_lshl_add_u64 v[202:203], s[20:21], 0, v[0:1]
	s_add_i32 s20, s14, 0x10000
	s_mov_b32 m0, s20
	s_nop 0
	s_nop 0
	global_load_lds_dwordx4 v[202:203], off
	v_lshl_add_u64 v[234:235], v[202:203], 0, s[72:73]
	s_add_i32 m0, s20, 0x2000
	s_add_i32 s20, s14, 0x14000
	global_load_lds_dwordx4 v[234:235], off
	v_lshl_add_u64 v[234:235], v[202:203], 0, s[28:29]
	s_mov_b32 m0, s20
	s_nop 0
	global_load_lds_dwordx4 v[234:235], off
	v_lshl_add_u64 v[234:235], v[202:203], 0, s[82:83]
	s_add_i32 m0, s20, 0x2000
	s_nop 0
	global_load_lds_dwordx4 v[234:235], off
	v_lshl_add_u64 v[234:235], s[78:79], 0, v[162:163]
	s_mov_b32 m0, s43
	v_lshl_add_u64 v[236:237], v[234:235], 0, s[72:73]
	global_load_lds_dwordx4 v[234:235], off
	s_mov_b32 m0, s46
	s_nop 0
	global_load_lds_dwordx4 v[236:237], off
	s_waitcnt vmcnt(8) lgkmcnt(0)
	s_barrier
	v_mfma_f32_16x16x32_bf16 v[62:65], v[130:133], v[184:187], v[62:65]
	v_mfma_f32_16x16x32_bf16 v[62:65], v[134:137], v[188:191], v[62:65]
	v_mfma_f32_16x16x32_bf16 v[58:61], v[138:141], v[184:187], v[58:61]
	v_mfma_f32_16x16x32_bf16 v[58:61], v[142:145], v[188:191], v[58:61]
	v_mfma_f32_16x16x32_bf16 v[46:49], v[130:133], v[198:201], v[46:49]
	v_mfma_f32_16x16x32_bf16 v[46:49], v[134:137], v[214:217], v[46:49]
	v_mfma_f32_16x16x32_bf16 v[42:45], v[138:141], v[198:201], v[42:45]
	v_mfma_f32_16x16x32_bf16 v[42:45], v[142:145], v[214:217], v[42:45]
	v_mfma_f32_16x16x32_bf16 v[30:33], v[130:133], v[218:221], v[30:33]
	v_mfma_f32_16x16x32_bf16 v[30:33], v[134:137], v[222:225], v[30:33]
	v_mfma_f32_16x16x32_bf16 v[26:29], v[138:141], v[218:221], v[26:29]
	v_mfma_f32_16x16x32_bf16 v[26:29], v[142:145], v[222:225], v[26:29]
	v_mfma_f32_16x16x32_bf16 v[14:17], v[130:133], v[226:229], v[14:17]
	v_mfma_f32_16x16x32_bf16 v[14:17], v[134:137], v[230:233], v[14:17]
	v_mfma_f32_16x16x32_bf16 v[10:13], v[138:141], v[226:229], v[10:13]
	v_mfma_f32_16x16x32_bf16 v[10:13], v[142:145], v[230:233], v[10:13]
	v_mfma_f32_16x16x32_bf16 v[54:57], v[146:149], v[184:187], v[54:57]
	v_mfma_f32_16x16x32_bf16 v[54:57], v[150:153], v[188:191], v[54:57]
	v_mfma_f32_16x16x32_bf16 v[50:53], v[154:157], v[184:187], v[50:53]
	v_mfma_f32_16x16x32_bf16 v[50:53], v[158:161], v[188:191], v[50:53]
	v_mfma_f32_16x16x32_bf16 v[38:41], v[146:149], v[198:201], v[38:41]
	v_mfma_f32_16x16x32_bf16 v[38:41], v[150:153], v[214:217], v[38:41]
	v_mfma_f32_16x16x32_bf16 v[34:37], v[154:157], v[198:201], v[34:37]
	v_mfma_f32_16x16x32_bf16 v[34:37], v[158:161], v[214:217], v[34:37]
	v_mfma_f32_16x16x32_bf16 v[22:25], v[146:149], v[218:221], v[22:25]
	v_mfma_f32_16x16x32_bf16 v[22:25], v[150:153], v[222:225], v[22:25]
	v_mfma_f32_16x16x32_bf16 v[18:21], v[154:157], v[218:221], v[18:21]
	v_mfma_f32_16x16x32_bf16 v[18:21], v[158:161], v[222:225], v[18:21]
	v_mfma_f32_16x16x32_bf16 v[6:9], v[146:149], v[226:229], v[6:9]
	v_mfma_f32_16x16x32_bf16 v[6:9], v[150:153], v[230:233], v[6:9]
	v_mfma_f32_16x16x32_bf16 v[2:5], v[154:157], v[226:229], v[2:5]
	v_mfma_f32_16x16x32_bf16 v[2:5], v[158:161], v[230:233], v[2:5]
	s_barrier
	ds_read_b128 v[130:133], v243 offset:32768
	ds_read_b128 v[134:137], v243 offset:33792
	ds_read_b128 v[138:141], v243 offset:34816
	ds_read_b128 v[142:145], v243 offset:35840
	ds_read_b128 v[146:149], v243 offset:49152
	ds_read_b128 v[150:153], v243 offset:50176
	ds_read_b128 v[154:157], v243 offset:51200
	ds_read_b128 v[158:161], v243 offset:52224
	ds_read_b128 v[184:187], v196 offset:32768
	ds_read_b128 v[188:191], v196 offset:33792
	ds_read_b128 v[198:201], v196 offset:34816
	ds_read_b128 v[214:217], v196 offset:35840
	ds_read_b128 v[218:221], v196 offset:36864
	ds_read_b128 v[222:225], v196 offset:37888
	ds_read_b128 v[226:229], v196 offset:38912
	ds_read_b128 v[230:233], v196 offset:39936
	s_mov_b32 m0, s47
	v_lshl_add_u64 v[236:237], v[234:235], 0, s[28:29]
	global_load_lds_dwordx4 v[236:237], off
	v_lshl_add_u64 v[236:237], v[234:235], 0, s[82:83]
	s_mov_b32 m0, s88
	s_nop 0
	global_load_lds_dwordx4 v[236:237], off
	s_waitcnt vmcnt(8) lgkmcnt(0)
	s_barrier
	v_mfma_f32_16x16x32_bf16 v[126:129], v[130:133], v[184:187], v[126:129]
	v_mfma_f32_16x16x32_bf16 v[126:129], v[134:137], v[188:191], v[126:129]
	v_mfma_f32_16x16x32_bf16 v[122:125], v[138:141], v[184:187], v[122:125]
	v_mfma_f32_16x16x32_bf16 v[122:125], v[142:145], v[188:191], v[122:125]
	v_mfma_f32_16x16x32_bf16 v[110:113], v[130:133], v[198:201], v[110:113]
	v_mfma_f32_16x16x32_bf16 v[110:113], v[134:137], v[214:217], v[110:113]
	v_mfma_f32_16x16x32_bf16 v[106:109], v[138:141], v[198:201], v[106:109]
	v_mfma_f32_16x16x32_bf16 v[106:109], v[142:145], v[214:217], v[106:109]
	v_mfma_f32_16x16x32_bf16 v[94:97], v[130:133], v[218:221], v[94:97]
	v_mfma_f32_16x16x32_bf16 v[94:97], v[134:137], v[222:225], v[94:97]
	v_mfma_f32_16x16x32_bf16 v[90:93], v[138:141], v[218:221], v[90:93]
	v_mfma_f32_16x16x32_bf16 v[90:93], v[142:145], v[222:225], v[90:93]
	v_mfma_f32_16x16x32_bf16 v[78:81], v[130:133], v[226:229], v[78:81]
	v_mfma_f32_16x16x32_bf16 v[78:81], v[134:137], v[230:233], v[78:81]
	v_mfma_f32_16x16x32_bf16 v[74:77], v[138:141], v[226:229], v[74:77]
	v_mfma_f32_16x16x32_bf16 v[74:77], v[142:145], v[230:233], v[74:77]
	v_mfma_f32_16x16x32_bf16 v[118:121], v[146:149], v[184:187], v[118:121]
	v_mfma_f32_16x16x32_bf16 v[118:121], v[150:153], v[188:191], v[118:121]
	v_mfma_f32_16x16x32_bf16 v[114:117], v[154:157], v[184:187], v[114:117]
	v_mfma_f32_16x16x32_bf16 v[114:117], v[158:161], v[188:191], v[114:117]
	v_mfma_f32_16x16x32_bf16 v[102:105], v[146:149], v[198:201], v[102:105]
	v_mfma_f32_16x16x32_bf16 v[102:105], v[150:153], v[214:217], v[102:105]
	v_mfma_f32_16x16x32_bf16 v[98:101], v[154:157], v[198:201], v[98:101]
	v_mfma_f32_16x16x32_bf16 v[98:101], v[158:161], v[214:217], v[98:101]
	v_mfma_f32_16x16x32_bf16 v[86:89], v[146:149], v[218:221], v[86:89]
	v_mfma_f32_16x16x32_bf16 v[86:89], v[150:153], v[222:225], v[86:89]
	v_mfma_f32_16x16x32_bf16 v[82:85], v[154:157], v[218:221], v[82:85]
	v_mfma_f32_16x16x32_bf16 v[82:85], v[158:161], v[222:225], v[82:85]
	v_mfma_f32_16x16x32_bf16 v[70:73], v[146:149], v[226:229], v[70:73]
	v_mfma_f32_16x16x32_bf16 v[70:73], v[150:153], v[230:233], v[70:73]
	v_mfma_f32_16x16x32_bf16 v[66:69], v[154:157], v[226:229], v[66:69]
	v_mfma_f32_16x16x32_bf16 v[66:69], v[158:161], v[230:233], v[66:69]
	s_barrier
	ds_read_b128 v[184:187], v196 offset:49152
	ds_read_b128 v[188:191], v196 offset:50176
	ds_read_b128 v[198:201], v196 offset:51200
	ds_read_b128 v[214:217], v196 offset:52224
	ds_read_b128 v[218:221], v196 offset:53248
	ds_read_b128 v[222:225], v196 offset:54272
	ds_read_b128 v[226:229], v196 offset:55296
	ds_read_b128 v[230:233], v196 offset:56320
	s_add_i32 s20, s14, 0x18000
	s_mov_b32 m0, s20
	v_lshl_add_u64 v[236:237], v[202:203], 0, s[34:35]
	global_load_lds_dwordx4 v[236:237], off
	v_lshl_add_u64 v[236:237], v[202:203], 0, s[38:39]
	s_add_i32 m0, s20, 0x2000
	s_add_i32 s20, s14, 0x1c000
	global_load_lds_dwordx4 v[236:237], off
	v_lshl_add_u64 v[236:237], v[202:203], 0, s[44:45]
	s_mov_b32 m0, s20
	v_lshl_add_u64 v[202:203], v[202:203], 0, s[10:11]
	global_load_lds_dwordx4 v[236:237], off
	s_add_i32 m0, s20, 0x2000
	s_nop 0
	global_load_lds_dwordx4 v[202:203], off
	v_lshl_add_u64 v[202:203], v[234:235], 0, s[34:35]
	s_mov_b32 m0, s89
	s_nop 0
	global_load_lds_dwordx4 v[202:203], off
	v_lshl_add_u64 v[202:203], v[234:235], 0, s[38:39]
	s_mov_b32 m0, s90
	s_nop 0
	global_load_lds_dwordx4 v[202:203], off
	s_waitcnt vmcnt(8) lgkmcnt(0)
	s_barrier
	v_mfma_f32_16x16x32_bf16 v[62:65], v[130:133], v[184:187], v[62:65]
	v_mfma_f32_16x16x32_bf16 v[62:65], v[134:137], v[188:191], v[62:65]
	v_mfma_f32_16x16x32_bf16 v[58:61], v[138:141], v[184:187], v[58:61]
	v_mfma_f32_16x16x32_bf16 v[58:61], v[142:145], v[188:191], v[58:61]
	v_mfma_f32_16x16x32_bf16 v[46:49], v[130:133], v[198:201], v[46:49]
	v_mfma_f32_16x16x32_bf16 v[46:49], v[134:137], v[214:217], v[46:49]
	v_mfma_f32_16x16x32_bf16 v[42:45], v[138:141], v[198:201], v[42:45]
	v_mfma_f32_16x16x32_bf16 v[42:45], v[142:145], v[214:217], v[42:45]
	v_mfma_f32_16x16x32_bf16 v[30:33], v[130:133], v[218:221], v[30:33]
	v_mfma_f32_16x16x32_bf16 v[30:33], v[134:137], v[222:225], v[30:33]
	v_mfma_f32_16x16x32_bf16 v[26:29], v[138:141], v[218:221], v[26:29]
	v_mfma_f32_16x16x32_bf16 v[26:29], v[142:145], v[222:225], v[26:29]
	v_mfma_f32_16x16x32_bf16 v[14:17], v[130:133], v[226:229], v[14:17]
	v_mfma_f32_16x16x32_bf16 v[14:17], v[134:137], v[230:233], v[14:17]
	v_mfma_f32_16x16x32_bf16 v[10:13], v[138:141], v[226:229], v[10:13]
	v_mfma_f32_16x16x32_bf16 v[10:13], v[142:145], v[230:233], v[10:13]
	s_add_i32 vcc_hi, vcc_hi, 2
	s_add_u32 s76, s76, 0x100
	s_addc_u32 s77, s77, 0
	s_add_u32 s87, s87, 0x100
	s_addc_u32 vcc_lo, vcc_lo, 0
	v_mfma_f32_16x16x32_bf16 v[54:57], v[146:149], v[184:187], v[54:57]
	v_mfma_f32_16x16x32_bf16 v[54:57], v[150:153], v[188:191], v[54:57]
	v_mfma_f32_16x16x32_bf16 v[50:53], v[154:157], v[184:187], v[50:53]
	v_mfma_f32_16x16x32_bf16 v[50:53], v[158:161], v[188:191], v[50:53]
	v_mfma_f32_16x16x32_bf16 v[38:41], v[146:149], v[198:201], v[38:41]
	v_mfma_f32_16x16x32_bf16 v[38:41], v[150:153], v[214:217], v[38:41]
	v_mfma_f32_16x16x32_bf16 v[34:37], v[154:157], v[198:201], v[34:37]
	v_mfma_f32_16x16x32_bf16 v[34:37], v[158:161], v[214:217], v[34:37]
	v_mfma_f32_16x16x32_bf16 v[22:25], v[146:149], v[218:221], v[22:25]
	v_mfma_f32_16x16x32_bf16 v[22:25], v[150:153], v[222:225], v[22:25]
	v_mfma_f32_16x16x32_bf16 v[18:21], v[154:157], v[218:221], v[18:21]
	v_mfma_f32_16x16x32_bf16 v[18:21], v[158:161], v[222:225], v[18:21]
	v_mfma_f32_16x16x32_bf16 v[6:9], v[146:149], v[226:229], v[6:9]
	v_mfma_f32_16x16x32_bf16 v[6:9], v[150:153], v[230:233], v[6:9]
	v_mfma_f32_16x16x32_bf16 v[2:5], v[154:157], v[226:229], v[2:5]
	v_mfma_f32_16x16x32_bf16 v[2:5], v[158:161], v[230:233], v[2:5]
	s_barrier
	s_cmp_gt_u32 vcc_hi, 13
	s_cbranch_scc0 .LBB0_778
	s_setprio 0
	s_and_b64 vcc, exec, s[50:51]
	s_cbranch_vccz .LBB0_781
	s_barrier

.LBB0_849:
	s_ashr_i32 s79, s78, 31
	s_lshl_b64 s[20:21], s[78:79], 19
	s_add_u32 s88, s4, s20
	s_addc_u32 s89, s5, s21
	s_and_b64 s[20:21], s[54:55], exec
	s_cselect_b32 s76, s89, s57
	s_cselect_b32 s77, s88, s56
	s_ashr_i32 s69, s68, 31
	s_lshl_b64 s[20:21], s[68:69], 19
	v_readlane_b32 s12, v247, 42
	s_add_u32 s94, s12, s20
	v_readlane_b32 s12, v245, 61
	s_addc_u32 s95, s12, s21
	s_and_b64 s[20:21], s[54:55], exec
	s_cselect_b32 s69, s95, s59
	s_cselect_b32 s79, s94, s58
	s_add_u32 s56, s56, 0x40080
	s_addc_u32 s57, s57, 0
	s_add_u32 s86, s58, 0x100
	v_mov_b32_e32 v2, 0
	s_addc_u32 s87, s59, 0
	s_mov_b32 s91, -2
	v_add_u32_e32 v243, 0x10000, v145
	ds_read_b128 v[138:141], v243
	ds_read_b128 v[146:149], v243 offset:1024
	ds_read_b128 v[150:153], v243 offset:2048
	ds_read_b128 v[158:161], v243 offset:3072
	ds_read_b128 v[182:185], v243 offset:16384
	ds_read_b128 v[186:189], v243 offset:17408
	ds_read_b128 v[190:193], v243 offset:18432
	ds_read_b128 v[194:197], v243 offset:19456
	ds_read_b128 v[198:201], v157
	ds_read_b128 v[214:217], v157 offset:1024
	ds_read_b128 v[218:221], v157 offset:2048
	ds_read_b128 v[222:225], v157 offset:3072
	ds_read_b128 v[226:229], v157 offset:4096
	ds_read_b128 v[230:233], v157 offset:5120
	ds_read_b128 v[234:237], v157 offset:6144
	ds_read_b128 v[238:241], v157 offset:7168
	s_cmp_eq_u64 s[62:63], 0
	s_cbranch_scc0 .Lpr_850
	s_setprio 1

.Lmid1_850:
	s_add_u32 s20, s56, 0xfffc0080
	s_addc_u32 s21, s57, -1
	s_cmp_eq_u32 s91, 12
	s_cselect_b32 s59, s76, s21
	s_cselect_b32 s58, s77, s20
	s_cselect_b32 s21, s69, s87
	s_cselect_b32 s20, s79, s86
	s_add_i32 m0, s15, 0xc000
	v_lshl_add_u64 v[142:143], s[56:57], 0, v[136:137]
	global_load_lds_dwordx4 v[142:143], off
	v_lshl_add_u64 v[142:143], v[142:143], 0, s[72:73]
	s_add_i32 m0, s15, 0xe000
	s_nop 0
	global_load_lds_dwordx4 v[142:143], off
	s_waitcnt vmcnt(8) lgkmcnt(0)
	s_barrier
	v_mfma_f32_16x16x32_bf16 v[126:129], v[138:141], v[198:201], 0
	v_mfma_f32_16x16x32_bf16 v[126:129], v[146:149], v[214:217], v[126:129]
	v_mfma_f32_16x16x32_bf16 v[122:125], v[150:153], v[198:201], 0
	v_mfma_f32_16x16x32_bf16 v[122:125], v[158:161], v[214:217], v[122:125]
	v_mfma_f32_16x16x32_bf16 v[110:113], v[138:141], v[218:221], 0
	v_mfma_f32_16x16x32_bf16 v[110:113], v[146:149], v[222:225], v[110:113]
	v_mfma_f32_16x16x32_bf16 v[106:109], v[150:153], v[218:221], 0
	v_mfma_f32_16x16x32_bf16 v[106:109], v[158:161], v[222:225], v[106:109]
	v_mfma_f32_16x16x32_bf16 v[94:97], v[138:141], v[226:229], 0
	v_mfma_f32_16x16x32_bf16 v[94:97], v[146:149], v[230:233], v[94:97]
	v_mfma_f32_16x16x32_bf16 v[90:93], v[150:153], v[226:229], 0
	v_mfma_f32_16x16x32_bf16 v[90:93], v[158:161], v[230:233], v[90:93]
	v_mfma_f32_16x16x32_bf16 v[78:81], v[138:141], v[234:237], 0
	v_mfma_f32_16x16x32_bf16 v[78:81], v[146:149], v[238:241], v[78:81]
	v_mfma_f32_16x16x32_bf16 v[74:77], v[150:153], v[234:237], 0
	v_mfma_f32_16x16x32_bf16 v[74:77], v[158:161], v[238:241], v[74:77]
	v_mfma_f32_16x16x32_bf16 v[118:121], v[182:185], v[198:201], 0
	v_mfma_f32_16x16x32_bf16 v[118:121], v[186:189], v[214:217], v[118:121]
	v_mfma_f32_16x16x32_bf16 v[114:117], v[190:193], v[198:201], 0
	v_mfma_f32_16x16x32_bf16 v[114:117], v[194:197], v[214:217], v[114:117]
	v_mfma_f32_16x16x32_bf16 v[102:105], v[182:185], v[218:221], 0
	v_mfma_f32_16x16x32_bf16 v[102:105], v[186:189], v[222:225], v[102:105]
	v_mfma_f32_16x16x32_bf16 v[98:101], v[190:193], v[218:221], 0
	v_mfma_f32_16x16x32_bf16 v[98:101], v[194:197], v[222:225], v[98:101]
	v_mfma_f32_16x16x32_bf16 v[86:89], v[182:185], v[226:229], 0
	v_mfma_f32_16x16x32_bf16 v[86:89], v[186:189], v[230:233], v[86:89]
	v_mfma_f32_16x16x32_bf16 v[82:85], v[190:193], v[226:229], 0
	v_mfma_f32_16x16x32_bf16 v[82:85], v[194:197], v[230:233], v[82:85]
	v_mfma_f32_16x16x32_bf16 v[70:73], v[182:185], v[234:237], 0
	v_mfma_f32_16x16x32_bf16 v[70:73], v[186:189], v[238:241], v[70:73]
	v_mfma_f32_16x16x32_bf16 v[66:69], v[190:193], v[234:237], 0
	v_mfma_f32_16x16x32_bf16 v[66:69], v[194:197], v[238:241], v[66:69]
	s_barrier
	ds_read_b128 v[198:201], v157 offset:16384
	ds_read_b128 v[214:217], v157 offset:17408
	ds_read_b128 v[218:221], v157 offset:18432
	ds_read_b128 v[222:225], v157 offset:19456
	ds_read_b128 v[226:229], v157 offset:20480
	ds_read_b128 v[230:233], v157 offset:21504
	ds_read_b128 v[234:237], v157 offset:22528
	ds_read_b128 v[238:241], v157 offset:23552
	v_lshl_add_u64 v[142:143], s[20:21], 0, v[130:131]
	s_add_i32 s20, s14, 0x10000
	s_mov_b32 m0, s20
	s_nop 0
	s_nop 0
	global_load_lds_dwordx4 v[142:143], off
	v_lshl_add_u64 v[162:163], v[142:143], 0, s[72:73]
	s_add_i32 m0, s20, 0x2000
	s_add_i32 s20, s14, 0x14000
	global_load_lds_dwordx4 v[162:163], off
	v_lshl_add_u64 v[162:163], v[142:143], 0, s[28:29]
	s_mov_b32 m0, s20
	s_nop 0
	global_load_lds_dwordx4 v[162:163], off
	v_lshl_add_u64 v[162:163], v[142:143], 0, s[82:83]
	s_add_i32 m0, s20, 0x2000
	s_nop 0
	global_load_lds_dwordx4 v[162:163], off
	v_lshl_add_u64 v[162:163], s[58:59], 0, v[132:133]
	s_mov_b32 m0, s15
	v_lshl_add_u64 v[202:203], v[162:163], 0, s[72:73]
	global_load_lds_dwordx4 v[162:163], off
	s_mov_b32 m0, s42
	s_nop 0
	global_load_lds_dwordx4 v[202:203], off
	s_waitcnt vmcnt(8) lgkmcnt(0)
	s_barrier
	v_mfma_f32_16x16x32_bf16 v[62:65], v[138:141], v[198:201], 0
	v_mfma_f32_16x16x32_bf16 v[62:65], v[146:149], v[214:217], v[62:65]
	v_mfma_f32_16x16x32_bf16 v[58:61], v[150:153], v[198:201], 0
	v_mfma_f32_16x16x32_bf16 v[58:61], v[158:161], v[214:217], v[58:61]
	v_mfma_f32_16x16x32_bf16 v[46:49], v[138:141], v[218:221], 0
	v_mfma_f32_16x16x32_bf16 v[46:49], v[146:149], v[222:225], v[46:49]
	v_mfma_f32_16x16x32_bf16 v[42:45], v[150:153], v[218:221], 0
	v_mfma_f32_16x16x32_bf16 v[42:45], v[158:161], v[222:225], v[42:45]
	v_mfma_f32_16x16x32_bf16 v[30:33], v[138:141], v[226:229], 0
	v_mfma_f32_16x16x32_bf16 v[30:33], v[146:149], v[230:233], v[30:33]
	v_mfma_f32_16x16x32_bf16 v[26:29], v[150:153], v[226:229], 0
	v_mfma_f32_16x16x32_bf16 v[26:29], v[158:161], v[230:233], v[26:29]
	v_mfma_f32_16x16x32_bf16 v[14:17], v[138:141], v[234:237], 0
	v_mfma_f32_16x16x32_bf16 v[14:17], v[146:149], v[238:241], v[14:17]
	v_mfma_f32_16x16x32_bf16 v[10:13], v[150:153], v[234:237], 0
	v_mfma_f32_16x16x32_bf16 v[10:13], v[158:161], v[238:241], v[10:13]
	v_mfma_f32_16x16x32_bf16 v[54:57], v[182:185], v[198:201], 0
	v_mfma_f32_16x16x32_bf16 v[54:57], v[186:189], v[214:217], v[54:57]
	v_mfma_f32_16x16x32_bf16 v[50:53], v[190:193], v[198:201], 0
	v_mfma_f32_16x16x32_bf16 v[50:53], v[194:197], v[214:217], v[50:53]
	v_mfma_f32_16x16x32_bf16 v[38:41], v[182:185], v[218:221], 0
	v_mfma_f32_16x16x32_bf16 v[38:41], v[186:189], v[222:225], v[38:41]
	v_mfma_f32_16x16x32_bf16 v[34:37], v[190:193], v[218:221], 0
	v_mfma_f32_16x16x32_bf16 v[34:37], v[194:197], v[222:225], v[34:37]
	v_mfma_f32_16x16x32_bf16 v[22:25], v[182:185], v[226:229], 0
	v_mfma_f32_16x16x32_bf16 v[22:25], v[186:189], v[230:233], v[22:25]
	v_mfma_f32_16x16x32_bf16 v[18:21], v[190:193], v[226:229], 0
	v_mfma_f32_16x16x32_bf16 v[18:21], v[194:197], v[230:233], v[18:21]
	v_mfma_f32_16x16x32_bf16 v[6:9], v[182:185], v[234:237], 0
	v_mfma_f32_16x16x32_bf16 v[6:9], v[186:189], v[238:241], v[6:9]
	v_mfma_f32_16x16x32_bf16 v[2:5], v[190:193], v[234:237], 0
	v_mfma_f32_16x16x32_bf16 v[2:5], v[194:197], v[238:241], v[2:5]
	s_barrier
	ds_read_b128 v[138:141], v243 offset:32768
	ds_read_b128 v[146:149], v243 offset:33792
	ds_read_b128 v[150:153], v243 offset:34816
	ds_read_b128 v[158:161], v243 offset:35840
	ds_read_b128 v[182:185], v243 offset:49152
	ds_read_b128 v[186:189], v243 offset:50176
	ds_read_b128 v[190:193], v243 offset:51200
	ds_read_b128 v[194:197], v243 offset:52224
	ds_read_b128 v[198:201], v157 offset:32768
	ds_read_b128 v[214:217], v157 offset:33792
	ds_read_b128 v[218:221], v157 offset:34816
	ds_read_b128 v[222:225], v157 offset:35840
	ds_read_b128 v[226:229], v157 offset:36864
	ds_read_b128 v[230:233], v157 offset:37888
	ds_read_b128 v[234:237], v157 offset:38912
	ds_read_b128 v[238:241], v157 offset:39936
	s_mov_b32 m0, s43
	v_lshl_add_u64 v[202:203], v[162:163], 0, s[28:29]
	global_load_lds_dwordx4 v[202:203], off
	v_lshl_add_u64 v[202:203], v[162:163], 0, s[82:83]
	s_mov_b32 m0, s46
	s_nop 0
	global_load_lds_dwordx4 v[202:203], off
	s_waitcnt vmcnt(8) lgkmcnt(0)
	s_barrier
	v_mfma_f32_16x16x32_bf16 v[126:129], v[138:141], v[198:201], v[126:129]
	v_mfma_f32_16x16x32_bf16 v[126:129], v[146:149], v[214:217], v[126:129]
	v_mfma_f32_16x16x32_bf16 v[122:125], v[150:153], v[198:201], v[122:125]
	v_mfma_f32_16x16x32_bf16 v[122:125], v[158:161], v[214:217], v[122:125]
	v_mfma_f32_16x16x32_bf16 v[110:113], v[138:141], v[218:221], v[110:113]
	v_mfma_f32_16x16x32_bf16 v[110:113], v[146:149], v[222:225], v[110:113]
	v_mfma_f32_16x16x32_bf16 v[106:109], v[150:153], v[218:221], v[106:109]
	v_mfma_f32_16x16x32_bf16 v[106:109], v[158:161], v[222:225], v[106:109]
	v_mfma_f32_16x16x32_bf16 v[94:97], v[138:141], v[226:229], v[94:97]
	v_mfma_f32_16x16x32_bf16 v[94:97], v[146:149], v[230:233], v[94:97]
	v_mfma_f32_16x16x32_bf16 v[90:93], v[150:153], v[226:229], v[90:93]
	v_mfma_f32_16x16x32_bf16 v[90:93], v[158:161], v[230:233], v[90:93]
	v_mfma_f32_16x16x32_bf16 v[78:81], v[138:141], v[234:237], v[78:81]
	v_mfma_f32_16x16x32_bf16 v[78:81], v[146:149], v[238:241], v[78:81]
	v_mfma_f32_16x16x32_bf16 v[74:77], v[150:153], v[234:237], v[74:77]
	v_mfma_f32_16x16x32_bf16 v[74:77], v[158:161], v[238:241], v[74:77]
	v_mfma_f32_16x16x32_bf16 v[118:121], v[182:185], v[198:201], v[118:121]
	v_mfma_f32_16x16x32_bf16 v[118:121], v[186:189], v[214:217], v[118:121]
	v_mfma_f32_16x16x32_bf16 v[114:117], v[190:193], v[198:201], v[114:117]
	v_mfma_f32_16x16x32_bf16 v[114:117], v[194:197], v[214:217], v[114:117]
	v_mfma_f32_16x16x32_bf16 v[102:105], v[182:185], v[218:221], v[102:105]
	v_mfma_f32_16x16x32_bf16 v[102:105], v[186:189], v[222:225], v[102:105]
	v_mfma_f32_16x16x32_bf16 v[98:101], v[190:193], v[218:221], v[98:101]
	v_mfma_f32_16x16x32_bf16 v[98:101], v[194:197], v[222:225], v[98:101]
	v_mfma_f32_16x16x32_bf16 v[86:89], v[182:185], v[226:229], v[86:89]
	v_mfma_f32_16x16x32_bf16 v[86:89], v[186:189], v[230:233], v[86:89]
	v_mfma_f32_16x16x32_bf16 v[82:85], v[190:193], v[226:229], v[82:85]
	v_mfma_f32_16x16x32_bf16 v[82:85], v[194:197], v[230:233], v[82:85]
	v_mfma_f32_16x16x32_bf16 v[70:73], v[182:185], v[234:237], v[70:73]
	v_mfma_f32_16x16x32_bf16 v[70:73], v[186:189], v[238:241], v[70:73]
	v_mfma_f32_16x16x32_bf16 v[66:69], v[190:193], v[234:237], v[66:69]
	v_mfma_f32_16x16x32_bf16 v[66:69], v[194:197], v[238:241], v[66:69]
	s_barrier
	ds_read_b128 v[198:201], v157 offset:49152
	ds_read_b128 v[214:217], v157 offset:50176
	ds_read_b128 v[218:221], v157 offset:51200
	ds_read_b128 v[222:225], v157 offset:52224
	ds_read_b128 v[226:229], v157 offset:53248
	ds_read_b128 v[230:233], v157 offset:54272
	ds_read_b128 v[234:237], v157 offset:55296
	ds_read_b128 v[238:241], v157 offset:56320
	s_add_i32 s20, s14, 0x18000
	s_mov_b32 m0, s20
	v_lshl_add_u64 v[202:203], v[142:143], 0, s[34:35]
	global_load_lds_dwordx4 v[202:203], off
	v_lshl_add_u64 v[202:203], v[142:143], 0, s[38:39]
	s_add_i32 m0, s20, 0x2000
	s_add_i32 s20, s14, 0x1c000
	global_load_lds_dwordx4 v[202:203], off
	v_lshl_add_u64 v[202:203], v[142:143], 0, s[44:45]
	s_mov_b32 m0, s20
	v_lshl_add_u64 v[142:143], v[142:143], 0, s[10:11]
	global_load_lds_dwordx4 v[202:203], off
	s_add_i32 m0, s20, 0x2000
	s_nop 0
	global_load_lds_dwordx4 v[142:143], off
	v_lshl_add_u64 v[142:143], v[162:163], 0, s[34:35]
	s_mov_b32 m0, s47
	s_nop 0
	global_load_lds_dwordx4 v[142:143], off
	v_lshl_add_u64 v[142:143], v[162:163], 0, s[38:39]
	s_mov_b32 m0, s96
	s_nop 0
	global_load_lds_dwordx4 v[142:143], off
	s_waitcnt vmcnt(8) lgkmcnt(0)
	s_barrier
	v_mfma_f32_16x16x32_bf16 v[62:65], v[138:141], v[198:201], v[62:65]
	v_mfma_f32_16x16x32_bf16 v[62:65], v[146:149], v[214:217], v[62:65]
	v_mfma_f32_16x16x32_bf16 v[58:61], v[150:153], v[198:201], v[58:61]
	v_mfma_f32_16x16x32_bf16 v[58:61], v[158:161], v[214:217], v[58:61]
	v_mfma_f32_16x16x32_bf16 v[46:49], v[138:141], v[218:221], v[46:49]
	v_mfma_f32_16x16x32_bf16 v[46:49], v[146:149], v[222:225], v[46:49]
	v_mfma_f32_16x16x32_bf16 v[42:45], v[150:153], v[218:221], v[42:45]
	v_mfma_f32_16x16x32_bf16 v[42:45], v[158:161], v[222:225], v[42:45]
	v_mfma_f32_16x16x32_bf16 v[30:33], v[138:141], v[226:229], v[30:33]
	v_mfma_f32_16x16x32_bf16 v[30:33], v[146:149], v[230:233], v[30:33]
	v_mfma_f32_16x16x32_bf16 v[26:29], v[150:153], v[226:229], v[26:29]
	v_mfma_f32_16x16x32_bf16 v[26:29], v[158:161], v[230:233], v[26:29]
	v_mfma_f32_16x16x32_bf16 v[14:17], v[138:141], v[234:237], v[14:17]
	v_mfma_f32_16x16x32_bf16 v[14:17], v[146:149], v[238:241], v[14:17]
	v_mfma_f32_16x16x32_bf16 v[10:13], v[150:153], v[234:237], v[10:13]
	v_mfma_f32_16x16x32_bf16 v[10:13], v[158:161], v[238:241], v[10:13]
	s_add_i32 s91, s91, 2
	s_add_u32 s56, s56, 0x100
	s_addc_u32 s57, s57, 0
	s_add_u32 s86, s86, 0x100
	s_addc_u32 s87, s87, 0
	v_mfma_f32_16x16x32_bf16 v[54:57], v[182:185], v[198:201], v[54:57]
	v_mfma_f32_16x16x32_bf16 v[54:57], v[186:189], v[214:217], v[54:57]
	v_mfma_f32_16x16x32_bf16 v[50:53], v[190:193], v[198:201], v[50:53]
	v_mfma_f32_16x16x32_bf16 v[50:53], v[194:197], v[214:217], v[50:53]
	v_mfma_f32_16x16x32_bf16 v[38:41], v[182:185], v[218:221], v[38:41]
	v_mfma_f32_16x16x32_bf16 v[38:41], v[186:189], v[222:225], v[38:41]
	v_mfma_f32_16x16x32_bf16 v[34:37], v[190:193], v[218:221], v[34:37]
	v_mfma_f32_16x16x32_bf16 v[34:37], v[194:197], v[222:225], v[34:37]
	v_mfma_f32_16x16x32_bf16 v[22:25], v[182:185], v[226:229], v[22:25]
	v_mfma_f32_16x16x32_bf16 v[22:25], v[186:189], v[230:233], v[22:25]
	v_mfma_f32_16x16x32_bf16 v[18:21], v[190:193], v[226:229], v[18:21]
	v_mfma_f32_16x16x32_bf16 v[18:21], v[194:197], v[230:233], v[18:21]
	v_mfma_f32_16x16x32_bf16 v[6:9], v[182:185], v[234:237], v[6:9]
	v_mfma_f32_16x16x32_bf16 v[6:9], v[186:189], v[238:241], v[6:9]
	v_mfma_f32_16x16x32_bf16 v[2:5], v[190:193], v[234:237], v[2:5]
	v_mfma_f32_16x16x32_bf16 v[2:5], v[194:197], v[238:241], v[2:5]
	s_barrier
	s_branch .LBB0_850
	.p2alignl 6, 3212836864
.LBB0_850:
	ds_read_b128 v[138:141], v243
	ds_read_b128 v[146:149], v243 offset:1024
	ds_read_b128 v[150:153], v243 offset:2048
	ds_read_b128 v[158:161], v243 offset:3072
	ds_read_b128 v[182:185], v243 offset:16384
	ds_read_b128 v[186:189], v243 offset:17408
	ds_read_b128 v[190:193], v243 offset:18432
	ds_read_b128 v[194:197], v243 offset:19456
	ds_read_b128 v[198:201], v157
	ds_read_b128 v[214:217], v157 offset:1024
	ds_read_b128 v[218:221], v157 offset:2048
	ds_read_b128 v[222:225], v157 offset:3072
	ds_read_b128 v[226:229], v157 offset:4096
	ds_read_b128 v[230:233], v157 offset:5120
	ds_read_b128 v[234:237], v157 offset:6144
	ds_read_b128 v[238:241], v157 offset:7168
	s_add_u32 s20, s56, 0xfffc0080
	s_addc_u32 s21, s57, -1
	s_cmp_eq_u32 s91, 12
	s_cselect_b32 s59, s76, s21
	s_cselect_b32 s58, s77, s20
	s_cselect_b32 s21, s69, s87
	s_cselect_b32 s20, s79, s86
	s_add_i32 m0, s15, 0xc000
	v_lshl_add_u64 v[142:143], s[56:57], 0, v[136:137]
	global_load_lds_dwordx4 v[142:143], off
	v_lshl_add_u64 v[142:143], v[142:143], 0, s[72:73]
	s_add_i32 m0, s15, 0xe000
	s_nop 0
	global_load_lds_dwordx4 v[142:143], off
	s_waitcnt vmcnt(8) lgkmcnt(0)
	s_barrier
	v_mfma_f32_16x16x32_bf16 v[126:129], v[138:141], v[198:201], v[126:129]
	v_mfma_f32_16x16x32_bf16 v[126:129], v[146:149], v[214:217], v[126:129]
	v_mfma_f32_16x16x32_bf16 v[122:125], v[150:153], v[198:201], v[122:125]
	v_mfma_f32_16x16x32_bf16 v[122:125], v[158:161], v[214:217], v[122:125]
	v_mfma_f32_16x16x32_bf16 v[110:113], v[138:141], v[218:221], v[110:113]
	v_mfma_f32_16x16x32_bf16 v[110:113], v[146:149], v[222:225], v[110:113]
	v_mfma_f32_16x16x32_bf16 v[106:109], v[150:153], v[218:221], v[106:109]
	v_mfma_f32_16x16x32_bf16 v[106:109], v[158:161], v[222:225], v[106:109]
	v_mfma_f32_16x16x32_bf16 v[94:97], v[138:141], v[226:229], v[94:97]
	v_mfma_f32_16x16x32_bf16 v[94:97], v[146:149], v[230:233], v[94:97]
	v_mfma_f32_16x16x32_bf16 v[90:93], v[150:153], v[226:229], v[90:93]
	v_mfma_f32_16x16x32_bf16 v[90:93], v[158:161], v[230:233], v[90:93]
	v_mfma_f32_16x16x32_bf16 v[78:81], v[138:141], v[234:237], v[78:81]
	v_mfma_f32_16x16x32_bf16 v[78:81], v[146:149], v[238:241], v[78:81]
	v_mfma_f32_16x16x32_bf16 v[74:77], v[150:153], v[234:237], v[74:77]
	v_mfma_f32_16x16x32_bf16 v[74:77], v[158:161], v[238:241], v[74:77]
	v_mfma_f32_16x16x32_bf16 v[118:121], v[182:185], v[198:201], v[118:121]
	v_mfma_f32_16x16x32_bf16 v[118:121], v[186:189], v[214:217], v[118:121]
	v_mfma_f32_16x16x32_bf16 v[114:117], v[190:193], v[198:201], v[114:117]
	v_mfma_f32_16x16x32_bf16 v[114:117], v[194:197], v[214:217], v[114:117]
	v_mfma_f32_16x16x32_bf16 v[102:105], v[182:185], v[218:221], v[102:105]
	v_mfma_f32_16x16x32_bf16 v[102:105], v[186:189], v[222:225], v[102:105]
	v_mfma_f32_16x16x32_bf16 v[98:101], v[190:193], v[218:221], v[98:101]
	v_mfma_f32_16x16x32_bf16 v[98:101], v[194:197], v[222:225], v[98:101]
	v_mfma_f32_16x16x32_bf16 v[86:89], v[182:185], v[226:229], v[86:89]
	v_mfma_f32_16x16x32_bf16 v[86:89], v[186:189], v[230:233], v[86:89]
	v_mfma_f32_16x16x32_bf16 v[82:85], v[190:193], v[226:229], v[82:85]
	v_mfma_f32_16x16x32_bf16 v[82:85], v[194:197], v[230:233], v[82:85]
	v_mfma_f32_16x16x32_bf16 v[70:73], v[182:185], v[234:237], v[70:73]
	v_mfma_f32_16x16x32_bf16 v[70:73], v[186:189], v[238:241], v[70:73]
	v_mfma_f32_16x16x32_bf16 v[66:69], v[190:193], v[234:237], v[66:69]
	v_mfma_f32_16x16x32_bf16 v[66:69], v[194:197], v[238:241], v[66:69]
	s_barrier
	ds_read_b128 v[198:201], v157 offset:16384
	ds_read_b128 v[214:217], v157 offset:17408
	ds_read_b128 v[218:221], v157 offset:18432
	ds_read_b128 v[222:225], v157 offset:19456
	ds_read_b128 v[226:229], v157 offset:20480
	ds_read_b128 v[230:233], v157 offset:21504
	ds_read_b128 v[234:237], v157 offset:22528
	ds_read_b128 v[238:241], v157 offset:23552
	v_lshl_add_u64 v[142:143], s[20:21], 0, v[130:131]
	s_add_i32 s20, s14, 0x10000
	s_mov_b32 m0, s20
	s_nop 0
	s_nop 0
	global_load_lds_dwordx4 v[142:143], off
	v_lshl_add_u64 v[162:163], v[142:143], 0, s[72:73]
	s_add_i32 m0, s20, 0x2000
	s_add_i32 s20, s14, 0x14000
	global_load_lds_dwordx4 v[162:163], off
	v_lshl_add_u64 v[162:163], v[142:143], 0, s[28:29]
	s_mov_b32 m0, s20
	s_nop 0
	global_load_lds_dwordx4 v[162:163], off
	v_lshl_add_u64 v[162:163], v[142:143], 0, s[82:83]
	s_add_i32 m0, s20, 0x2000
	s_nop 0
	global_load_lds_dwordx4 v[162:163], off
	v_lshl_add_u64 v[162:163], s[58:59], 0, v[132:133]
	s_mov_b32 m0, s15
	v_lshl_add_u64 v[202:203], v[162:163], 0, s[72:73]
	global_load_lds_dwordx4 v[162:163], off
	s_mov_b32 m0, s42
	s_nop 0
	global_load_lds_dwordx4 v[202:203], off
	s_waitcnt vmcnt(8) lgkmcnt(0)
	s_barrier
	v_mfma_f32_16x16x32_bf16 v[62:65], v[138:141], v[198:201], v[62:65]
	v_mfma_f32_16x16x32_bf16 v[62:65], v[146:149], v[214:217], v[62:65]
	v_mfma_f32_16x16x32_bf16 v[58:61], v[150:153], v[198:201], v[58:61]
	v_mfma_f32_16x16x32_bf16 v[58:61], v[158:161], v[214:217], v[58:61]
	v_mfma_f32_16x16x32_bf16 v[46:49], v[138:141], v[218:221], v[46:49]
	v_mfma_f32_16x16x32_bf16 v[46:49], v[146:149], v[222:225], v[46:49]
	v_mfma_f32_16x16x32_bf16 v[42:45], v[150:153], v[218:221], v[42:45]
	v_mfma_f32_16x16x32_bf16 v[42:45], v[158:161], v[222:225], v[42:45]
	v_mfma_f32_16x16x32_bf16 v[30:33], v[138:141], v[226:229], v[30:33]
	v_mfma_f32_16x16x32_bf16 v[30:33], v[146:149], v[230:233], v[30:33]
	v_mfma_f32_16x16x32_bf16 v[26:29], v[150:153], v[226:229], v[26:29]
	v_mfma_f32_16x16x32_bf16 v[26:29], v[158:161], v[230:233], v[26:29]
	v_mfma_f32_16x16x32_bf16 v[14:17], v[138:141], v[234:237], v[14:17]
	v_mfma_f32_16x16x32_bf16 v[14:17], v[146:149], v[238:241], v[14:17]
	v_mfma_f32_16x16x32_bf16 v[10:13], v[150:153], v[234:237], v[10:13]
	v_mfma_f32_16x16x32_bf16 v[10:13], v[158:161], v[238:241], v[10:13]
	v_mfma_f32_16x16x32_bf16 v[54:57], v[182:185], v[198:201], v[54:57]
	v_mfma_f32_16x16x32_bf16 v[54:57], v[186:189], v[214:217], v[54:57]
	v_mfma_f32_16x16x32_bf16 v[50:53], v[190:193], v[198:201], v[50:53]
	v_mfma_f32_16x16x32_bf16 v[50:53], v[194:197], v[214:217], v[50:53]
	v_mfma_f32_16x16x32_bf16 v[38:41], v[182:185], v[218:221], v[38:41]
	v_mfma_f32_16x16x32_bf16 v[38:41], v[186:189], v[222:225], v[38:41]
	v_mfma_f32_16x16x32_bf16 v[34:37], v[190:193], v[218:221], v[34:37]
	v_mfma_f32_16x16x32_bf16 v[34:37], v[194:197], v[222:225], v[34:37]
	v_mfma_f32_16x16x32_bf16 v[22:25], v[182:185], v[226:229], v[22:25]
	v_mfma_f32_16x16x32_bf16 v[22:25], v[186:189], v[230:233], v[22:25]
	v_mfma_f32_16x16x32_bf16 v[18:21], v[190:193], v[226:229], v[18:21]
	v_mfma_f32_16x16x32_bf16 v[18:21], v[194:197], v[230:233], v[18:21]
	v_mfma_f32_16x16x32_bf16 v[6:9], v[182:185], v[234:237], v[6:9]
	v_mfma_f32_16x16x32_bf16 v[6:9], v[186:189], v[238:241], v[6:9]
	v_mfma_f32_16x16x32_bf16 v[2:5], v[190:193], v[234:237], v[2:5]
	v_mfma_f32_16x16x32_bf16 v[2:5], v[194:197], v[238:241], v[2:5]
	s_barrier
	ds_read_b128 v[138:141], v243 offset:32768
	ds_read_b128 v[146:149], v243 offset:33792
	ds_read_b128 v[150:153], v243 offset:34816
	ds_read_b128 v[158:161], v243 offset:35840
	ds_read_b128 v[182:185], v243 offset:49152
	ds_read_b128 v[186:189], v243 offset:50176
	ds_read_b128 v[190:193], v243 offset:51200
	ds_read_b128 v[194:197], v243 offset:52224
	ds_read_b128 v[198:201], v157 offset:32768
	ds_read_b128 v[214:217], v157 offset:33792
	ds_read_b128 v[218:221], v157 offset:34816
	ds_read_b128 v[222:225], v157 offset:35840
	ds_read_b128 v[226:229], v157 offset:36864
	ds_read_b128 v[230:233], v157 offset:37888
	ds_read_b128 v[234:237], v157 offset:38912
	ds_read_b128 v[238:241], v157 offset:39936
	s_mov_b32 m0, s43
	v_lshl_add_u64 v[202:203], v[162:163], 0, s[28:29]
	global_load_lds_dwordx4 v[202:203], off
	v_lshl_add_u64 v[202:203], v[162:163], 0, s[82:83]
	s_mov_b32 m0, s46
	s_nop 0
	global_load_lds_dwordx4 v[202:203], off
	s_waitcnt vmcnt(8) lgkmcnt(0)
	s_barrier
	v_mfma_f32_16x16x32_bf16 v[126:129], v[138:141], v[198:201], v[126:129]
	v_mfma_f32_16x16x32_bf16 v[126:129], v[146:149], v[214:217], v[126:129]
	v_mfma_f32_16x16x32_bf16 v[122:125], v[150:153], v[198:201], v[122:125]
	v_mfma_f32_16x16x32_bf16 v[122:125], v[158:161], v[214:217], v[122:125]
	v_mfma_f32_16x16x32_bf16 v[110:113], v[138:141], v[218:221], v[110:113]
	v_mfma_f32_16x16x32_bf16 v[110:113], v[146:149], v[222:225], v[110:113]
	v_mfma_f32_16x16x32_bf16 v[106:109], v[150:153], v[218:221], v[106:109]
	v_mfma_f32_16x16x32_bf16 v[106:109], v[158:161], v[222:225], v[106:109]
	v_mfma_f32_16x16x32_bf16 v[94:97], v[138:141], v[226:229], v[94:97]
	v_mfma_f32_16x16x32_bf16 v[94:97], v[146:149], v[230:233], v[94:97]
	v_mfma_f32_16x16x32_bf16 v[90:93], v[150:153], v[226:229], v[90:93]
	v_mfma_f32_16x16x32_bf16 v[90:93], v[158:161], v[230:233], v[90:93]
	v_mfma_f32_16x16x32_bf16 v[78:81], v[138:141], v[234:237], v[78:81]
	v_mfma_f32_16x16x32_bf16 v[78:81], v[146:149], v[238:241], v[78:81]
	v_mfma_f32_16x16x32_bf16 v[74:77], v[150:153], v[234:237], v[74:77]
	v_mfma_f32_16x16x32_bf16 v[74:77], v[158:161], v[238:241], v[74:77]
	v_mfma_f32_16x16x32_bf16 v[118:121], v[182:185], v[198:201], v[118:121]
	v_mfma_f32_16x16x32_bf16 v[118:121], v[186:189], v[214:217], v[118:121]
	v_mfma_f32_16x16x32_bf16 v[114:117], v[190:193], v[198:201], v[114:117]
	v_mfma_f32_16x16x32_bf16 v[114:117], v[194:197], v[214:217], v[114:117]
	v_mfma_f32_16x16x32_bf16 v[102:105], v[182:185], v[218:221], v[102:105]
	v_mfma_f32_16x16x32_bf16 v[102:105], v[186:189], v[222:225], v[102:105]
	v_mfma_f32_16x16x32_bf16 v[98:101], v[190:193], v[218:221], v[98:101]
	v_mfma_f32_16x16x32_bf16 v[98:101], v[194:197], v[222:225], v[98:101]
	v_mfma_f32_16x16x32_bf16 v[86:89], v[182:185], v[226:229], v[86:89]
	v_mfma_f32_16x16x32_bf16 v[86:89], v[186:189], v[230:233], v[86:89]
	v_mfma_f32_16x16x32_bf16 v[82:85], v[190:193], v[226:229], v[82:85]
	v_mfma_f32_16x16x32_bf16 v[82:85], v[194:197], v[230:233], v[82:85]
	v_mfma_f32_16x16x32_bf16 v[70:73], v[182:185], v[234:237], v[70:73]
	v_mfma_f32_16x16x32_bf16 v[70:73], v[186:189], v[238:241], v[70:73]
	v_mfma_f32_16x16x32_bf16 v[66:69], v[190:193], v[234:237], v[66:69]
	v_mfma_f32_16x16x32_bf16 v[66:69], v[194:197], v[238:241], v[66:69]
	s_barrier
	ds_read_b128 v[198:201], v157 offset:49152
	ds_read_b128 v[214:217], v157 offset:50176
	ds_read_b128 v[218:221], v157 offset:51200
	ds_read_b128 v[222:225], v157 offset:52224
	ds_read_b128 v[226:229], v157 offset:53248
	ds_read_b128 v[230:233], v157 offset:54272
	ds_read_b128 v[234:237], v157 offset:55296
	ds_read_b128 v[238:241], v157 offset:56320
	s_add_i32 s20, s14, 0x18000
	s_mov_b32 m0, s20
	v_lshl_add_u64 v[202:203], v[142:143], 0, s[34:35]
	global_load_lds_dwordx4 v[202:203], off
	v_lshl_add_u64 v[202:203], v[142:143], 0, s[38:39]
	s_add_i32 m0, s20, 0x2000
	s_add_i32 s20, s14, 0x1c000
	global_load_lds_dwordx4 v[202:203], off
	v_lshl_add_u64 v[202:203], v[142:143], 0, s[44:45]
	s_mov_b32 m0, s20
	v_lshl_add_u64 v[142:143], v[142:143], 0, s[10:11]
	global_load_lds_dwordx4 v[202:203], off
	s_add_i32 m0, s20, 0x2000
	s_nop 0
	global_load_lds_dwordx4 v[142:143], off
	v_lshl_add_u64 v[142:143], v[162:163], 0, s[34:35]
	s_mov_b32 m0, s47
	s_nop 0
	global_load_lds_dwordx4 v[142:143], off
	v_lshl_add_u64 v[142:143], v[162:163], 0, s[38:39]
	s_mov_b32 m0, s96
	s_nop 0
	global_load_lds_dwordx4 v[142:143], off
	s_waitcnt vmcnt(8) lgkmcnt(0)
	s_barrier
	v_mfma_f32_16x16x32_bf16 v[62:65], v[138:141], v[198:201], v[62:65]
	v_mfma_f32_16x16x32_bf16 v[62:65], v[146:149], v[214:217], v[62:65]
	v_mfma_f32_16x16x32_bf16 v[58:61], v[150:153], v[198:201], v[58:61]
	v_mfma_f32_16x16x32_bf16 v[58:61], v[158:161], v[214:217], v[58:61]
	v_mfma_f32_16x16x32_bf16 v[46:49], v[138:141], v[218:221], v[46:49]
	v_mfma_f32_16x16x32_bf16 v[46:49], v[146:149], v[222:225], v[46:49]
	v_mfma_f32_16x16x32_bf16 v[42:45], v[150:153], v[218:221], v[42:45]
	v_mfma_f32_16x16x32_bf16 v[42:45], v[158:161], v[222:225], v[42:45]
	v_mfma_f32_16x16x32_bf16 v[30:33], v[138:141], v[226:229], v[30:33]
	v_mfma_f32_16x16x32_bf16 v[30:33], v[146:149], v[230:233], v[30:33]
	v_mfma_f32_16x16x32_bf16 v[26:29], v[150:153], v[226:229], v[26:29]
	v_mfma_f32_16x16x32_bf16 v[26:29], v[158:161], v[230:233], v[26:29]
	v_mfma_f32_16x16x32_bf16 v[14:17], v[138:141], v[234:237], v[14:17]
	v_mfma_f32_16x16x32_bf16 v[14:17], v[146:149], v[238:241], v[14:17]
	v_mfma_f32_16x16x32_bf16 v[10:13], v[150:153], v[234:237], v[10:13]
	v_mfma_f32_16x16x32_bf16 v[10:13], v[158:161], v[238:241], v[10:13]
	s_add_i32 s91, s91, 2
	s_add_u32 s56, s56, 0x100
	s_addc_u32 s57, s57, 0
	s_add_u32 s86, s86, 0x100
	s_addc_u32 s87, s87, 0
	v_mfma_f32_16x16x32_bf16 v[54:57], v[182:185], v[198:201], v[54:57]
	v_mfma_f32_16x16x32_bf16 v[54:57], v[186:189], v[214:217], v[54:57]
	v_mfma_f32_16x16x32_bf16 v[50:53], v[190:193], v[198:201], v[50:53]
	v_mfma_f32_16x16x32_bf16 v[50:53], v[194:197], v[214:217], v[50:53]
	v_mfma_f32_16x16x32_bf16 v[38:41], v[182:185], v[218:221], v[38:41]
	v_mfma_f32_16x16x32_bf16 v[38:41], v[186:189], v[222:225], v[38:41]
	v_mfma_f32_16x16x32_bf16 v[34:37], v[190:193], v[218:221], v[34:37]
	v_mfma_f32_16x16x32_bf16 v[34:37], v[194:197], v[222:225], v[34:37]
	v_mfma_f32_16x16x32_bf16 v[22:25], v[182:185], v[226:229], v[22:25]
	v_mfma_f32_16x16x32_bf16 v[22:25], v[186:189], v[230:233], v[22:25]
	v_mfma_f32_16x16x32_bf16 v[18:21], v[190:193], v[226:229], v[18:21]
	v_mfma_f32_16x16x32_bf16 v[18:21], v[194:197], v[230:233], v[18:21]
	v_mfma_f32_16x16x32_bf16 v[6:9], v[182:185], v[234:237], v[6:9]
	v_mfma_f32_16x16x32_bf16 v[6:9], v[186:189], v[238:241], v[6:9]
	v_mfma_f32_16x16x32_bf16 v[2:5], v[190:193], v[234:237], v[2:5]
	v_mfma_f32_16x16x32_bf16 v[2:5], v[194:197], v[238:241], v[2:5]
	s_barrier
	s_cmp_gt_u32 s91, 13
	s_cbranch_scc0 .LBB0_850
	s_setprio 0
	s_and_b64 vcc, exec, s[62:63]
	s_cbranch_vccz .LBB0_853
	s_barrier
